# previous + in the two 16-read load segments of each K-tile pair the two LDS-DMA loads (and their address/m0 setup) are issued before the ds_reads instead of after them
# speedup vs baseline: 1.0030x; 1.0030x over previous
.LBB0_287:
	s_add_u32 s28, s26, 0xfff00080
	s_addc_u32 s29, s27, -1
	s_cmp_eq_u32 s58, 60
	s_cselect_b32 s31, s21, s29
	s_cselect_b32 s30, s54, s28
	s_cselect_b32 s29, s19, s57
	s_cselect_b32 s28, s55, s56
	v_lshl_add_u64 v[192:193], s[26:27], 0, v[138:139]
	s_add_i32 m0, s17, 0xc000
	s_nop 0
	global_load_lds_dwordx4 v[192:193], off
	v_lshl_add_u64 v[192:193], s[26:27], 0, v[140:141]
	s_add_i32 m0, s17, 0xe000
	s_nop 0
	global_load_lds_dwordx4 v[192:193], off
	ds_read_b128 v[160:163], v156
	ds_read_b128 v[164:167], v156 offset:1024
	ds_read_b128 v[168:171], v156 offset:2048
	ds_read_b128 v[172:175], v156 offset:3072
	ds_read_b128 v[176:179], v157
	ds_read_b128 v[180:183], v157 offset:1024
	ds_read_b128 v[184:187], v157 offset:2048
	ds_read_b128 v[188:191], v157 offset:3072
	ds_read_b128 v[196:199], v158
	ds_read_b128 v[200:203], v158 offset:1024
	ds_read_b128 v[204:207], v158 offset:2048
	ds_read_b128 v[208:211], v158 offset:3072
	ds_read_b128 v[212:215], v158 offset:4096
	ds_read_b128 v[216:219], v158 offset:5120
	ds_read_b128 v[220:223], v158 offset:6144
	ds_read_b128 v[224:227], v158 offset:7168
	s_waitcnt vmcnt(8)
	s_waitcnt lgkmcnt(0)
	s_barrier
	s_setprio 1
	v_mfma_f32_16x16x32_bf16 v[126:129], v[160:163], v[196:199], v[126:129]
	v_mfma_f32_16x16x32_bf16 v[122:125], v[168:171], v[196:199], v[122:125]
	v_mfma_f32_16x16x32_bf16 v[118:121], v[160:163], v[204:207], v[118:121]
	v_mfma_f32_16x16x32_bf16 v[114:117], v[168:171], v[204:207], v[114:117]
	v_mfma_f32_16x16x32_bf16 v[102:105], v[160:163], v[212:215], v[102:105]
	v_mfma_f32_16x16x32_bf16 v[98:101], v[168:171], v[212:215], v[98:101]
	v_mfma_f32_16x16x32_bf16 v[86:89], v[160:163], v[220:223], v[86:89]
	v_mfma_f32_16x16x32_bf16 v[82:85], v[168:171], v[220:223], v[82:85]
	v_mfma_f32_16x16x32_bf16 v[126:129], v[164:167], v[200:203], v[126:129]
	v_mfma_f32_16x16x32_bf16 v[122:125], v[172:175], v[200:203], v[122:125]
	v_mfma_f32_16x16x32_bf16 v[118:121], v[164:167], v[208:211], v[118:121]
	v_mfma_f32_16x16x32_bf16 v[114:117], v[172:175], v[208:211], v[114:117]
	v_mfma_f32_16x16x32_bf16 v[102:105], v[164:167], v[216:219], v[102:105]
	v_mfma_f32_16x16x32_bf16 v[98:101], v[172:175], v[216:219], v[98:101]
	v_mfma_f32_16x16x32_bf16 v[86:89], v[164:167], v[224:227], v[86:89]
	v_mfma_f32_16x16x32_bf16 v[82:85], v[172:175], v[224:227], v[82:85]
	v_mfma_f32_16x16x32_bf16 v[110:113], v[176:179], v[196:199], v[110:113]
	v_mfma_f32_16x16x32_bf16 v[106:109], v[184:187], v[196:199], v[106:109]
	v_mfma_f32_16x16x32_bf16 v[94:97], v[176:179], v[204:207], v[94:97]
	v_mfma_f32_16x16x32_bf16 v[90:93], v[184:187], v[204:207], v[90:93]
	v_mfma_f32_16x16x32_bf16 v[78:81], v[176:179], v[212:215], v[78:81]
	v_mfma_f32_16x16x32_bf16 v[74:77], v[184:187], v[212:215], v[74:77]
	v_mfma_f32_16x16x32_bf16 v[70:73], v[176:179], v[220:223], v[70:73]
	v_mfma_f32_16x16x32_bf16 v[66:69], v[184:187], v[220:223], v[66:69]
	v_mfma_f32_16x16x32_bf16 v[110:113], v[180:183], v[200:203], v[110:113]
	v_mfma_f32_16x16x32_bf16 v[106:109], v[188:191], v[200:203], v[106:109]
	v_mfma_f32_16x16x32_bf16 v[94:97], v[180:183], v[208:211], v[94:97]
	v_mfma_f32_16x16x32_bf16 v[90:93], v[188:191], v[208:211], v[90:93]
	v_mfma_f32_16x16x32_bf16 v[78:81], v[180:183], v[216:219], v[78:81]
	v_mfma_f32_16x16x32_bf16 v[74:77], v[188:191], v[216:219], v[74:77]
	v_mfma_f32_16x16x32_bf16 v[70:73], v[180:183], v[224:227], v[70:73]
	v_mfma_f32_16x16x32_bf16 v[66:69], v[188:191], v[224:227], v[66:69]
	s_setprio 0
	s_barrier
	s_add_i32 s59, s50, s41
	v_lshl_add_u64 v[192:193], s[28:29], 0, v[134:135]
	s_mov_b32 m0, s59
	ds_read_b128 v[196:199], v158 offset:16384
	ds_read_b128 v[200:203], v158 offset:17408
	ds_read_b128 v[204:207], v158 offset:18432
	ds_read_b128 v[208:211], v158 offset:19456
	ds_read_b128 v[212:215], v158 offset:20480
	ds_read_b128 v[216:219], v158 offset:21504
	ds_read_b128 v[220:223], v158 offset:22528
	ds_read_b128 v[224:227], v158 offset:23552
	global_load_lds_dwordx4 v[192:193], off
	s_add_i32 m0, s59, 0x2000
	s_add_u32 s60, s28, 0x100000
	v_lshl_add_u64 v[228:229], s[28:29], 0, v[136:137]
	s_addc_u32 s61, s29, 0
	s_add_i32 s59, s51, s41
	global_load_lds_dwordx4 v[228:229], off
	v_lshl_add_u64 v[230:231], s[60:61], 0, v[134:135]
	s_mov_b32 m0, s59
	v_lshl_add_u64 v[232:233], s[30:31], 0, v[132:133]
	global_load_lds_dwordx4 v[230:231], off
	v_lshl_add_u64 v[230:231], s[60:61], 0, v[136:137]
	s_add_i32 m0, s59, 0x2000
	s_nop 0
	global_load_lds_dwordx4 v[230:231], off
	v_lshl_add_u64 v[230:231], s[30:31], 0, v[130:131]
	s_mov_b32 m0, s17
	s_nop 0
	global_load_lds_dwordx4 v[230:231], off
	s_mov_b32 m0, s42
	s_nop 0
	global_load_lds_dwordx4 v[232:233], off
	s_waitcnt vmcnt(8)
	s_waitcnt lgkmcnt(0)
	s_barrier
	s_setprio 1
	v_mfma_f32_16x16x32_bf16 v[62:65], v[160:163], v[196:199], v[62:65]
	v_mfma_f32_16x16x32_bf16 v[58:61], v[168:171], v[196:199], v[58:61]
	v_mfma_f32_16x16x32_bf16 v[54:57], v[160:163], v[204:207], v[54:57]
	v_mfma_f32_16x16x32_bf16 v[50:53], v[168:171], v[204:207], v[50:53]
	v_mfma_f32_16x16x32_bf16 v[38:41], v[160:163], v[212:215], v[38:41]
	v_mfma_f32_16x16x32_bf16 v[34:37], v[168:171], v[212:215], v[34:37]
	v_mfma_f32_16x16x32_bf16 v[22:25], v[160:163], v[220:223], v[22:25]
	v_mfma_f32_16x16x32_bf16 v[18:21], v[168:171], v[220:223], v[18:21]
	v_mfma_f32_16x16x32_bf16 v[62:65], v[164:167], v[200:203], v[62:65]
	v_mfma_f32_16x16x32_bf16 v[58:61], v[172:175], v[200:203], v[58:61]
	v_mfma_f32_16x16x32_bf16 v[54:57], v[164:167], v[208:211], v[54:57]
	v_mfma_f32_16x16x32_bf16 v[50:53], v[172:175], v[208:211], v[50:53]
	v_mfma_f32_16x16x32_bf16 v[38:41], v[164:167], v[216:219], v[38:41]
	v_mfma_f32_16x16x32_bf16 v[34:37], v[172:175], v[216:219], v[34:37]
	v_mfma_f32_16x16x32_bf16 v[22:25], v[164:167], v[224:227], v[22:25]
	v_mfma_f32_16x16x32_bf16 v[18:21], v[172:175], v[224:227], v[18:21]
	v_mfma_f32_16x16x32_bf16 v[46:49], v[176:179], v[196:199], v[46:49]
	v_mfma_f32_16x16x32_bf16 v[42:45], v[184:187], v[196:199], v[42:45]
	v_mfma_f32_16x16x32_bf16 v[30:33], v[176:179], v[204:207], v[30:33]
	v_mfma_f32_16x16x32_bf16 v[26:29], v[184:187], v[204:207], v[26:29]
	v_mfma_f32_16x16x32_bf16 v[14:17], v[176:179], v[212:215], v[14:17]
	v_mfma_f32_16x16x32_bf16 v[10:13], v[184:187], v[212:215], v[10:13]
	v_mfma_f32_16x16x32_bf16 v[6:9], v[176:179], v[220:223], v[6:9]
	v_mfma_f32_16x16x32_bf16 v[2:5], v[184:187], v[220:223], v[2:5]
	v_mfma_f32_16x16x32_bf16 v[46:49], v[180:183], v[200:203], v[46:49]
	v_mfma_f32_16x16x32_bf16 v[42:45], v[188:191], v[200:203], v[42:45]
	v_mfma_f32_16x16x32_bf16 v[30:33], v[180:183], v[208:211], v[30:33]
	v_mfma_f32_16x16x32_bf16 v[26:29], v[188:191], v[208:211], v[26:29]
	v_mfma_f32_16x16x32_bf16 v[14:17], v[180:183], v[216:219], v[14:17]
	v_mfma_f32_16x16x32_bf16 v[10:13], v[188:191], v[216:219], v[10:13]
	v_mfma_f32_16x16x32_bf16 v[6:9], v[180:183], v[224:227], v[6:9]
	v_mfma_f32_16x16x32_bf16 v[2:5], v[188:191], v[224:227], v[2:5]
	s_setprio 0
	s_barrier
	s_add_u32 s30, s30, 0x100000
	s_addc_u32 s31, s31, 0
	s_mov_b32 m0, s43
	v_lshl_add_u64 v[234:235], s[30:31], 0, v[130:131]
	global_load_lds_dwordx4 v[234:235], off
	v_lshl_add_u64 v[234:235], s[30:31], 0, v[132:133]
	s_mov_b32 m0, s45
	s_nop 0
	global_load_lds_dwordx4 v[234:235], off
	s_add_i32 s59, 0, 0x18000
	v_add_u32_e32 v159, s59, v154
	s_add_i32 s60, 0, 0x1c000
	ds_read_b128 v[160:163], v159
	ds_read_b128 v[164:167], v159 offset:1024
	ds_read_b128 v[168:171], v159 offset:2048
	ds_read_b128 v[172:175], v159 offset:3072
	v_add_u32_e32 v159, s60, v154
	ds_read_b128 v[176:179], v159
	ds_read_b128 v[180:183], v159 offset:1024
	ds_read_b128 v[184:187], v159 offset:2048
	ds_read_b128 v[188:191], v159 offset:3072
	ds_read_b128 v[196:199], v158 offset:32768
	ds_read_b128 v[200:203], v158 offset:33792
	ds_read_b128 v[204:207], v158 offset:34816
	ds_read_b128 v[208:211], v158 offset:35840
	ds_read_b128 v[212:215], v158 offset:36864
	ds_read_b128 v[216:219], v158 offset:37888
	ds_read_b128 v[220:223], v158 offset:38912
	ds_read_b128 v[224:227], v158 offset:39936
	s_waitcnt vmcnt(8)
	s_waitcnt lgkmcnt(0)
	s_barrier
	s_setprio 1
	v_mfma_f32_16x16x32_bf16 v[126:129], v[160:163], v[196:199], v[126:129]
	v_mfma_f32_16x16x32_bf16 v[122:125], v[168:171], v[196:199], v[122:125]
	v_mfma_f32_16x16x32_bf16 v[118:121], v[160:163], v[204:207], v[118:121]
	v_mfma_f32_16x16x32_bf16 v[114:117], v[168:171], v[204:207], v[114:117]
	v_mfma_f32_16x16x32_bf16 v[102:105], v[160:163], v[212:215], v[102:105]
	v_mfma_f32_16x16x32_bf16 v[98:101], v[168:171], v[212:215], v[98:101]
	v_mfma_f32_16x16x32_bf16 v[86:89], v[160:163], v[220:223], v[86:89]
	v_mfma_f32_16x16x32_bf16 v[82:85], v[168:171], v[220:223], v[82:85]
	v_mfma_f32_16x16x32_bf16 v[126:129], v[164:167], v[200:203], v[126:129]
	v_mfma_f32_16x16x32_bf16 v[122:125], v[172:175], v[200:203], v[122:125]
	v_mfma_f32_16x16x32_bf16 v[118:121], v[164:167], v[208:211], v[118:121]
	v_mfma_f32_16x16x32_bf16 v[114:117], v[172:175], v[208:211], v[114:117]
	v_mfma_f32_16x16x32_bf16 v[102:105], v[164:167], v[216:219], v[102:105]
	v_mfma_f32_16x16x32_bf16 v[98:101], v[172:175], v[216:219], v[98:101]
	v_mfma_f32_16x16x32_bf16 v[86:89], v[164:167], v[224:227], v[86:89]
	v_mfma_f32_16x16x32_bf16 v[82:85], v[172:175], v[224:227], v[82:85]
	v_mfma_f32_16x16x32_bf16 v[110:113], v[176:179], v[196:199], v[110:113]
	v_mfma_f32_16x16x32_bf16 v[106:109], v[184:187], v[196:199], v[106:109]
	v_mfma_f32_16x16x32_bf16 v[94:97], v[176:179], v[204:207], v[94:97]
	v_mfma_f32_16x16x32_bf16 v[90:93], v[184:187], v[204:207], v[90:93]
	v_mfma_f32_16x16x32_bf16 v[78:81], v[176:179], v[212:215], v[78:81]
	v_mfma_f32_16x16x32_bf16 v[74:77], v[184:187], v[212:215], v[74:77]
	v_mfma_f32_16x16x32_bf16 v[70:73], v[176:179], v[220:223], v[70:73]
	v_mfma_f32_16x16x32_bf16 v[66:69], v[184:187], v[220:223], v[66:69]
	v_mfma_f32_16x16x32_bf16 v[110:113], v[180:183], v[200:203], v[110:113]
	v_mfma_f32_16x16x32_bf16 v[106:109], v[188:191], v[200:203], v[106:109]
	v_mfma_f32_16x16x32_bf16 v[94:97], v[180:183], v[208:211], v[94:97]
	v_mfma_f32_16x16x32_bf16 v[90:93], v[188:191], v[208:211], v[90:93]
	v_mfma_f32_16x16x32_bf16 v[78:81], v[180:183], v[216:219], v[78:81]
	v_mfma_f32_16x16x32_bf16 v[74:77], v[188:191], v[216:219], v[74:77]
	v_mfma_f32_16x16x32_bf16 v[70:73], v[180:183], v[224:227], v[70:73]
	v_mfma_f32_16x16x32_bf16 v[66:69], v[188:191], v[224:227], v[66:69]
	s_setprio 0
	s_barrier
	s_add_i32 s30, s59, s41
	v_lshl_add_u64 v[192:193], v[192:193], 0, s[12:13]
	s_mov_b32 m0, s30
	ds_read_b128 v[196:199], v158 offset:49152
	ds_read_b128 v[200:203], v158 offset:50176
	ds_read_b128 v[204:207], v158 offset:51200
	ds_read_b128 v[208:211], v158 offset:52224
	ds_read_b128 v[212:215], v158 offset:53248
	ds_read_b128 v[216:219], v158 offset:54272
	ds_read_b128 v[220:223], v158 offset:55296
	ds_read_b128 v[224:227], v158 offset:56320
	global_load_lds_dwordx4 v[192:193], off
	s_add_i32 m0, s30, 0x2000
	s_add_u32 s28, s28, 0x100080
	v_lshl_add_u64 v[192:193], v[228:229], 0, s[12:13]
	s_addc_u32 s29, s29, 0
	s_add_i32 s30, s60, s41
	global_load_lds_dwordx4 v[192:193], off
	v_lshl_add_u64 v[192:193], s[28:29], 0, v[134:135]
	s_mov_b32 m0, s30
	s_nop 0
	global_load_lds_dwordx4 v[192:193], off
	v_lshl_add_u64 v[192:193], s[28:29], 0, v[136:137]
	s_add_i32 m0, s30, 0x2000
	s_nop 0
	global_load_lds_dwordx4 v[192:193], off
	v_lshl_add_u64 v[192:193], v[230:231], 0, s[12:13]
	s_mov_b32 m0, s47
	s_nop 0
	global_load_lds_dwordx4 v[192:193], off
	v_lshl_add_u64 v[192:193], v[232:233], 0, s[12:13]
	s_mov_b32 m0, s48
	s_nop 0
	global_load_lds_dwordx4 v[192:193], off
	s_nop 0
	s_waitcnt vmcnt(8)
	s_waitcnt lgkmcnt(0)
	s_barrier
	s_setprio 1
	v_mfma_f32_16x16x32_bf16 v[62:65], v[160:163], v[196:199], v[62:65]
	v_mfma_f32_16x16x32_bf16 v[58:61], v[168:171], v[196:199], v[58:61]
	v_mfma_f32_16x16x32_bf16 v[54:57], v[160:163], v[204:207], v[54:57]
	v_mfma_f32_16x16x32_bf16 v[50:53], v[168:171], v[204:207], v[50:53]
	v_mfma_f32_16x16x32_bf16 v[38:41], v[160:163], v[212:215], v[38:41]
	v_mfma_f32_16x16x32_bf16 v[34:37], v[168:171], v[212:215], v[34:37]
	v_mfma_f32_16x16x32_bf16 v[22:25], v[160:163], v[220:223], v[22:25]
	v_mfma_f32_16x16x32_bf16 v[18:21], v[168:171], v[220:223], v[18:21]
	v_mfma_f32_16x16x32_bf16 v[62:65], v[164:167], v[200:203], v[62:65]
	v_mfma_f32_16x16x32_bf16 v[58:61], v[172:175], v[200:203], v[58:61]
	v_mfma_f32_16x16x32_bf16 v[54:57], v[164:167], v[208:211], v[54:57]
	v_mfma_f32_16x16x32_bf16 v[50:53], v[172:175], v[208:211], v[50:53]
	v_mfma_f32_16x16x32_bf16 v[38:41], v[164:167], v[216:219], v[38:41]
	v_mfma_f32_16x16x32_bf16 v[34:37], v[172:175], v[216:219], v[34:37]
	v_mfma_f32_16x16x32_bf16 v[22:25], v[164:167], v[224:227], v[22:25]
	v_mfma_f32_16x16x32_bf16 v[18:21], v[172:175], v[224:227], v[18:21]
	v_mfma_f32_16x16x32_bf16 v[46:49], v[176:179], v[196:199], v[46:49]
	v_mfma_f32_16x16x32_bf16 v[42:45], v[184:187], v[196:199], v[42:45]
	v_mfma_f32_16x16x32_bf16 v[30:33], v[176:179], v[204:207], v[30:33]
	v_mfma_f32_16x16x32_bf16 v[26:29], v[184:187], v[204:207], v[26:29]
	v_mfma_f32_16x16x32_bf16 v[14:17], v[176:179], v[212:215], v[14:17]
	v_mfma_f32_16x16x32_bf16 v[10:13], v[184:187], v[212:215], v[10:13]
	v_mfma_f32_16x16x32_bf16 v[6:9], v[176:179], v[220:223], v[6:9]
	v_mfma_f32_16x16x32_bf16 v[2:5], v[184:187], v[220:223], v[2:5]
	v_mfma_f32_16x16x32_bf16 v[46:49], v[180:183], v[200:203], v[46:49]
	v_mfma_f32_16x16x32_bf16 v[42:45], v[188:191], v[200:203], v[42:45]
	v_mfma_f32_16x16x32_bf16 v[30:33], v[180:183], v[208:211], v[30:33]
	v_mfma_f32_16x16x32_bf16 v[26:29], v[188:191], v[208:211], v[26:29]
	v_mfma_f32_16x16x32_bf16 v[14:17], v[180:183], v[216:219], v[14:17]
	v_mfma_f32_16x16x32_bf16 v[10:13], v[188:191], v[216:219], v[10:13]
	v_mfma_f32_16x16x32_bf16 v[6:9], v[180:183], v[224:227], v[6:9]
	v_mfma_f32_16x16x32_bf16 v[2:5], v[188:191], v[224:227], v[2:5]
	s_setprio 0
	s_barrier
	s_add_i32 s58, s58, 2
	s_add_u32 s26, s26, 0x100
	s_addc_u32 s27, s27, 0
	s_add_u32 s56, s56, 0x100
	s_addc_u32 s57, s57, 0
	s_cmp_gt_u32 s58, 61
	s_cbranch_scc0 .LBB0_287
	s_and_b64 vcc, exec, s[14:15]
	s_cbranch_vccz .LBB0_290
	s_barrier

.LBB0_311:
	s_add_u32 s42, s40, 0xfff00080
	s_addc_u32 s43, s41, -1
	s_cmp_eq_u32 s70, 60
	s_cselect_b32 s47, s27, s43
	s_cselect_b32 s46, s66, s42
	s_cselect_b32 s43, s25, s69
	s_cselect_b32 s42, s67, s68
	v_lshl_add_u64 v[192:193], s[40:41], 0, v[134:135]
	s_add_i32 m0, s29, 0xc000
	s_nop 0
	global_load_lds_dwordx4 v[192:193], off
	v_lshl_add_u64 v[192:193], s[40:41], 0, v[136:137]
	s_add_i32 m0, s29, 0xe000
	s_nop 0
	global_load_lds_dwordx4 v[192:193], off
	ds_read_b128 v[152:155], v144
	ds_read_b128 v[156:159], v144 offset:1024
	ds_read_b128 v[160:163], v144 offset:2048
	ds_read_b128 v[164:167], v144 offset:3072
	ds_read_b128 v[168:171], v145
	ds_read_b128 v[172:175], v145 offset:1024
	ds_read_b128 v[176:179], v145 offset:2048
	ds_read_b128 v[180:183], v145 offset:3072
	ds_read_b128 v[184:187], v151
	ds_read_b128 v[188:191], v151 offset:1024
	ds_read_b128 v[196:199], v151 offset:2048
	ds_read_b128 v[200:203], v151 offset:3072
	ds_read_b128 v[204:207], v151 offset:4096
	ds_read_b128 v[208:211], v151 offset:5120
	ds_read_b128 v[212:215], v151 offset:6144
	ds_read_b128 v[216:219], v151 offset:7168
	s_nop 0
	s_waitcnt vmcnt(8)
	s_waitcnt lgkmcnt(0)
	s_barrier
	s_setprio 1
	v_mfma_f32_16x16x32_bf16 v[126:129], v[152:155], v[184:187], v[126:129]
	v_mfma_f32_16x16x32_bf16 v[122:125], v[160:163], v[184:187], v[122:125]
	v_mfma_f32_16x16x32_bf16 v[118:121], v[152:155], v[196:199], v[118:121]
	v_mfma_f32_16x16x32_bf16 v[110:113], v[160:163], v[196:199], v[110:113]
	v_mfma_f32_16x16x32_bf16 v[102:105], v[152:155], v[204:207], v[102:105]
	v_mfma_f32_16x16x32_bf16 v[94:97], v[160:163], v[204:207], v[94:97]
	v_mfma_f32_16x16x32_bf16 v[86:89], v[152:155], v[212:215], v[86:89]
	v_mfma_f32_16x16x32_bf16 v[78:81], v[160:163], v[212:215], v[78:81]
	v_mfma_f32_16x16x32_bf16 v[126:129], v[156:159], v[188:191], v[126:129]
	v_mfma_f32_16x16x32_bf16 v[122:125], v[164:167], v[188:191], v[122:125]
	v_mfma_f32_16x16x32_bf16 v[118:121], v[156:159], v[200:203], v[118:121]
	v_mfma_f32_16x16x32_bf16 v[110:113], v[164:167], v[200:203], v[110:113]
	v_mfma_f32_16x16x32_bf16 v[102:105], v[156:159], v[208:211], v[102:105]
	v_mfma_f32_16x16x32_bf16 v[94:97], v[164:167], v[208:211], v[94:97]
	v_mfma_f32_16x16x32_bf16 v[86:89], v[156:159], v[216:219], v[86:89]
	v_mfma_f32_16x16x32_bf16 v[78:81], v[164:167], v[216:219], v[78:81]
	v_mfma_f32_16x16x32_bf16 v[114:117], v[168:171], v[184:187], v[114:117]
	v_mfma_f32_16x16x32_bf16 v[106:109], v[176:179], v[184:187], v[106:109]
	v_mfma_f32_16x16x32_bf16 v[98:101], v[168:171], v[196:199], v[98:101]
	v_mfma_f32_16x16x32_bf16 v[90:93], v[176:179], v[196:199], v[90:93]
	v_mfma_f32_16x16x32_bf16 v[82:85], v[168:171], v[204:207], v[82:85]
	v_mfma_f32_16x16x32_bf16 v[74:77], v[176:179], v[204:207], v[74:77]
	v_mfma_f32_16x16x32_bf16 v[70:73], v[168:171], v[212:215], v[70:73]
	v_mfma_f32_16x16x32_bf16 v[66:69], v[176:179], v[212:215], v[66:69]
	v_mfma_f32_16x16x32_bf16 v[114:117], v[172:175], v[188:191], v[114:117]
	v_mfma_f32_16x16x32_bf16 v[106:109], v[180:183], v[188:191], v[106:109]
	v_mfma_f32_16x16x32_bf16 v[98:101], v[172:175], v[200:203], v[98:101]
	v_mfma_f32_16x16x32_bf16 v[90:93], v[180:183], v[200:203], v[90:93]
	v_mfma_f32_16x16x32_bf16 v[82:85], v[172:175], v[208:211], v[82:85]
	v_mfma_f32_16x16x32_bf16 v[74:77], v[180:183], v[208:211], v[74:77]
	v_mfma_f32_16x16x32_bf16 v[70:73], v[172:175], v[216:219], v[70:73]
	v_mfma_f32_16x16x32_bf16 v[66:69], v[180:183], v[216:219], v[66:69]
	s_setprio 0
	s_barrier
	s_add_i32 s71, s62, s54
	v_lshl_add_u64 v[192:193], s[42:43], 0, v[130:131]
	s_mov_b32 m0, s71
	ds_read_b128 v[184:187], v151 offset:16384
	ds_read_b128 v[188:191], v151 offset:17408
	ds_read_b128 v[196:199], v151 offset:18432
	ds_read_b128 v[200:203], v151 offset:19456
	ds_read_b128 v[204:207], v151 offset:20480
	ds_read_b128 v[208:211], v151 offset:21504
	ds_read_b128 v[212:215], v151 offset:22528
	ds_read_b128 v[216:219], v151 offset:23552
	global_load_lds_dwordx4 v[192:193], off
	s_add_i32 m0, s71, 0x2000
	s_add_u32 s72, s42, 0x100000
	v_lshl_add_u64 v[220:221], s[42:43], 0, v[132:133]
	s_addc_u32 s73, s43, 0
	s_add_i32 s71, s63, s54
	global_load_lds_dwordx4 v[220:221], off
	v_lshl_add_u64 v[222:223], s[72:73], 0, v[130:131]
	s_mov_b32 m0, s71
	v_lshl_add_u64 v[224:225], s[46:47], 0, v[132:133]
	global_load_lds_dwordx4 v[222:223], off
	v_lshl_add_u64 v[222:223], s[72:73], 0, v[132:133]
	s_add_i32 m0, s71, 0x2000
	s_nop 0
	global_load_lds_dwordx4 v[222:223], off
	v_lshl_add_u64 v[222:223], s[46:47], 0, v[130:131]
	s_mov_b32 m0, s29
	s_nop 0
	global_load_lds_dwordx4 v[222:223], off
	s_mov_b32 m0, s55
	s_nop 0
	global_load_lds_dwordx4 v[224:225], off
	s_waitcnt vmcnt(8)
	s_waitcnt lgkmcnt(0)
	s_barrier
	s_setprio 1
	v_mfma_f32_16x16x32_bf16 v[62:65], v[152:155], v[184:187], v[62:65]
	v_mfma_f32_16x16x32_bf16 v[58:61], v[160:163], v[184:187], v[58:61]
	v_mfma_f32_16x16x32_bf16 v[54:57], v[152:155], v[196:199], v[54:57]
	v_mfma_f32_16x16x32_bf16 v[46:49], v[160:163], v[196:199], v[46:49]
	v_mfma_f32_16x16x32_bf16 v[38:41], v[152:155], v[204:207], v[38:41]
	v_mfma_f32_16x16x32_bf16 v[30:33], v[160:163], v[204:207], v[30:33]
	v_mfma_f32_16x16x32_bf16 v[22:25], v[152:155], v[212:215], v[22:25]
	v_mfma_f32_16x16x32_bf16 v[14:17], v[160:163], v[212:215], v[14:17]
	v_mfma_f32_16x16x32_bf16 v[62:65], v[156:159], v[188:191], v[62:65]
	v_mfma_f32_16x16x32_bf16 v[58:61], v[164:167], v[188:191], v[58:61]
	v_mfma_f32_16x16x32_bf16 v[54:57], v[156:159], v[200:203], v[54:57]
	v_mfma_f32_16x16x32_bf16 v[46:49], v[164:167], v[200:203], v[46:49]
	v_mfma_f32_16x16x32_bf16 v[38:41], v[156:159], v[208:211], v[38:41]
	v_mfma_f32_16x16x32_bf16 v[30:33], v[164:167], v[208:211], v[30:33]
	v_mfma_f32_16x16x32_bf16 v[22:25], v[156:159], v[216:219], v[22:25]
	v_mfma_f32_16x16x32_bf16 v[14:17], v[164:167], v[216:219], v[14:17]
	v_mfma_f32_16x16x32_bf16 v[50:53], v[168:171], v[184:187], v[50:53]
	v_mfma_f32_16x16x32_bf16 v[42:45], v[176:179], v[184:187], v[42:45]
	v_mfma_f32_16x16x32_bf16 v[34:37], v[168:171], v[196:199], v[34:37]
	v_mfma_f32_16x16x32_bf16 v[26:29], v[176:179], v[196:199], v[26:29]
	v_mfma_f32_16x16x32_bf16 v[18:21], v[168:171], v[204:207], v[18:21]
	v_mfma_f32_16x16x32_bf16 v[10:13], v[176:179], v[204:207], v[10:13]
	v_mfma_f32_16x16x32_bf16 v[6:9], v[168:171], v[212:215], v[6:9]
	v_mfma_f32_16x16x32_bf16 v[2:5], v[176:179], v[212:215], v[2:5]
	v_mfma_f32_16x16x32_bf16 v[50:53], v[172:175], v[188:191], v[50:53]
	v_mfma_f32_16x16x32_bf16 v[42:45], v[180:183], v[188:191], v[42:45]
	v_mfma_f32_16x16x32_bf16 v[34:37], v[172:175], v[200:203], v[34:37]
	v_mfma_f32_16x16x32_bf16 v[26:29], v[180:183], v[200:203], v[26:29]
	v_mfma_f32_16x16x32_bf16 v[18:21], v[172:175], v[208:211], v[18:21]
	v_mfma_f32_16x16x32_bf16 v[10:13], v[180:183], v[208:211], v[10:13]
	v_mfma_f32_16x16x32_bf16 v[6:9], v[172:175], v[216:219], v[6:9]
	v_mfma_f32_16x16x32_bf16 v[2:5], v[180:183], v[216:219], v[2:5]
	s_setprio 0
	s_barrier
	s_add_u32 s46, s46, 0x100000
	s_addc_u32 s47, s47, 0
	s_mov_b32 m0, s56
	v_lshl_add_u64 v[226:227], s[46:47], 0, v[130:131]
	global_load_lds_dwordx4 v[226:227], off
	v_lshl_add_u64 v[226:227], s[46:47], 0, v[132:133]
	s_mov_b32 m0, s57
	s_nop 0
	global_load_lds_dwordx4 v[226:227], off
	s_add_i32 s71, 0, 0x18000
	s_add_i32 s72, 0, 0x1c000
	v_add_u32_e32 v164, s71, v142
	v_add_u32_e32 v180, s72, v142
	ds_read_b128 v[152:155], v164
	ds_read_b128 v[156:159], v164 offset:1024
	ds_read_b128 v[160:163], v164 offset:2048
	ds_read_b128 v[164:167], v164 offset:3072
	ds_read_b128 v[168:171], v180
	ds_read_b128 v[172:175], v180 offset:1024
	ds_read_b128 v[176:179], v180 offset:2048
	ds_read_b128 v[180:183], v180 offset:3072
	ds_read_b128 v[184:187], v151 offset:32768
	ds_read_b128 v[188:191], v151 offset:33792
	ds_read_b128 v[196:199], v151 offset:34816
	ds_read_b128 v[200:203], v151 offset:35840
	ds_read_b128 v[204:207], v151 offset:36864
	ds_read_b128 v[208:211], v151 offset:37888
	ds_read_b128 v[212:215], v151 offset:38912
	ds_read_b128 v[216:219], v151 offset:39936
	s_waitcnt vmcnt(8)
	s_waitcnt lgkmcnt(0)
	s_barrier
	s_setprio 1
	v_mfma_f32_16x16x32_bf16 v[126:129], v[152:155], v[184:187], v[126:129]
	v_mfma_f32_16x16x32_bf16 v[122:125], v[160:163], v[184:187], v[122:125]
	v_mfma_f32_16x16x32_bf16 v[118:121], v[152:155], v[196:199], v[118:121]
	v_mfma_f32_16x16x32_bf16 v[110:113], v[160:163], v[196:199], v[110:113]
	v_mfma_f32_16x16x32_bf16 v[102:105], v[152:155], v[204:207], v[102:105]
	v_mfma_f32_16x16x32_bf16 v[94:97], v[160:163], v[204:207], v[94:97]
	v_mfma_f32_16x16x32_bf16 v[86:89], v[152:155], v[212:215], v[86:89]
	v_mfma_f32_16x16x32_bf16 v[78:81], v[160:163], v[212:215], v[78:81]
	v_mfma_f32_16x16x32_bf16 v[126:129], v[156:159], v[188:191], v[126:129]
	v_mfma_f32_16x16x32_bf16 v[122:125], v[164:167], v[188:191], v[122:125]
	v_mfma_f32_16x16x32_bf16 v[118:121], v[156:159], v[200:203], v[118:121]
	v_mfma_f32_16x16x32_bf16 v[110:113], v[164:167], v[200:203], v[110:113]
	v_mfma_f32_16x16x32_bf16 v[102:105], v[156:159], v[208:211], v[102:105]
	v_mfma_f32_16x16x32_bf16 v[94:97], v[164:167], v[208:211], v[94:97]
	v_mfma_f32_16x16x32_bf16 v[86:89], v[156:159], v[216:219], v[86:89]
	v_mfma_f32_16x16x32_bf16 v[78:81], v[164:167], v[216:219], v[78:81]
	v_mfma_f32_16x16x32_bf16 v[114:117], v[168:171], v[184:187], v[114:117]
	v_mfma_f32_16x16x32_bf16 v[106:109], v[176:179], v[184:187], v[106:109]
	v_mfma_f32_16x16x32_bf16 v[98:101], v[168:171], v[196:199], v[98:101]
	v_mfma_f32_16x16x32_bf16 v[90:93], v[176:179], v[196:199], v[90:93]
	v_mfma_f32_16x16x32_bf16 v[82:85], v[168:171], v[204:207], v[82:85]
	v_mfma_f32_16x16x32_bf16 v[74:77], v[176:179], v[204:207], v[74:77]
	v_mfma_f32_16x16x32_bf16 v[70:73], v[168:171], v[212:215], v[70:73]
	v_mfma_f32_16x16x32_bf16 v[66:69], v[176:179], v[212:215], v[66:69]
	v_mfma_f32_16x16x32_bf16 v[114:117], v[172:175], v[188:191], v[114:117]
	v_mfma_f32_16x16x32_bf16 v[106:109], v[180:183], v[188:191], v[106:109]
	v_mfma_f32_16x16x32_bf16 v[98:101], v[172:175], v[200:203], v[98:101]
	v_mfma_f32_16x16x32_bf16 v[90:93], v[180:183], v[200:203], v[90:93]
	v_mfma_f32_16x16x32_bf16 v[82:85], v[172:175], v[208:211], v[82:85]
	v_mfma_f32_16x16x32_bf16 v[74:77], v[180:183], v[208:211], v[74:77]
	v_mfma_f32_16x16x32_bf16 v[70:73], v[172:175], v[216:219], v[70:73]
	v_mfma_f32_16x16x32_bf16 v[66:69], v[180:183], v[216:219], v[66:69]
	s_setprio 0
	s_barrier
	s_add_i32 s46, s71, s54
	v_lshl_add_u64 v[192:193], v[192:193], 0, s[10:11]
	s_mov_b32 m0, s46
	ds_read_b128 v[184:187], v151 offset:49152
	ds_read_b128 v[188:191], v151 offset:50176
	ds_read_b128 v[196:199], v151 offset:51200
	ds_read_b128 v[200:203], v151 offset:52224
	ds_read_b128 v[204:207], v151 offset:53248
	ds_read_b128 v[208:211], v151 offset:54272
	ds_read_b128 v[212:215], v151 offset:55296
	ds_read_b128 v[216:219], v151 offset:56320
	global_load_lds_dwordx4 v[192:193], off
	s_add_i32 m0, s46, 0x2000
	s_add_u32 s42, s42, 0x100080
	v_lshl_add_u64 v[192:193], v[220:221], 0, s[10:11]
	s_addc_u32 s43, s43, 0
	s_add_i32 s46, s72, s54
	global_load_lds_dwordx4 v[192:193], off
	v_lshl_add_u64 v[192:193], s[42:43], 0, v[130:131]
	s_mov_b32 m0, s46
	s_nop 0
	global_load_lds_dwordx4 v[192:193], off
	v_lshl_add_u64 v[192:193], s[42:43], 0, v[132:133]
	s_add_i32 m0, s46, 0x2000
	s_nop 0
	global_load_lds_dwordx4 v[192:193], off
	v_lshl_add_u64 v[192:193], v[222:223], 0, s[10:11]
	s_mov_b32 m0, s59
	s_nop 0
	global_load_lds_dwordx4 v[192:193], off
	v_lshl_add_u64 v[192:193], v[224:225], 0, s[10:11]
	s_mov_b32 m0, s60
	s_nop 0
	global_load_lds_dwordx4 v[192:193], off
	s_nop 0
	s_waitcnt vmcnt(8)
	s_waitcnt lgkmcnt(0)
	s_barrier
	s_setprio 1
	v_mfma_f32_16x16x32_bf16 v[62:65], v[152:155], v[184:187], v[62:65]
	v_mfma_f32_16x16x32_bf16 v[58:61], v[160:163], v[184:187], v[58:61]
	v_mfma_f32_16x16x32_bf16 v[54:57], v[152:155], v[196:199], v[54:57]
	v_mfma_f32_16x16x32_bf16 v[46:49], v[160:163], v[196:199], v[46:49]
	v_mfma_f32_16x16x32_bf16 v[38:41], v[152:155], v[204:207], v[38:41]
	v_mfma_f32_16x16x32_bf16 v[30:33], v[160:163], v[204:207], v[30:33]
	v_mfma_f32_16x16x32_bf16 v[22:25], v[152:155], v[212:215], v[22:25]
	v_mfma_f32_16x16x32_bf16 v[14:17], v[160:163], v[212:215], v[14:17]
	v_mfma_f32_16x16x32_bf16 v[62:65], v[156:159], v[188:191], v[62:65]
	v_mfma_f32_16x16x32_bf16 v[58:61], v[164:167], v[188:191], v[58:61]
	v_mfma_f32_16x16x32_bf16 v[54:57], v[156:159], v[200:203], v[54:57]
	v_mfma_f32_16x16x32_bf16 v[46:49], v[164:167], v[200:203], v[46:49]
	v_mfma_f32_16x16x32_bf16 v[38:41], v[156:159], v[208:211], v[38:41]
	v_mfma_f32_16x16x32_bf16 v[30:33], v[164:167], v[208:211], v[30:33]
	v_mfma_f32_16x16x32_bf16 v[22:25], v[156:159], v[216:219], v[22:25]
	v_mfma_f32_16x16x32_bf16 v[14:17], v[164:167], v[216:219], v[14:17]
	v_mfma_f32_16x16x32_bf16 v[50:53], v[168:171], v[184:187], v[50:53]
	v_mfma_f32_16x16x32_bf16 v[42:45], v[176:179], v[184:187], v[42:45]
	v_mfma_f32_16x16x32_bf16 v[34:37], v[168:171], v[196:199], v[34:37]
	v_mfma_f32_16x16x32_bf16 v[26:29], v[176:179], v[196:199], v[26:29]
	v_mfma_f32_16x16x32_bf16 v[18:21], v[168:171], v[204:207], v[18:21]
	v_mfma_f32_16x16x32_bf16 v[10:13], v[176:179], v[204:207], v[10:13]
	v_mfma_f32_16x16x32_bf16 v[6:9], v[168:171], v[212:215], v[6:9]
	v_mfma_f32_16x16x32_bf16 v[2:5], v[176:179], v[212:215], v[2:5]
	v_mfma_f32_16x16x32_bf16 v[50:53], v[172:175], v[188:191], v[50:53]
	v_mfma_f32_16x16x32_bf16 v[42:45], v[180:183], v[188:191], v[42:45]
	v_mfma_f32_16x16x32_bf16 v[34:37], v[172:175], v[200:203], v[34:37]
	v_mfma_f32_16x16x32_bf16 v[26:29], v[180:183], v[200:203], v[26:29]
	v_mfma_f32_16x16x32_bf16 v[18:21], v[172:175], v[208:211], v[18:21]
	v_mfma_f32_16x16x32_bf16 v[10:13], v[180:183], v[208:211], v[10:13]
	v_mfma_f32_16x16x32_bf16 v[6:9], v[172:175], v[216:219], v[6:9]
	v_mfma_f32_16x16x32_bf16 v[2:5], v[180:183], v[216:219], v[2:5]
	s_setprio 0
	s_barrier
	s_add_i32 s70, s70, 2
	s_add_u32 s40, s40, 0x100
	s_addc_u32 s41, s41, 0
	s_add_u32 s68, s68, 0x100
	s_addc_u32 s69, s69, 0
	s_cmp_gt_u32 s70, 61
	s_cbranch_scc0 .LBB0_311
	s_and_b64 vcc, exec, s[12:13]
	s_cbranch_vccz .LBB0_314
	s_barrier

.LBB0_335:
	s_add_u32 s42, s40, 0xfff00080
	s_addc_u32 s43, s41, -1
	s_cmp_eq_u32 s67, 60
	s_cselect_b32 s47, s27, s43
	s_cselect_b32 s46, s63, s42
	s_cselect_b32 s43, s25, s66
	s_cselect_b32 s42, s64, s65
	v_lshl_add_u64 v[192:193], s[40:41], 0, v[134:135]
	s_add_i32 m0, s29, 0xc000
	s_nop 0
	global_load_lds_dwordx4 v[192:193], off
	v_lshl_add_u64 v[192:193], s[40:41], 0, v[136:137]
	s_add_i32 m0, s29, 0xe000
	s_nop 0
	global_load_lds_dwordx4 v[192:193], off
	ds_read_b128 v[144:147], v140
	ds_read_b128 v[148:151], v140 offset:1024
	ds_read_b128 v[152:155], v140 offset:2048
	ds_read_b128 v[156:159], v140 offset:3072
	ds_read_b128 v[160:163], v142
	ds_read_b128 v[164:167], v142 offset:1024
	ds_read_b128 v[168:171], v142 offset:2048
	ds_read_b128 v[172:175], v142 offset:3072
	ds_read_b128 v[176:179], v143
	ds_read_b128 v[180:183], v143 offset:1024
	ds_read_b128 v[184:187], v143 offset:2048
	ds_read_b128 v[188:191], v143 offset:3072
	ds_read_b128 v[196:199], v143 offset:4096
	ds_read_b128 v[200:203], v143 offset:5120
	ds_read_b128 v[204:207], v143 offset:6144
	ds_read_b128 v[208:211], v143 offset:7168
	s_nop 0
	s_waitcnt vmcnt(8)
	s_waitcnt lgkmcnt(0)
	s_barrier
	s_setprio 1
	v_mfma_f32_16x16x32_bf16 v[126:129], v[144:147], v[176:179], v[126:129]
	v_mfma_f32_16x16x32_bf16 v[122:125], v[152:155], v[176:179], v[122:125]
	v_mfma_f32_16x16x32_bf16 v[118:121], v[144:147], v[184:187], v[118:121]
	v_mfma_f32_16x16x32_bf16 v[110:113], v[152:155], v[184:187], v[110:113]
	v_mfma_f32_16x16x32_bf16 v[102:105], v[144:147], v[196:199], v[102:105]
	v_mfma_f32_16x16x32_bf16 v[94:97], v[152:155], v[196:199], v[94:97]
	v_mfma_f32_16x16x32_bf16 v[86:89], v[144:147], v[204:207], v[86:89]
	v_mfma_f32_16x16x32_bf16 v[78:81], v[152:155], v[204:207], v[78:81]
	v_mfma_f32_16x16x32_bf16 v[126:129], v[148:151], v[180:183], v[126:129]
	v_mfma_f32_16x16x32_bf16 v[122:125], v[156:159], v[180:183], v[122:125]
	v_mfma_f32_16x16x32_bf16 v[118:121], v[148:151], v[188:191], v[118:121]
	v_mfma_f32_16x16x32_bf16 v[110:113], v[156:159], v[188:191], v[110:113]
	v_mfma_f32_16x16x32_bf16 v[102:105], v[148:151], v[200:203], v[102:105]
	v_mfma_f32_16x16x32_bf16 v[94:97], v[156:159], v[200:203], v[94:97]
	v_mfma_f32_16x16x32_bf16 v[86:89], v[148:151], v[208:211], v[86:89]
	v_mfma_f32_16x16x32_bf16 v[78:81], v[156:159], v[208:211], v[78:81]
	v_mfma_f32_16x16x32_bf16 v[114:117], v[160:163], v[176:179], v[114:117]
	v_mfma_f32_16x16x32_bf16 v[106:109], v[168:171], v[176:179], v[106:109]
	v_mfma_f32_16x16x32_bf16 v[98:101], v[160:163], v[184:187], v[98:101]
	v_mfma_f32_16x16x32_bf16 v[90:93], v[168:171], v[184:187], v[90:93]
	v_mfma_f32_16x16x32_bf16 v[82:85], v[160:163], v[196:199], v[82:85]
	v_mfma_f32_16x16x32_bf16 v[74:77], v[168:171], v[196:199], v[74:77]
	v_mfma_f32_16x16x32_bf16 v[70:73], v[160:163], v[204:207], v[70:73]
	v_mfma_f32_16x16x32_bf16 v[66:69], v[168:171], v[204:207], v[66:69]
	v_mfma_f32_16x16x32_bf16 v[114:117], v[164:167], v[180:183], v[114:117]
	v_mfma_f32_16x16x32_bf16 v[106:109], v[172:175], v[180:183], v[106:109]
	v_mfma_f32_16x16x32_bf16 v[98:101], v[164:167], v[188:191], v[98:101]
	v_mfma_f32_16x16x32_bf16 v[90:93], v[172:175], v[188:191], v[90:93]
	v_mfma_f32_16x16x32_bf16 v[82:85], v[164:167], v[200:203], v[82:85]
	v_mfma_f32_16x16x32_bf16 v[74:77], v[172:175], v[200:203], v[74:77]
	v_mfma_f32_16x16x32_bf16 v[70:73], v[164:167], v[208:211], v[70:73]
	v_mfma_f32_16x16x32_bf16 v[66:69], v[172:175], v[208:211], v[66:69]
	s_setprio 0
	s_barrier
	s_add_i32 s68, s59, s51
	v_lshl_add_u64 v[192:193], s[42:43], 0, v[130:131]
	s_mov_b32 m0, s68
	ds_read_b128 v[176:179], v143 offset:16384
	ds_read_b128 v[180:183], v143 offset:17408
	ds_read_b128 v[184:187], v143 offset:18432
	ds_read_b128 v[188:191], v143 offset:19456
	ds_read_b128 v[196:199], v143 offset:20480
	ds_read_b128 v[200:203], v143 offset:21504
	ds_read_b128 v[204:207], v143 offset:22528
	ds_read_b128 v[208:211], v143 offset:23552
	global_load_lds_dwordx4 v[192:193], off
	s_add_i32 m0, s68, 0x2000
	s_add_u32 s68, s42, 0x100000
	v_lshl_add_u64 v[212:213], s[42:43], 0, v[132:133]
	s_addc_u32 s69, s43, 0
	s_add_i32 s70, s60, s51
	global_load_lds_dwordx4 v[212:213], off
	v_lshl_add_u64 v[214:215], s[68:69], 0, v[130:131]
	s_mov_b32 m0, s70
	v_lshl_add_u64 v[216:217], s[46:47], 0, v[132:133]
	global_load_lds_dwordx4 v[214:215], off
	v_lshl_add_u64 v[214:215], s[68:69], 0, v[132:133]
	s_add_i32 m0, s70, 0x2000
	s_nop 0
	global_load_lds_dwordx4 v[214:215], off
	v_lshl_add_u64 v[214:215], s[46:47], 0, v[130:131]
	s_mov_b32 m0, s29
	s_nop 0
	global_load_lds_dwordx4 v[214:215], off
	s_mov_b32 m0, s52
	s_nop 0
	global_load_lds_dwordx4 v[216:217], off
	s_waitcnt vmcnt(8)
	s_waitcnt lgkmcnt(0)
	s_barrier
	s_setprio 1
	v_mfma_f32_16x16x32_bf16 v[62:65], v[144:147], v[176:179], v[62:65]
	v_mfma_f32_16x16x32_bf16 v[58:61], v[152:155], v[176:179], v[58:61]
	v_mfma_f32_16x16x32_bf16 v[54:57], v[144:147], v[184:187], v[54:57]
	v_mfma_f32_16x16x32_bf16 v[46:49], v[152:155], v[184:187], v[46:49]
	v_mfma_f32_16x16x32_bf16 v[38:41], v[144:147], v[196:199], v[38:41]
	v_mfma_f32_16x16x32_bf16 v[30:33], v[152:155], v[196:199], v[30:33]
	v_mfma_f32_16x16x32_bf16 v[22:25], v[144:147], v[204:207], v[22:25]
	v_mfma_f32_16x16x32_bf16 v[14:17], v[152:155], v[204:207], v[14:17]
	v_mfma_f32_16x16x32_bf16 v[62:65], v[148:151], v[180:183], v[62:65]
	v_mfma_f32_16x16x32_bf16 v[58:61], v[156:159], v[180:183], v[58:61]
	v_mfma_f32_16x16x32_bf16 v[54:57], v[148:151], v[188:191], v[54:57]
	v_mfma_f32_16x16x32_bf16 v[46:49], v[156:159], v[188:191], v[46:49]
	v_mfma_f32_16x16x32_bf16 v[38:41], v[148:151], v[200:203], v[38:41]
	v_mfma_f32_16x16x32_bf16 v[30:33], v[156:159], v[200:203], v[30:33]
	v_mfma_f32_16x16x32_bf16 v[22:25], v[148:151], v[208:211], v[22:25]
	v_mfma_f32_16x16x32_bf16 v[14:17], v[156:159], v[208:211], v[14:17]
	v_mfma_f32_16x16x32_bf16 v[50:53], v[160:163], v[176:179], v[50:53]
	v_mfma_f32_16x16x32_bf16 v[42:45], v[168:171], v[176:179], v[42:45]
	v_mfma_f32_16x16x32_bf16 v[34:37], v[160:163], v[184:187], v[34:37]
	v_mfma_f32_16x16x32_bf16 v[26:29], v[168:171], v[184:187], v[26:29]
	v_mfma_f32_16x16x32_bf16 v[18:21], v[160:163], v[196:199], v[18:21]
	v_mfma_f32_16x16x32_bf16 v[10:13], v[168:171], v[196:199], v[10:13]
	v_mfma_f32_16x16x32_bf16 v[6:9], v[160:163], v[204:207], v[6:9]
	v_mfma_f32_16x16x32_bf16 v[2:5], v[168:171], v[204:207], v[2:5]
	v_mfma_f32_16x16x32_bf16 v[50:53], v[164:167], v[180:183], v[50:53]
	v_mfma_f32_16x16x32_bf16 v[42:45], v[172:175], v[180:183], v[42:45]
	v_mfma_f32_16x16x32_bf16 v[34:37], v[164:167], v[188:191], v[34:37]
	v_mfma_f32_16x16x32_bf16 v[26:29], v[172:175], v[188:191], v[26:29]
	v_mfma_f32_16x16x32_bf16 v[18:21], v[164:167], v[200:203], v[18:21]
	v_mfma_f32_16x16x32_bf16 v[10:13], v[172:175], v[200:203], v[10:13]
	v_mfma_f32_16x16x32_bf16 v[6:9], v[164:167], v[208:211], v[6:9]
	v_mfma_f32_16x16x32_bf16 v[2:5], v[172:175], v[208:211], v[2:5]
	s_setprio 0
	s_barrier
	s_add_u32 s46, s46, 0x100000
	s_addc_u32 s47, s47, 0
	s_mov_b32 m0, s53
	v_lshl_add_u64 v[218:219], s[46:47], 0, v[130:131]
	global_load_lds_dwordx4 v[218:219], off
	v_lshl_add_u64 v[218:219], s[46:47], 0, v[132:133]
	s_mov_b32 m0, s54
	s_nop 0
	global_load_lds_dwordx4 v[218:219], off
	s_add_i32 s68, 0, 0x18000
	s_add_i32 s69, 0, 0x1c000
	v_add_u32_e32 v156, s68, v139
	v_add_u32_e32 v172, s69, v139
	ds_read_b128 v[144:147], v156
	ds_read_b128 v[148:151], v156 offset:1024
	ds_read_b128 v[152:155], v156 offset:2048
	ds_read_b128 v[156:159], v156 offset:3072
	ds_read_b128 v[160:163], v172
	ds_read_b128 v[164:167], v172 offset:1024
	ds_read_b128 v[168:171], v172 offset:2048
	ds_read_b128 v[172:175], v172 offset:3072
	ds_read_b128 v[176:179], v143 offset:32768
	ds_read_b128 v[180:183], v143 offset:33792
	ds_read_b128 v[184:187], v143 offset:34816
	ds_read_b128 v[188:191], v143 offset:35840
	ds_read_b128 v[196:199], v143 offset:36864
	ds_read_b128 v[200:203], v143 offset:37888
	ds_read_b128 v[204:207], v143 offset:38912
	ds_read_b128 v[208:211], v143 offset:39936
	s_waitcnt vmcnt(8)
	s_waitcnt lgkmcnt(0)
	s_barrier
	s_setprio 1
	v_mfma_f32_16x16x32_bf16 v[126:129], v[144:147], v[176:179], v[126:129]
	v_mfma_f32_16x16x32_bf16 v[122:125], v[152:155], v[176:179], v[122:125]
	v_mfma_f32_16x16x32_bf16 v[118:121], v[144:147], v[184:187], v[118:121]
	v_mfma_f32_16x16x32_bf16 v[110:113], v[152:155], v[184:187], v[110:113]
	v_mfma_f32_16x16x32_bf16 v[102:105], v[144:147], v[196:199], v[102:105]
	v_mfma_f32_16x16x32_bf16 v[94:97], v[152:155], v[196:199], v[94:97]
	v_mfma_f32_16x16x32_bf16 v[86:89], v[144:147], v[204:207], v[86:89]
	v_mfma_f32_16x16x32_bf16 v[78:81], v[152:155], v[204:207], v[78:81]
	v_mfma_f32_16x16x32_bf16 v[126:129], v[148:151], v[180:183], v[126:129]
	v_mfma_f32_16x16x32_bf16 v[122:125], v[156:159], v[180:183], v[122:125]
	v_mfma_f32_16x16x32_bf16 v[118:121], v[148:151], v[188:191], v[118:121]
	v_mfma_f32_16x16x32_bf16 v[110:113], v[156:159], v[188:191], v[110:113]
	v_mfma_f32_16x16x32_bf16 v[102:105], v[148:151], v[200:203], v[102:105]
	v_mfma_f32_16x16x32_bf16 v[94:97], v[156:159], v[200:203], v[94:97]
	v_mfma_f32_16x16x32_bf16 v[86:89], v[148:151], v[208:211], v[86:89]
	v_mfma_f32_16x16x32_bf16 v[78:81], v[156:159], v[208:211], v[78:81]
	v_mfma_f32_16x16x32_bf16 v[114:117], v[160:163], v[176:179], v[114:117]
	v_mfma_f32_16x16x32_bf16 v[106:109], v[168:171], v[176:179], v[106:109]
	v_mfma_f32_16x16x32_bf16 v[98:101], v[160:163], v[184:187], v[98:101]
	v_mfma_f32_16x16x32_bf16 v[90:93], v[168:171], v[184:187], v[90:93]
	v_mfma_f32_16x16x32_bf16 v[82:85], v[160:163], v[196:199], v[82:85]
	v_mfma_f32_16x16x32_bf16 v[74:77], v[168:171], v[196:199], v[74:77]
	v_mfma_f32_16x16x32_bf16 v[70:73], v[160:163], v[204:207], v[70:73]
	v_mfma_f32_16x16x32_bf16 v[66:69], v[168:171], v[204:207], v[66:69]
	v_mfma_f32_16x16x32_bf16 v[114:117], v[164:167], v[180:183], v[114:117]
	v_mfma_f32_16x16x32_bf16 v[106:109], v[172:175], v[180:183], v[106:109]
	v_mfma_f32_16x16x32_bf16 v[98:101], v[164:167], v[188:191], v[98:101]
	v_mfma_f32_16x16x32_bf16 v[90:93], v[172:175], v[188:191], v[90:93]
	v_mfma_f32_16x16x32_bf16 v[82:85], v[164:167], v[200:203], v[82:85]
	v_mfma_f32_16x16x32_bf16 v[74:77], v[172:175], v[200:203], v[74:77]
	v_mfma_f32_16x16x32_bf16 v[70:73], v[164:167], v[208:211], v[70:73]
	v_mfma_f32_16x16x32_bf16 v[66:69], v[172:175], v[208:211], v[66:69]
	s_setprio 0
	s_barrier
	s_add_i32 s46, s68, s51
	v_lshl_add_u64 v[192:193], v[192:193], 0, s[10:11]
	s_mov_b32 m0, s46
	ds_read_b128 v[176:179], v143 offset:49152
	ds_read_b128 v[180:183], v143 offset:50176
	ds_read_b128 v[184:187], v143 offset:51200
	ds_read_b128 v[188:191], v143 offset:52224
	ds_read_b128 v[196:199], v143 offset:53248
	ds_read_b128 v[200:203], v143 offset:54272
	ds_read_b128 v[204:207], v143 offset:55296
	ds_read_b128 v[208:211], v143 offset:56320
	global_load_lds_dwordx4 v[192:193], off
	s_add_i32 m0, s46, 0x2000
	s_add_u32 s42, s42, 0x100080
	v_lshl_add_u64 v[192:193], v[212:213], 0, s[10:11]
	s_addc_u32 s43, s43, 0
	s_add_i32 s46, s69, s51
	global_load_lds_dwordx4 v[192:193], off
	v_lshl_add_u64 v[192:193], s[42:43], 0, v[130:131]
	s_mov_b32 m0, s46
	s_nop 0
	global_load_lds_dwordx4 v[192:193], off
	v_lshl_add_u64 v[192:193], s[42:43], 0, v[132:133]
	s_add_i32 m0, s46, 0x2000
	s_nop 0
	global_load_lds_dwordx4 v[192:193], off
	v_lshl_add_u64 v[192:193], v[214:215], 0, s[10:11]
	s_mov_b32 m0, s56
	s_nop 0
	global_load_lds_dwordx4 v[192:193], off
	v_lshl_add_u64 v[192:193], v[216:217], 0, s[10:11]
	s_mov_b32 m0, s57
	s_nop 0
	global_load_lds_dwordx4 v[192:193], off
	s_nop 0
	s_waitcnt vmcnt(8)
	s_waitcnt lgkmcnt(0)
	s_barrier
	s_setprio 1
	v_mfma_f32_16x16x32_bf16 v[62:65], v[144:147], v[176:179], v[62:65]
	v_mfma_f32_16x16x32_bf16 v[58:61], v[152:155], v[176:179], v[58:61]
	v_mfma_f32_16x16x32_bf16 v[54:57], v[144:147], v[184:187], v[54:57]
	v_mfma_f32_16x16x32_bf16 v[46:49], v[152:155], v[184:187], v[46:49]
	v_mfma_f32_16x16x32_bf16 v[38:41], v[144:147], v[196:199], v[38:41]
	v_mfma_f32_16x16x32_bf16 v[30:33], v[152:155], v[196:199], v[30:33]
	v_mfma_f32_16x16x32_bf16 v[22:25], v[144:147], v[204:207], v[22:25]
	v_mfma_f32_16x16x32_bf16 v[14:17], v[152:155], v[204:207], v[14:17]
	v_mfma_f32_16x16x32_bf16 v[62:65], v[148:151], v[180:183], v[62:65]
	v_mfma_f32_16x16x32_bf16 v[58:61], v[156:159], v[180:183], v[58:61]
	v_mfma_f32_16x16x32_bf16 v[54:57], v[148:151], v[188:191], v[54:57]
	v_mfma_f32_16x16x32_bf16 v[46:49], v[156:159], v[188:191], v[46:49]
	v_mfma_f32_16x16x32_bf16 v[38:41], v[148:151], v[200:203], v[38:41]
	v_mfma_f32_16x16x32_bf16 v[30:33], v[156:159], v[200:203], v[30:33]
	v_mfma_f32_16x16x32_bf16 v[22:25], v[148:151], v[208:211], v[22:25]
	v_mfma_f32_16x16x32_bf16 v[14:17], v[156:159], v[208:211], v[14:17]
	v_mfma_f32_16x16x32_bf16 v[50:53], v[160:163], v[176:179], v[50:53]
	v_mfma_f32_16x16x32_bf16 v[42:45], v[168:171], v[176:179], v[42:45]
	v_mfma_f32_16x16x32_bf16 v[34:37], v[160:163], v[184:187], v[34:37]
	v_mfma_f32_16x16x32_bf16 v[26:29], v[168:171], v[184:187], v[26:29]
	v_mfma_f32_16x16x32_bf16 v[18:21], v[160:163], v[196:199], v[18:21]
	v_mfma_f32_16x16x32_bf16 v[10:13], v[168:171], v[196:199], v[10:13]
	v_mfma_f32_16x16x32_bf16 v[6:9], v[160:163], v[204:207], v[6:9]
	v_mfma_f32_16x16x32_bf16 v[2:5], v[168:171], v[204:207], v[2:5]
	v_mfma_f32_16x16x32_bf16 v[50:53], v[164:167], v[180:183], v[50:53]
	v_mfma_f32_16x16x32_bf16 v[42:45], v[172:175], v[180:183], v[42:45]
	v_mfma_f32_16x16x32_bf16 v[34:37], v[164:167], v[188:191], v[34:37]
	v_mfma_f32_16x16x32_bf16 v[26:29], v[172:175], v[188:191], v[26:29]
	v_mfma_f32_16x16x32_bf16 v[18:21], v[164:167], v[200:203], v[18:21]
	v_mfma_f32_16x16x32_bf16 v[10:13], v[172:175], v[200:203], v[10:13]
	v_mfma_f32_16x16x32_bf16 v[6:9], v[164:167], v[208:211], v[6:9]
	v_mfma_f32_16x16x32_bf16 v[2:5], v[172:175], v[208:211], v[2:5]
	s_setprio 0
	s_barrier
	s_add_i32 s67, s67, 2
	s_add_u32 s40, s40, 0x100
	s_addc_u32 s41, s41, 0
	s_add_u32 s65, s65, 0x100
	s_addc_u32 s66, s66, 0
	s_cmp_gt_u32 s67, 61
	s_cbranch_scc0 .LBB0_335
	s_and_b64 vcc, exec, s[12:13]
	s_cbranch_vccz .LBB0_338
	s_barrier

.LBB0_657:
	s_add_u32 s28, s26, 0xfff00080
	s_addc_u32 s29, s27, -1
	s_cmp_eq_u32 s58, 60
	s_cselect_b32 s31, s21, s29
	s_cselect_b32 s30, s54, s28
	s_cselect_b32 s29, s19, s57
	s_cselect_b32 s28, s55, s56
	v_lshl_add_u64 v[224:225], s[26:27], 0, v[138:139]
	s_add_i32 m0, s17, 0xc000
	s_nop 0
	global_load_lds_dwordx4 v[224:225], off
	v_lshl_add_u64 v[224:225], s[26:27], 0, v[140:141]
	s_add_i32 m0, s17, 0xe000
	s_nop 0
	global_load_lds_dwordx4 v[224:225], off
	ds_read_b128 v[158:161], v155
	ds_read_b128 v[162:165], v155 offset:1024
	ds_read_b128 v[166:169], v155 offset:2048
	ds_read_b128 v[170:173], v155 offset:3072
	ds_read_b128 v[174:177], v156
	ds_read_b128 v[178:181], v156 offset:1024
	ds_read_b128 v[182:185], v156 offset:2048
	ds_read_b128 v[186:189], v156 offset:3072
	ds_read_b128 v[190:193], v157
	ds_read_b128 v[196:199], v157 offset:1024
	ds_read_b128 v[200:203], v157 offset:2048
	ds_read_b128 v[204:207], v157 offset:3072
	ds_read_b128 v[208:211], v157 offset:4096
	ds_read_b128 v[212:215], v157 offset:5120
	ds_read_b128 v[216:219], v157 offset:6144
	ds_read_b128 v[220:223], v157 offset:7168
	s_waitcnt vmcnt(8)
	s_waitcnt lgkmcnt(0)
	s_barrier
	s_setprio 1
	v_mfma_f32_16x16x32_bf16 v[126:129], v[158:161], v[190:193], v[126:129]
	v_mfma_f32_16x16x32_bf16 v[122:125], v[166:169], v[190:193], v[122:125]
	v_mfma_f32_16x16x32_bf16 v[118:121], v[158:161], v[200:203], v[118:121]
	v_mfma_f32_16x16x32_bf16 v[114:117], v[166:169], v[200:203], v[114:117]
	v_mfma_f32_16x16x32_bf16 v[102:105], v[158:161], v[208:211], v[102:105]
	v_mfma_f32_16x16x32_bf16 v[98:101], v[166:169], v[208:211], v[98:101]
	v_mfma_f32_16x16x32_bf16 v[86:89], v[158:161], v[216:219], v[86:89]
	v_mfma_f32_16x16x32_bf16 v[82:85], v[166:169], v[216:219], v[82:85]
	v_mfma_f32_16x16x32_bf16 v[126:129], v[162:165], v[196:199], v[126:129]
	v_mfma_f32_16x16x32_bf16 v[122:125], v[170:173], v[196:199], v[122:125]
	v_mfma_f32_16x16x32_bf16 v[118:121], v[162:165], v[204:207], v[118:121]
	v_mfma_f32_16x16x32_bf16 v[114:117], v[170:173], v[204:207], v[114:117]
	v_mfma_f32_16x16x32_bf16 v[102:105], v[162:165], v[212:215], v[102:105]
	v_mfma_f32_16x16x32_bf16 v[98:101], v[170:173], v[212:215], v[98:101]
	v_mfma_f32_16x16x32_bf16 v[86:89], v[162:165], v[220:223], v[86:89]
	v_mfma_f32_16x16x32_bf16 v[82:85], v[170:173], v[220:223], v[82:85]
	v_mfma_f32_16x16x32_bf16 v[110:113], v[174:177], v[190:193], v[110:113]
	v_mfma_f32_16x16x32_bf16 v[106:109], v[182:185], v[190:193], v[106:109]
	v_mfma_f32_16x16x32_bf16 v[94:97], v[174:177], v[200:203], v[94:97]
	v_mfma_f32_16x16x32_bf16 v[90:93], v[182:185], v[200:203], v[90:93]
	v_mfma_f32_16x16x32_bf16 v[78:81], v[174:177], v[208:211], v[78:81]
	v_mfma_f32_16x16x32_bf16 v[74:77], v[182:185], v[208:211], v[74:77]
	v_mfma_f32_16x16x32_bf16 v[70:73], v[174:177], v[216:219], v[70:73]
	v_mfma_f32_16x16x32_bf16 v[66:69], v[182:185], v[216:219], v[66:69]
	v_mfma_f32_16x16x32_bf16 v[110:113], v[178:181], v[196:199], v[110:113]
	v_mfma_f32_16x16x32_bf16 v[106:109], v[186:189], v[196:199], v[106:109]
	v_mfma_f32_16x16x32_bf16 v[94:97], v[178:181], v[204:207], v[94:97]
	v_mfma_f32_16x16x32_bf16 v[90:93], v[186:189], v[204:207], v[90:93]
	v_mfma_f32_16x16x32_bf16 v[78:81], v[178:181], v[212:215], v[78:81]
	v_mfma_f32_16x16x32_bf16 v[74:77], v[186:189], v[212:215], v[74:77]
	v_mfma_f32_16x16x32_bf16 v[70:73], v[178:181], v[220:223], v[70:73]
	v_mfma_f32_16x16x32_bf16 v[66:69], v[186:189], v[220:223], v[66:69]
	s_setprio 0
	s_barrier
	s_add_i32 s59, s50, s41
	v_lshl_add_u64 v[224:225], s[28:29], 0, v[134:135]
	s_mov_b32 m0, s59
	ds_read_b128 v[190:193], v157 offset:16384
	ds_read_b128 v[196:199], v157 offset:17408
	ds_read_b128 v[200:203], v157 offset:18432
	ds_read_b128 v[204:207], v157 offset:19456
	ds_read_b128 v[208:211], v157 offset:20480
	ds_read_b128 v[212:215], v157 offset:21504
	ds_read_b128 v[216:219], v157 offset:22528
	ds_read_b128 v[220:223], v157 offset:23552
	global_load_lds_dwordx4 v[224:225], off
	s_add_i32 m0, s59, 0x2000
	s_add_u32 s60, s28, 0x100000
	v_lshl_add_u64 v[226:227], s[28:29], 0, v[136:137]
	s_addc_u32 s61, s29, 0
	s_add_i32 s59, s51, s41
	global_load_lds_dwordx4 v[226:227], off
	v_lshl_add_u64 v[228:229], s[60:61], 0, v[134:135]
	s_mov_b32 m0, s59
	v_lshl_add_u64 v[230:231], s[30:31], 0, v[132:133]
	global_load_lds_dwordx4 v[228:229], off
	v_lshl_add_u64 v[228:229], s[60:61], 0, v[136:137]
	s_add_i32 m0, s59, 0x2000
	s_nop 0
	global_load_lds_dwordx4 v[228:229], off
	v_lshl_add_u64 v[228:229], s[30:31], 0, v[130:131]
	s_mov_b32 m0, s17
	s_nop 0
	global_load_lds_dwordx4 v[228:229], off
	s_mov_b32 m0, s42
	s_nop 0
	global_load_lds_dwordx4 v[230:231], off
	s_waitcnt vmcnt(8)
	s_waitcnt lgkmcnt(0)
	s_barrier
	s_setprio 1
	v_mfma_f32_16x16x32_bf16 v[62:65], v[158:161], v[190:193], v[62:65]
	v_mfma_f32_16x16x32_bf16 v[58:61], v[166:169], v[190:193], v[58:61]
	v_mfma_f32_16x16x32_bf16 v[54:57], v[158:161], v[200:203], v[54:57]
	v_mfma_f32_16x16x32_bf16 v[50:53], v[166:169], v[200:203], v[50:53]
	v_mfma_f32_16x16x32_bf16 v[38:41], v[158:161], v[208:211], v[38:41]
	v_mfma_f32_16x16x32_bf16 v[34:37], v[166:169], v[208:211], v[34:37]
	v_mfma_f32_16x16x32_bf16 v[22:25], v[158:161], v[216:219], v[22:25]
	v_mfma_f32_16x16x32_bf16 v[18:21], v[166:169], v[216:219], v[18:21]
	v_mfma_f32_16x16x32_bf16 v[62:65], v[162:165], v[196:199], v[62:65]
	v_mfma_f32_16x16x32_bf16 v[58:61], v[170:173], v[196:199], v[58:61]
	v_mfma_f32_16x16x32_bf16 v[54:57], v[162:165], v[204:207], v[54:57]
	v_mfma_f32_16x16x32_bf16 v[50:53], v[170:173], v[204:207], v[50:53]
	v_mfma_f32_16x16x32_bf16 v[38:41], v[162:165], v[212:215], v[38:41]
	v_mfma_f32_16x16x32_bf16 v[34:37], v[170:173], v[212:215], v[34:37]
	v_mfma_f32_16x16x32_bf16 v[22:25], v[162:165], v[220:223], v[22:25]
	v_mfma_f32_16x16x32_bf16 v[18:21], v[170:173], v[220:223], v[18:21]
	v_mfma_f32_16x16x32_bf16 v[46:49], v[174:177], v[190:193], v[46:49]
	v_mfma_f32_16x16x32_bf16 v[42:45], v[182:185], v[190:193], v[42:45]
	v_mfma_f32_16x16x32_bf16 v[30:33], v[174:177], v[200:203], v[30:33]
	v_mfma_f32_16x16x32_bf16 v[26:29], v[182:185], v[200:203], v[26:29]
	v_mfma_f32_16x16x32_bf16 v[14:17], v[174:177], v[208:211], v[14:17]
	v_mfma_f32_16x16x32_bf16 v[10:13], v[182:185], v[208:211], v[10:13]
	v_mfma_f32_16x16x32_bf16 v[6:9], v[174:177], v[216:219], v[6:9]
	v_mfma_f32_16x16x32_bf16 v[2:5], v[182:185], v[216:219], v[2:5]
	v_mfma_f32_16x16x32_bf16 v[46:49], v[178:181], v[196:199], v[46:49]
	v_mfma_f32_16x16x32_bf16 v[42:45], v[186:189], v[196:199], v[42:45]
	v_mfma_f32_16x16x32_bf16 v[30:33], v[178:181], v[204:207], v[30:33]
	v_mfma_f32_16x16x32_bf16 v[26:29], v[186:189], v[204:207], v[26:29]
	v_mfma_f32_16x16x32_bf16 v[14:17], v[178:181], v[212:215], v[14:17]
	v_mfma_f32_16x16x32_bf16 v[10:13], v[186:189], v[212:215], v[10:13]
	v_mfma_f32_16x16x32_bf16 v[6:9], v[178:181], v[220:223], v[6:9]
	v_mfma_f32_16x16x32_bf16 v[2:5], v[186:189], v[220:223], v[2:5]
	s_setprio 0
	s_barrier
	s_add_u32 s30, s30, 0x100000
	s_addc_u32 s31, s31, 0
	s_mov_b32 m0, s43
	v_lshl_add_u64 v[232:233], s[30:31], 0, v[130:131]
	global_load_lds_dwordx4 v[232:233], off
	v_lshl_add_u64 v[232:233], s[30:31], 0, v[132:133]
	s_mov_b32 m0, s45
	s_nop 0
	global_load_lds_dwordx4 v[232:233], off
	s_add_i32 s59, 0, 0x18000
	s_add_i32 s60, 0, 0x1c000
	v_add_u32_e32 v170, s59, v153
	v_add_u32_e32 v186, s60, v153
	ds_read_b128 v[158:161], v170
	ds_read_b128 v[162:165], v170 offset:1024
	ds_read_b128 v[166:169], v170 offset:2048
	ds_read_b128 v[170:173], v170 offset:3072
	ds_read_b128 v[174:177], v186
	ds_read_b128 v[178:181], v186 offset:1024
	ds_read_b128 v[182:185], v186 offset:2048
	ds_read_b128 v[186:189], v186 offset:3072
	ds_read_b128 v[190:193], v157 offset:32768
	ds_read_b128 v[196:199], v157 offset:33792
	ds_read_b128 v[200:203], v157 offset:34816
	ds_read_b128 v[204:207], v157 offset:35840
	ds_read_b128 v[208:211], v157 offset:36864
	ds_read_b128 v[212:215], v157 offset:37888
	ds_read_b128 v[216:219], v157 offset:38912
	ds_read_b128 v[220:223], v157 offset:39936
	s_waitcnt vmcnt(8)
	s_waitcnt lgkmcnt(0)
	s_barrier
	s_setprio 1
	v_mfma_f32_16x16x32_bf16 v[126:129], v[158:161], v[190:193], v[126:129]
	v_mfma_f32_16x16x32_bf16 v[122:125], v[166:169], v[190:193], v[122:125]
	v_mfma_f32_16x16x32_bf16 v[118:121], v[158:161], v[200:203], v[118:121]
	v_mfma_f32_16x16x32_bf16 v[114:117], v[166:169], v[200:203], v[114:117]
	v_mfma_f32_16x16x32_bf16 v[102:105], v[158:161], v[208:211], v[102:105]
	v_mfma_f32_16x16x32_bf16 v[98:101], v[166:169], v[208:211], v[98:101]
	v_mfma_f32_16x16x32_bf16 v[86:89], v[158:161], v[216:219], v[86:89]
	v_mfma_f32_16x16x32_bf16 v[82:85], v[166:169], v[216:219], v[82:85]
	v_mfma_f32_16x16x32_bf16 v[126:129], v[162:165], v[196:199], v[126:129]
	v_mfma_f32_16x16x32_bf16 v[122:125], v[170:173], v[196:199], v[122:125]
	v_mfma_f32_16x16x32_bf16 v[118:121], v[162:165], v[204:207], v[118:121]
	v_mfma_f32_16x16x32_bf16 v[114:117], v[170:173], v[204:207], v[114:117]
	v_mfma_f32_16x16x32_bf16 v[102:105], v[162:165], v[212:215], v[102:105]
	v_mfma_f32_16x16x32_bf16 v[98:101], v[170:173], v[212:215], v[98:101]
	v_mfma_f32_16x16x32_bf16 v[86:89], v[162:165], v[220:223], v[86:89]
	v_mfma_f32_16x16x32_bf16 v[82:85], v[170:173], v[220:223], v[82:85]
	v_mfma_f32_16x16x32_bf16 v[110:113], v[174:177], v[190:193], v[110:113]
	v_mfma_f32_16x16x32_bf16 v[106:109], v[182:185], v[190:193], v[106:109]
	v_mfma_f32_16x16x32_bf16 v[94:97], v[174:177], v[200:203], v[94:97]
	v_mfma_f32_16x16x32_bf16 v[90:93], v[182:185], v[200:203], v[90:93]
	v_mfma_f32_16x16x32_bf16 v[78:81], v[174:177], v[208:211], v[78:81]
	v_mfma_f32_16x16x32_bf16 v[74:77], v[182:185], v[208:211], v[74:77]
	v_mfma_f32_16x16x32_bf16 v[70:73], v[174:177], v[216:219], v[70:73]
	v_mfma_f32_16x16x32_bf16 v[66:69], v[182:185], v[216:219], v[66:69]
	v_mfma_f32_16x16x32_bf16 v[110:113], v[178:181], v[196:199], v[110:113]
	v_mfma_f32_16x16x32_bf16 v[106:109], v[186:189], v[196:199], v[106:109]
	v_mfma_f32_16x16x32_bf16 v[94:97], v[178:181], v[204:207], v[94:97]
	v_mfma_f32_16x16x32_bf16 v[90:93], v[186:189], v[204:207], v[90:93]
	v_mfma_f32_16x16x32_bf16 v[78:81], v[178:181], v[212:215], v[78:81]
	v_mfma_f32_16x16x32_bf16 v[74:77], v[186:189], v[212:215], v[74:77]
	v_mfma_f32_16x16x32_bf16 v[70:73], v[178:181], v[220:223], v[70:73]
	v_mfma_f32_16x16x32_bf16 v[66:69], v[186:189], v[220:223], v[66:69]
	s_setprio 0
	s_barrier
	s_add_i32 s30, s59, s41
	v_lshl_add_u64 v[224:225], v[224:225], 0, s[12:13]
	s_mov_b32 m0, s30
	ds_read_b128 v[190:193], v157 offset:49152
	ds_read_b128 v[196:199], v157 offset:50176
	ds_read_b128 v[200:203], v157 offset:51200
	ds_read_b128 v[204:207], v157 offset:52224
	ds_read_b128 v[208:211], v157 offset:53248
	ds_read_b128 v[212:215], v157 offset:54272
	ds_read_b128 v[216:219], v157 offset:55296
	ds_read_b128 v[220:223], v157 offset:56320
	global_load_lds_dwordx4 v[224:225], off
	s_add_i32 m0, s30, 0x2000
	s_add_u32 s28, s28, 0x100080
	v_lshl_add_u64 v[224:225], v[226:227], 0, s[12:13]
	s_addc_u32 s29, s29, 0
	s_add_i32 s30, s60, s41
	global_load_lds_dwordx4 v[224:225], off
	v_lshl_add_u64 v[224:225], s[28:29], 0, v[134:135]
	s_mov_b32 m0, s30
	s_nop 0
	global_load_lds_dwordx4 v[224:225], off
	v_lshl_add_u64 v[224:225], s[28:29], 0, v[136:137]
	s_add_i32 m0, s30, 0x2000
	s_nop 0
	global_load_lds_dwordx4 v[224:225], off
	v_lshl_add_u64 v[224:225], v[228:229], 0, s[12:13]
	s_mov_b32 m0, s47
	s_nop 0
	global_load_lds_dwordx4 v[224:225], off
	v_lshl_add_u64 v[224:225], v[230:231], 0, s[12:13]
	s_mov_b32 m0, s48
	s_nop 0
	global_load_lds_dwordx4 v[224:225], off
	s_nop 0
	s_waitcnt vmcnt(8)
	s_waitcnt lgkmcnt(0)
	s_barrier
	s_setprio 1
	v_mfma_f32_16x16x32_bf16 v[62:65], v[158:161], v[190:193], v[62:65]
	v_mfma_f32_16x16x32_bf16 v[58:61], v[166:169], v[190:193], v[58:61]
	v_mfma_f32_16x16x32_bf16 v[54:57], v[158:161], v[200:203], v[54:57]
	v_mfma_f32_16x16x32_bf16 v[50:53], v[166:169], v[200:203], v[50:53]
	v_mfma_f32_16x16x32_bf16 v[38:41], v[158:161], v[208:211], v[38:41]
	v_mfma_f32_16x16x32_bf16 v[34:37], v[166:169], v[208:211], v[34:37]
	v_mfma_f32_16x16x32_bf16 v[22:25], v[158:161], v[216:219], v[22:25]
	v_mfma_f32_16x16x32_bf16 v[18:21], v[166:169], v[216:219], v[18:21]
	v_mfma_f32_16x16x32_bf16 v[62:65], v[162:165], v[196:199], v[62:65]
	v_mfma_f32_16x16x32_bf16 v[58:61], v[170:173], v[196:199], v[58:61]
	v_mfma_f32_16x16x32_bf16 v[54:57], v[162:165], v[204:207], v[54:57]
	v_mfma_f32_16x16x32_bf16 v[50:53], v[170:173], v[204:207], v[50:53]
	v_mfma_f32_16x16x32_bf16 v[38:41], v[162:165], v[212:215], v[38:41]
	v_mfma_f32_16x16x32_bf16 v[34:37], v[170:173], v[212:215], v[34:37]
	v_mfma_f32_16x16x32_bf16 v[22:25], v[162:165], v[220:223], v[22:25]
	v_mfma_f32_16x16x32_bf16 v[18:21], v[170:173], v[220:223], v[18:21]
	v_mfma_f32_16x16x32_bf16 v[46:49], v[174:177], v[190:193], v[46:49]
	v_mfma_f32_16x16x32_bf16 v[42:45], v[182:185], v[190:193], v[42:45]
	v_mfma_f32_16x16x32_bf16 v[30:33], v[174:177], v[200:203], v[30:33]
	v_mfma_f32_16x16x32_bf16 v[26:29], v[182:185], v[200:203], v[26:29]
	v_mfma_f32_16x16x32_bf16 v[14:17], v[174:177], v[208:211], v[14:17]
	v_mfma_f32_16x16x32_bf16 v[10:13], v[182:185], v[208:211], v[10:13]
	v_mfma_f32_16x16x32_bf16 v[6:9], v[174:177], v[216:219], v[6:9]
	v_mfma_f32_16x16x32_bf16 v[2:5], v[182:185], v[216:219], v[2:5]
	v_mfma_f32_16x16x32_bf16 v[46:49], v[178:181], v[196:199], v[46:49]
	v_mfma_f32_16x16x32_bf16 v[42:45], v[186:189], v[196:199], v[42:45]
	v_mfma_f32_16x16x32_bf16 v[30:33], v[178:181], v[204:207], v[30:33]
	v_mfma_f32_16x16x32_bf16 v[26:29], v[186:189], v[204:207], v[26:29]
	v_mfma_f32_16x16x32_bf16 v[14:17], v[178:181], v[212:215], v[14:17]
	v_mfma_f32_16x16x32_bf16 v[10:13], v[186:189], v[212:215], v[10:13]
	v_mfma_f32_16x16x32_bf16 v[6:9], v[178:181], v[220:223], v[6:9]
	v_mfma_f32_16x16x32_bf16 v[2:5], v[186:189], v[220:223], v[2:5]
	s_setprio 0
	s_barrier
	s_add_i32 s58, s58, 2
	s_add_u32 s26, s26, 0x100
	s_addc_u32 s27, s27, 0
	s_add_u32 s56, s56, 0x100
	s_addc_u32 s57, s57, 0
	s_cmp_gt_u32 s58, 61
	s_cbranch_scc0 .LBB0_657
	s_and_b64 vcc, exec, s[14:15]
	s_cbranch_vccz .LBB0_660
	s_barrier

.LBB0_681:
	s_add_u32 s42, s40, 0xfff00080
	s_addc_u32 s43, s41, -1
	s_cmp_eq_u32 s70, 60
	s_cselect_b32 s47, s27, s43
	s_cselect_b32 s46, s66, s42
	s_cselect_b32 s43, s25, s69
	s_cselect_b32 s42, s67, s68
	v_lshl_add_u64 v[192:193], s[40:41], 0, v[134:135]
	s_add_i32 m0, s29, 0xc000
	s_nop 0
	global_load_lds_dwordx4 v[192:193], off
	v_lshl_add_u64 v[192:193], s[40:41], 0, v[136:137]
	s_add_i32 m0, s29, 0xe000
	s_nop 0
	global_load_lds_dwordx4 v[192:193], off
	ds_read_b128 v[152:155], v144
	ds_read_b128 v[156:159], v144 offset:1024
	ds_read_b128 v[160:163], v144 offset:2048
	ds_read_b128 v[164:167], v144 offset:3072
	ds_read_b128 v[168:171], v145
	ds_read_b128 v[172:175], v145 offset:1024
	ds_read_b128 v[176:179], v145 offset:2048
	ds_read_b128 v[180:183], v145 offset:3072
	ds_read_b128 v[184:187], v150
	ds_read_b128 v[188:191], v150 offset:1024
	ds_read_b128 v[196:199], v150 offset:2048
	ds_read_b128 v[200:203], v150 offset:3072
	ds_read_b128 v[204:207], v150 offset:4096
	ds_read_b128 v[208:211], v150 offset:5120
	ds_read_b128 v[212:215], v150 offset:6144
	ds_read_b128 v[216:219], v150 offset:7168
	s_waitcnt vmcnt(8)
	s_waitcnt lgkmcnt(0)
	s_barrier
	s_setprio 1
	v_mfma_f32_16x16x32_bf16 v[126:129], v[152:155], v[184:187], v[126:129]
	v_mfma_f32_16x16x32_bf16 v[122:125], v[160:163], v[184:187], v[122:125]
	v_mfma_f32_16x16x32_bf16 v[118:121], v[152:155], v[196:199], v[118:121]
	v_mfma_f32_16x16x32_bf16 v[110:113], v[160:163], v[196:199], v[110:113]
	v_mfma_f32_16x16x32_bf16 v[102:105], v[152:155], v[204:207], v[102:105]
	v_mfma_f32_16x16x32_bf16 v[94:97], v[160:163], v[204:207], v[94:97]
	v_mfma_f32_16x16x32_bf16 v[86:89], v[152:155], v[212:215], v[86:89]
	v_mfma_f32_16x16x32_bf16 v[78:81], v[160:163], v[212:215], v[78:81]
	v_mfma_f32_16x16x32_bf16 v[126:129], v[156:159], v[188:191], v[126:129]
	v_mfma_f32_16x16x32_bf16 v[122:125], v[164:167], v[188:191], v[122:125]
	v_mfma_f32_16x16x32_bf16 v[118:121], v[156:159], v[200:203], v[118:121]
	v_mfma_f32_16x16x32_bf16 v[110:113], v[164:167], v[200:203], v[110:113]
	v_mfma_f32_16x16x32_bf16 v[102:105], v[156:159], v[208:211], v[102:105]
	v_mfma_f32_16x16x32_bf16 v[94:97], v[164:167], v[208:211], v[94:97]
	v_mfma_f32_16x16x32_bf16 v[86:89], v[156:159], v[216:219], v[86:89]
	v_mfma_f32_16x16x32_bf16 v[78:81], v[164:167], v[216:219], v[78:81]
	v_mfma_f32_16x16x32_bf16 v[114:117], v[168:171], v[184:187], v[114:117]
	v_mfma_f32_16x16x32_bf16 v[106:109], v[176:179], v[184:187], v[106:109]
	v_mfma_f32_16x16x32_bf16 v[98:101], v[168:171], v[196:199], v[98:101]
	v_mfma_f32_16x16x32_bf16 v[90:93], v[176:179], v[196:199], v[90:93]
	v_mfma_f32_16x16x32_bf16 v[82:85], v[168:171], v[204:207], v[82:85]
	v_mfma_f32_16x16x32_bf16 v[74:77], v[176:179], v[204:207], v[74:77]
	v_mfma_f32_16x16x32_bf16 v[70:73], v[168:171], v[212:215], v[70:73]
	v_mfma_f32_16x16x32_bf16 v[66:69], v[176:179], v[212:215], v[66:69]
	v_mfma_f32_16x16x32_bf16 v[114:117], v[172:175], v[188:191], v[114:117]
	v_mfma_f32_16x16x32_bf16 v[106:109], v[180:183], v[188:191], v[106:109]
	v_mfma_f32_16x16x32_bf16 v[98:101], v[172:175], v[200:203], v[98:101]
	v_mfma_f32_16x16x32_bf16 v[90:93], v[180:183], v[200:203], v[90:93]
	v_mfma_f32_16x16x32_bf16 v[82:85], v[172:175], v[208:211], v[82:85]
	v_mfma_f32_16x16x32_bf16 v[74:77], v[180:183], v[208:211], v[74:77]
	v_mfma_f32_16x16x32_bf16 v[70:73], v[172:175], v[216:219], v[70:73]
	v_mfma_f32_16x16x32_bf16 v[66:69], v[180:183], v[216:219], v[66:69]
	s_setprio 0
	s_barrier
	s_add_i32 s71, s62, s54
	v_lshl_add_u64 v[192:193], s[42:43], 0, v[130:131]
	s_mov_b32 m0, s71
	ds_read_b128 v[184:187], v150 offset:16384
	ds_read_b128 v[188:191], v150 offset:17408
	ds_read_b128 v[196:199], v150 offset:18432
	ds_read_b128 v[200:203], v150 offset:19456
	ds_read_b128 v[204:207], v150 offset:20480
	ds_read_b128 v[208:211], v150 offset:21504
	ds_read_b128 v[212:215], v150 offset:22528
	ds_read_b128 v[216:219], v150 offset:23552
	global_load_lds_dwordx4 v[192:193], off
	s_add_i32 m0, s71, 0x2000
	s_add_u32 s72, s42, 0x100000
	v_lshl_add_u64 v[220:221], s[42:43], 0, v[132:133]
	s_addc_u32 s73, s43, 0
	s_add_i32 s71, s63, s54
	global_load_lds_dwordx4 v[220:221], off
	v_lshl_add_u64 v[222:223], s[72:73], 0, v[130:131]
	s_mov_b32 m0, s71
	v_lshl_add_u64 v[224:225], s[46:47], 0, v[132:133]
	global_load_lds_dwordx4 v[222:223], off
	v_lshl_add_u64 v[222:223], s[72:73], 0, v[132:133]
	s_add_i32 m0, s71, 0x2000
	s_nop 0
	global_load_lds_dwordx4 v[222:223], off
	v_lshl_add_u64 v[222:223], s[46:47], 0, v[130:131]
	s_mov_b32 m0, s29
	s_nop 0
	global_load_lds_dwordx4 v[222:223], off
	s_mov_b32 m0, s55
	s_nop 0
	global_load_lds_dwordx4 v[224:225], off
	s_waitcnt vmcnt(8)
	s_waitcnt lgkmcnt(0)
	s_barrier
	s_setprio 1
	v_mfma_f32_16x16x32_bf16 v[62:65], v[152:155], v[184:187], v[62:65]
	v_mfma_f32_16x16x32_bf16 v[58:61], v[160:163], v[184:187], v[58:61]
	v_mfma_f32_16x16x32_bf16 v[54:57], v[152:155], v[196:199], v[54:57]
	v_mfma_f32_16x16x32_bf16 v[46:49], v[160:163], v[196:199], v[46:49]
	v_mfma_f32_16x16x32_bf16 v[38:41], v[152:155], v[204:207], v[38:41]
	v_mfma_f32_16x16x32_bf16 v[30:33], v[160:163], v[204:207], v[30:33]
	v_mfma_f32_16x16x32_bf16 v[22:25], v[152:155], v[212:215], v[22:25]
	v_mfma_f32_16x16x32_bf16 v[14:17], v[160:163], v[212:215], v[14:17]
	v_mfma_f32_16x16x32_bf16 v[62:65], v[156:159], v[188:191], v[62:65]
	v_mfma_f32_16x16x32_bf16 v[58:61], v[164:167], v[188:191], v[58:61]
	v_mfma_f32_16x16x32_bf16 v[54:57], v[156:159], v[200:203], v[54:57]
	v_mfma_f32_16x16x32_bf16 v[46:49], v[164:167], v[200:203], v[46:49]
	v_mfma_f32_16x16x32_bf16 v[38:41], v[156:159], v[208:211], v[38:41]
	v_mfma_f32_16x16x32_bf16 v[30:33], v[164:167], v[208:211], v[30:33]
	v_mfma_f32_16x16x32_bf16 v[22:25], v[156:159], v[216:219], v[22:25]
	v_mfma_f32_16x16x32_bf16 v[14:17], v[164:167], v[216:219], v[14:17]
	v_mfma_f32_16x16x32_bf16 v[50:53], v[168:171], v[184:187], v[50:53]
	v_mfma_f32_16x16x32_bf16 v[42:45], v[176:179], v[184:187], v[42:45]
	v_mfma_f32_16x16x32_bf16 v[34:37], v[168:171], v[196:199], v[34:37]
	v_mfma_f32_16x16x32_bf16 v[26:29], v[176:179], v[196:199], v[26:29]
	v_mfma_f32_16x16x32_bf16 v[18:21], v[168:171], v[204:207], v[18:21]
	v_mfma_f32_16x16x32_bf16 v[10:13], v[176:179], v[204:207], v[10:13]
	v_mfma_f32_16x16x32_bf16 v[6:9], v[168:171], v[212:215], v[6:9]
	v_mfma_f32_16x16x32_bf16 v[2:5], v[176:179], v[212:215], v[2:5]
	v_mfma_f32_16x16x32_bf16 v[50:53], v[172:175], v[188:191], v[50:53]
	v_mfma_f32_16x16x32_bf16 v[42:45], v[180:183], v[188:191], v[42:45]
	v_mfma_f32_16x16x32_bf16 v[34:37], v[172:175], v[200:203], v[34:37]
	v_mfma_f32_16x16x32_bf16 v[26:29], v[180:183], v[200:203], v[26:29]
	v_mfma_f32_16x16x32_bf16 v[18:21], v[172:175], v[208:211], v[18:21]
	v_mfma_f32_16x16x32_bf16 v[10:13], v[180:183], v[208:211], v[10:13]
	v_mfma_f32_16x16x32_bf16 v[6:9], v[172:175], v[216:219], v[6:9]
	v_mfma_f32_16x16x32_bf16 v[2:5], v[180:183], v[216:219], v[2:5]
	s_setprio 0
	s_barrier
	s_add_u32 s46, s46, 0x100000
	s_addc_u32 s47, s47, 0
	s_mov_b32 m0, s56
	v_lshl_add_u64 v[226:227], s[46:47], 0, v[130:131]
	global_load_lds_dwordx4 v[226:227], off
	v_lshl_add_u64 v[226:227], s[46:47], 0, v[132:133]
	s_mov_b32 m0, s57
	s_nop 0
	global_load_lds_dwordx4 v[226:227], off
	s_add_i32 s71, 0, 0x18000
	v_add_u32_e32 v151, s71, v142
	s_add_i32 s72, 0, 0x1c000
	ds_read_b128 v[152:155], v151
	ds_read_b128 v[156:159], v151 offset:1024
	ds_read_b128 v[160:163], v151 offset:2048
	ds_read_b128 v[164:167], v151 offset:3072
	v_add_u32_e32 v151, s72, v142
	ds_read_b128 v[168:171], v151
	ds_read_b128 v[172:175], v151 offset:1024
	ds_read_b128 v[176:179], v151 offset:2048
	ds_read_b128 v[180:183], v151 offset:3072
	ds_read_b128 v[184:187], v150 offset:32768
	ds_read_b128 v[188:191], v150 offset:33792
	ds_read_b128 v[196:199], v150 offset:34816
	ds_read_b128 v[200:203], v150 offset:35840
	ds_read_b128 v[204:207], v150 offset:36864
	ds_read_b128 v[208:211], v150 offset:37888
	ds_read_b128 v[212:215], v150 offset:38912
	ds_read_b128 v[216:219], v150 offset:39936
	s_waitcnt vmcnt(8)
	s_waitcnt lgkmcnt(0)
	s_barrier
	s_setprio 1
	v_mfma_f32_16x16x32_bf16 v[126:129], v[152:155], v[184:187], v[126:129]
	v_mfma_f32_16x16x32_bf16 v[122:125], v[160:163], v[184:187], v[122:125]
	v_mfma_f32_16x16x32_bf16 v[118:121], v[152:155], v[196:199], v[118:121]
	v_mfma_f32_16x16x32_bf16 v[110:113], v[160:163], v[196:199], v[110:113]
	v_mfma_f32_16x16x32_bf16 v[102:105], v[152:155], v[204:207], v[102:105]
	v_mfma_f32_16x16x32_bf16 v[94:97], v[160:163], v[204:207], v[94:97]
	v_mfma_f32_16x16x32_bf16 v[86:89], v[152:155], v[212:215], v[86:89]
	v_mfma_f32_16x16x32_bf16 v[78:81], v[160:163], v[212:215], v[78:81]
	v_mfma_f32_16x16x32_bf16 v[126:129], v[156:159], v[188:191], v[126:129]
	v_mfma_f32_16x16x32_bf16 v[122:125], v[164:167], v[188:191], v[122:125]
	v_mfma_f32_16x16x32_bf16 v[118:121], v[156:159], v[200:203], v[118:121]
	v_mfma_f32_16x16x32_bf16 v[110:113], v[164:167], v[200:203], v[110:113]
	v_mfma_f32_16x16x32_bf16 v[102:105], v[156:159], v[208:211], v[102:105]
	v_mfma_f32_16x16x32_bf16 v[94:97], v[164:167], v[208:211], v[94:97]
	v_mfma_f32_16x16x32_bf16 v[86:89], v[156:159], v[216:219], v[86:89]
	v_mfma_f32_16x16x32_bf16 v[78:81], v[164:167], v[216:219], v[78:81]
	v_mfma_f32_16x16x32_bf16 v[114:117], v[168:171], v[184:187], v[114:117]
	v_mfma_f32_16x16x32_bf16 v[106:109], v[176:179], v[184:187], v[106:109]
	v_mfma_f32_16x16x32_bf16 v[98:101], v[168:171], v[196:199], v[98:101]
	v_mfma_f32_16x16x32_bf16 v[90:93], v[176:179], v[196:199], v[90:93]
	v_mfma_f32_16x16x32_bf16 v[82:85], v[168:171], v[204:207], v[82:85]
	v_mfma_f32_16x16x32_bf16 v[74:77], v[176:179], v[204:207], v[74:77]
	v_mfma_f32_16x16x32_bf16 v[70:73], v[168:171], v[212:215], v[70:73]
	v_mfma_f32_16x16x32_bf16 v[66:69], v[176:179], v[212:215], v[66:69]
	v_mfma_f32_16x16x32_bf16 v[114:117], v[172:175], v[188:191], v[114:117]
	v_mfma_f32_16x16x32_bf16 v[106:109], v[180:183], v[188:191], v[106:109]
	v_mfma_f32_16x16x32_bf16 v[98:101], v[172:175], v[200:203], v[98:101]
	v_mfma_f32_16x16x32_bf16 v[90:93], v[180:183], v[200:203], v[90:93]
	v_mfma_f32_16x16x32_bf16 v[82:85], v[172:175], v[208:211], v[82:85]
	v_mfma_f32_16x16x32_bf16 v[74:77], v[180:183], v[208:211], v[74:77]
	v_mfma_f32_16x16x32_bf16 v[70:73], v[172:175], v[216:219], v[70:73]
	v_mfma_f32_16x16x32_bf16 v[66:69], v[180:183], v[216:219], v[66:69]
	s_setprio 0
	s_barrier
	s_add_i32 s46, s71, s54
	v_lshl_add_u64 v[192:193], v[192:193], 0, s[10:11]
	s_mov_b32 m0, s46
	ds_read_b128 v[184:187], v150 offset:49152
	ds_read_b128 v[188:191], v150 offset:50176
	ds_read_b128 v[196:199], v150 offset:51200
	ds_read_b128 v[200:203], v150 offset:52224
	ds_read_b128 v[204:207], v150 offset:53248
	ds_read_b128 v[208:211], v150 offset:54272
	ds_read_b128 v[212:215], v150 offset:55296
	ds_read_b128 v[216:219], v150 offset:56320
	global_load_lds_dwordx4 v[192:193], off
	s_add_i32 m0, s46, 0x2000
	s_add_u32 s42, s42, 0x100080
	v_lshl_add_u64 v[192:193], v[220:221], 0, s[10:11]
	s_addc_u32 s43, s43, 0
	s_add_i32 s46, s72, s54
	global_load_lds_dwordx4 v[192:193], off
	v_lshl_add_u64 v[192:193], s[42:43], 0, v[130:131]
	s_mov_b32 m0, s46
	s_nop 0
	global_load_lds_dwordx4 v[192:193], off
	v_lshl_add_u64 v[192:193], s[42:43], 0, v[132:133]
	s_add_i32 m0, s46, 0x2000
	s_nop 0
	global_load_lds_dwordx4 v[192:193], off
	v_lshl_add_u64 v[192:193], v[222:223], 0, s[10:11]
	s_mov_b32 m0, s59
	s_nop 0
	global_load_lds_dwordx4 v[192:193], off
	v_lshl_add_u64 v[192:193], v[224:225], 0, s[10:11]
	s_mov_b32 m0, s60
	s_nop 0
	global_load_lds_dwordx4 v[192:193], off
	s_nop 0
	s_waitcnt vmcnt(8)
	s_waitcnt lgkmcnt(0)
	s_barrier
	s_setprio 1
	v_mfma_f32_16x16x32_bf16 v[62:65], v[152:155], v[184:187], v[62:65]
	v_mfma_f32_16x16x32_bf16 v[58:61], v[160:163], v[184:187], v[58:61]
	v_mfma_f32_16x16x32_bf16 v[54:57], v[152:155], v[196:199], v[54:57]
	v_mfma_f32_16x16x32_bf16 v[46:49], v[160:163], v[196:199], v[46:49]
	v_mfma_f32_16x16x32_bf16 v[38:41], v[152:155], v[204:207], v[38:41]
	v_mfma_f32_16x16x32_bf16 v[30:33], v[160:163], v[204:207], v[30:33]
	v_mfma_f32_16x16x32_bf16 v[22:25], v[152:155], v[212:215], v[22:25]
	v_mfma_f32_16x16x32_bf16 v[14:17], v[160:163], v[212:215], v[14:17]
	v_mfma_f32_16x16x32_bf16 v[62:65], v[156:159], v[188:191], v[62:65]
	v_mfma_f32_16x16x32_bf16 v[58:61], v[164:167], v[188:191], v[58:61]
	v_mfma_f32_16x16x32_bf16 v[54:57], v[156:159], v[200:203], v[54:57]
	v_mfma_f32_16x16x32_bf16 v[46:49], v[164:167], v[200:203], v[46:49]
	v_mfma_f32_16x16x32_bf16 v[38:41], v[156:159], v[208:211], v[38:41]
	v_mfma_f32_16x16x32_bf16 v[30:33], v[164:167], v[208:211], v[30:33]
	v_mfma_f32_16x16x32_bf16 v[22:25], v[156:159], v[216:219], v[22:25]
	v_mfma_f32_16x16x32_bf16 v[14:17], v[164:167], v[216:219], v[14:17]
	v_mfma_f32_16x16x32_bf16 v[50:53], v[168:171], v[184:187], v[50:53]
	v_mfma_f32_16x16x32_bf16 v[42:45], v[176:179], v[184:187], v[42:45]
	v_mfma_f32_16x16x32_bf16 v[34:37], v[168:171], v[196:199], v[34:37]
	v_mfma_f32_16x16x32_bf16 v[26:29], v[176:179], v[196:199], v[26:29]
	v_mfma_f32_16x16x32_bf16 v[18:21], v[168:171], v[204:207], v[18:21]
	v_mfma_f32_16x16x32_bf16 v[10:13], v[176:179], v[204:207], v[10:13]
	v_mfma_f32_16x16x32_bf16 v[6:9], v[168:171], v[212:215], v[6:9]
	v_mfma_f32_16x16x32_bf16 v[2:5], v[176:179], v[212:215], v[2:5]
	v_mfma_f32_16x16x32_bf16 v[50:53], v[172:175], v[188:191], v[50:53]
	v_mfma_f32_16x16x32_bf16 v[42:45], v[180:183], v[188:191], v[42:45]
	v_mfma_f32_16x16x32_bf16 v[34:37], v[172:175], v[200:203], v[34:37]
	v_mfma_f32_16x16x32_bf16 v[26:29], v[180:183], v[200:203], v[26:29]
	v_mfma_f32_16x16x32_bf16 v[18:21], v[172:175], v[208:211], v[18:21]
	v_mfma_f32_16x16x32_bf16 v[10:13], v[180:183], v[208:211], v[10:13]
	v_mfma_f32_16x16x32_bf16 v[6:9], v[172:175], v[216:219], v[6:9]
	v_mfma_f32_16x16x32_bf16 v[2:5], v[180:183], v[216:219], v[2:5]
	s_setprio 0
	s_barrier
	s_add_i32 s70, s70, 2
	s_add_u32 s40, s40, 0x100
	s_addc_u32 s41, s41, 0
	s_add_u32 s68, s68, 0x100
	s_addc_u32 s69, s69, 0
	s_cmp_gt_u32 s70, 61
	s_cbranch_scc0 .LBB0_681
	s_and_b64 vcc, exec, s[12:13]
	s_cbranch_vccz .LBB0_684
	s_barrier

.LBB0_705:
	s_add_u32 s42, s40, 0xfff00080
	s_addc_u32 s43, s41, -1
	s_cmp_eq_u32 s67, 60
	s_cselect_b32 s47, s27, s43
	s_cselect_b32 s46, s63, s42
	s_cselect_b32 s43, s25, s66
	s_cselect_b32 s42, s64, s65
	v_lshl_add_u64 v[192:193], s[40:41], 0, v[134:135]
	s_add_i32 m0, s29, 0xc000
	s_nop 0
	global_load_lds_dwordx4 v[192:193], off
	v_lshl_add_u64 v[192:193], s[40:41], 0, v[136:137]
	s_add_i32 m0, s29, 0xe000
	s_nop 0
	global_load_lds_dwordx4 v[192:193], off
	ds_read_b128 v[144:147], v139
	ds_read_b128 v[148:151], v139 offset:1024
	ds_read_b128 v[152:155], v139 offset:2048
	ds_read_b128 v[156:159], v139 offset:3072
	ds_read_b128 v[160:163], v140
	ds_read_b128 v[164:167], v140 offset:1024
	ds_read_b128 v[168:171], v140 offset:2048
	ds_read_b128 v[172:175], v140 offset:3072
	ds_read_b128 v[176:179], v142
	ds_read_b128 v[180:183], v142 offset:1024
	ds_read_b128 v[184:187], v142 offset:2048
	ds_read_b128 v[188:191], v142 offset:3072
	ds_read_b128 v[196:199], v142 offset:4096
	ds_read_b128 v[200:203], v142 offset:5120
	ds_read_b128 v[204:207], v142 offset:6144
	ds_read_b128 v[208:211], v142 offset:7168
	s_waitcnt vmcnt(8)
	s_waitcnt lgkmcnt(0)
	s_barrier
	s_setprio 1
	v_mfma_f32_16x16x32_bf16 v[126:129], v[144:147], v[176:179], v[126:129]
	v_mfma_f32_16x16x32_bf16 v[122:125], v[152:155], v[176:179], v[122:125]
	v_mfma_f32_16x16x32_bf16 v[118:121], v[144:147], v[184:187], v[118:121]
	v_mfma_f32_16x16x32_bf16 v[110:113], v[152:155], v[184:187], v[110:113]
	v_mfma_f32_16x16x32_bf16 v[102:105], v[144:147], v[196:199], v[102:105]
	v_mfma_f32_16x16x32_bf16 v[94:97], v[152:155], v[196:199], v[94:97]
	v_mfma_f32_16x16x32_bf16 v[86:89], v[144:147], v[204:207], v[86:89]
	v_mfma_f32_16x16x32_bf16 v[78:81], v[152:155], v[204:207], v[78:81]
	v_mfma_f32_16x16x32_bf16 v[126:129], v[148:151], v[180:183], v[126:129]
	v_mfma_f32_16x16x32_bf16 v[122:125], v[156:159], v[180:183], v[122:125]
	v_mfma_f32_16x16x32_bf16 v[118:121], v[148:151], v[188:191], v[118:121]
	v_mfma_f32_16x16x32_bf16 v[110:113], v[156:159], v[188:191], v[110:113]
	v_mfma_f32_16x16x32_bf16 v[102:105], v[148:151], v[200:203], v[102:105]
	v_mfma_f32_16x16x32_bf16 v[94:97], v[156:159], v[200:203], v[94:97]
	v_mfma_f32_16x16x32_bf16 v[86:89], v[148:151], v[208:211], v[86:89]
	v_mfma_f32_16x16x32_bf16 v[78:81], v[156:159], v[208:211], v[78:81]
	v_mfma_f32_16x16x32_bf16 v[114:117], v[160:163], v[176:179], v[114:117]
	v_mfma_f32_16x16x32_bf16 v[106:109], v[168:171], v[176:179], v[106:109]
	v_mfma_f32_16x16x32_bf16 v[98:101], v[160:163], v[184:187], v[98:101]
	v_mfma_f32_16x16x32_bf16 v[90:93], v[168:171], v[184:187], v[90:93]
	v_mfma_f32_16x16x32_bf16 v[82:85], v[160:163], v[196:199], v[82:85]
	v_mfma_f32_16x16x32_bf16 v[74:77], v[168:171], v[196:199], v[74:77]
	v_mfma_f32_16x16x32_bf16 v[70:73], v[160:163], v[204:207], v[70:73]
	v_mfma_f32_16x16x32_bf16 v[66:69], v[168:171], v[204:207], v[66:69]
	v_mfma_f32_16x16x32_bf16 v[114:117], v[164:167], v[180:183], v[114:117]
	v_mfma_f32_16x16x32_bf16 v[106:109], v[172:175], v[180:183], v[106:109]
	v_mfma_f32_16x16x32_bf16 v[98:101], v[164:167], v[188:191], v[98:101]
	v_mfma_f32_16x16x32_bf16 v[90:93], v[172:175], v[188:191], v[90:93]
	v_mfma_f32_16x16x32_bf16 v[82:85], v[164:167], v[200:203], v[82:85]
	v_mfma_f32_16x16x32_bf16 v[74:77], v[172:175], v[200:203], v[74:77]
	v_mfma_f32_16x16x32_bf16 v[70:73], v[164:167], v[208:211], v[70:73]
	v_mfma_f32_16x16x32_bf16 v[66:69], v[172:175], v[208:211], v[66:69]
	s_setprio 0
	s_barrier
	s_add_i32 s68, s59, s51
	v_lshl_add_u64 v[192:193], s[42:43], 0, v[130:131]
	s_mov_b32 m0, s68
	ds_read_b128 v[176:179], v142 offset:16384
	ds_read_b128 v[180:183], v142 offset:17408
	ds_read_b128 v[184:187], v142 offset:18432
	ds_read_b128 v[188:191], v142 offset:19456
	ds_read_b128 v[196:199], v142 offset:20480
	ds_read_b128 v[200:203], v142 offset:21504
	ds_read_b128 v[204:207], v142 offset:22528
	ds_read_b128 v[208:211], v142 offset:23552
	global_load_lds_dwordx4 v[192:193], off
	s_add_i32 m0, s68, 0x2000
	s_add_u32 s68, s42, 0x100000
	v_lshl_add_u64 v[212:213], s[42:43], 0, v[132:133]
	s_addc_u32 s69, s43, 0
	s_add_i32 s70, s60, s51
	global_load_lds_dwordx4 v[212:213], off
	v_lshl_add_u64 v[214:215], s[68:69], 0, v[130:131]
	s_mov_b32 m0, s70
	v_lshl_add_u64 v[216:217], s[46:47], 0, v[132:133]
	global_load_lds_dwordx4 v[214:215], off
	v_lshl_add_u64 v[214:215], s[68:69], 0, v[132:133]
	s_add_i32 m0, s70, 0x2000
	s_nop 0
	global_load_lds_dwordx4 v[214:215], off
	v_lshl_add_u64 v[214:215], s[46:47], 0, v[130:131]
	s_mov_b32 m0, s29
	s_nop 0
	global_load_lds_dwordx4 v[214:215], off
	s_mov_b32 m0, s52
	s_nop 0
	global_load_lds_dwordx4 v[216:217], off
	s_waitcnt vmcnt(8)
	s_waitcnt lgkmcnt(0)
	s_barrier
	s_setprio 1
	v_mfma_f32_16x16x32_bf16 v[62:65], v[144:147], v[176:179], v[62:65]
	v_mfma_f32_16x16x32_bf16 v[58:61], v[152:155], v[176:179], v[58:61]
	v_mfma_f32_16x16x32_bf16 v[54:57], v[144:147], v[184:187], v[54:57]
	v_mfma_f32_16x16x32_bf16 v[46:49], v[152:155], v[184:187], v[46:49]
	v_mfma_f32_16x16x32_bf16 v[38:41], v[144:147], v[196:199], v[38:41]
	v_mfma_f32_16x16x32_bf16 v[30:33], v[152:155], v[196:199], v[30:33]
	v_mfma_f32_16x16x32_bf16 v[22:25], v[144:147], v[204:207], v[22:25]
	v_mfma_f32_16x16x32_bf16 v[14:17], v[152:155], v[204:207], v[14:17]
	v_mfma_f32_16x16x32_bf16 v[62:65], v[148:151], v[180:183], v[62:65]
	v_mfma_f32_16x16x32_bf16 v[58:61], v[156:159], v[180:183], v[58:61]
	v_mfma_f32_16x16x32_bf16 v[54:57], v[148:151], v[188:191], v[54:57]
	v_mfma_f32_16x16x32_bf16 v[46:49], v[156:159], v[188:191], v[46:49]
	v_mfma_f32_16x16x32_bf16 v[38:41], v[148:151], v[200:203], v[38:41]
	v_mfma_f32_16x16x32_bf16 v[30:33], v[156:159], v[200:203], v[30:33]
	v_mfma_f32_16x16x32_bf16 v[22:25], v[148:151], v[208:211], v[22:25]
	v_mfma_f32_16x16x32_bf16 v[14:17], v[156:159], v[208:211], v[14:17]
	v_mfma_f32_16x16x32_bf16 v[50:53], v[160:163], v[176:179], v[50:53]
	v_mfma_f32_16x16x32_bf16 v[42:45], v[168:171], v[176:179], v[42:45]
	v_mfma_f32_16x16x32_bf16 v[34:37], v[160:163], v[184:187], v[34:37]
	v_mfma_f32_16x16x32_bf16 v[26:29], v[168:171], v[184:187], v[26:29]
	v_mfma_f32_16x16x32_bf16 v[18:21], v[160:163], v[196:199], v[18:21]
	v_mfma_f32_16x16x32_bf16 v[10:13], v[168:171], v[196:199], v[10:13]
	v_mfma_f32_16x16x32_bf16 v[6:9], v[160:163], v[204:207], v[6:9]
	v_mfma_f32_16x16x32_bf16 v[2:5], v[168:171], v[204:207], v[2:5]
	v_mfma_f32_16x16x32_bf16 v[50:53], v[164:167], v[180:183], v[50:53]
	v_mfma_f32_16x16x32_bf16 v[42:45], v[172:175], v[180:183], v[42:45]
	v_mfma_f32_16x16x32_bf16 v[34:37], v[164:167], v[188:191], v[34:37]
	v_mfma_f32_16x16x32_bf16 v[26:29], v[172:175], v[188:191], v[26:29]
	v_mfma_f32_16x16x32_bf16 v[18:21], v[164:167], v[200:203], v[18:21]
	v_mfma_f32_16x16x32_bf16 v[10:13], v[172:175], v[200:203], v[10:13]
	v_mfma_f32_16x16x32_bf16 v[6:9], v[164:167], v[208:211], v[6:9]
	v_mfma_f32_16x16x32_bf16 v[2:5], v[172:175], v[208:211], v[2:5]
	s_setprio 0
	s_barrier
	s_add_u32 s46, s46, 0x100000
	s_addc_u32 s47, s47, 0
	s_mov_b32 m0, s53
	v_lshl_add_u64 v[218:219], s[46:47], 0, v[130:131]
	global_load_lds_dwordx4 v[218:219], off
	v_lshl_add_u64 v[218:219], s[46:47], 0, v[132:133]
	s_mov_b32 m0, s54
	s_nop 0
	global_load_lds_dwordx4 v[218:219], off
	s_add_i32 s68, 0, 0x18000
	v_add_u32_e32 v143, s68, v1
	s_add_i32 s69, 0, 0x1c000
	ds_read_b128 v[144:147], v143
	ds_read_b128 v[148:151], v143 offset:1024
	ds_read_b128 v[152:155], v143 offset:2048
	ds_read_b128 v[156:159], v143 offset:3072
	v_add_u32_e32 v143, s69, v1
	ds_read_b128 v[160:163], v143
	ds_read_b128 v[164:167], v143 offset:1024
	ds_read_b128 v[168:171], v143 offset:2048
	ds_read_b128 v[172:175], v143 offset:3072
	ds_read_b128 v[176:179], v142 offset:32768
	ds_read_b128 v[180:183], v142 offset:33792
	ds_read_b128 v[184:187], v142 offset:34816
	ds_read_b128 v[188:191], v142 offset:35840
	ds_read_b128 v[196:199], v142 offset:36864
	ds_read_b128 v[200:203], v142 offset:37888
	ds_read_b128 v[204:207], v142 offset:38912
	ds_read_b128 v[208:211], v142 offset:39936
	s_waitcnt vmcnt(8)
	s_waitcnt lgkmcnt(0)
	s_barrier
	s_setprio 1
	v_mfma_f32_16x16x32_bf16 v[126:129], v[144:147], v[176:179], v[126:129]
	v_mfma_f32_16x16x32_bf16 v[122:125], v[152:155], v[176:179], v[122:125]
	v_mfma_f32_16x16x32_bf16 v[118:121], v[144:147], v[184:187], v[118:121]
	v_mfma_f32_16x16x32_bf16 v[110:113], v[152:155], v[184:187], v[110:113]
	v_mfma_f32_16x16x32_bf16 v[102:105], v[144:147], v[196:199], v[102:105]
	v_mfma_f32_16x16x32_bf16 v[94:97], v[152:155], v[196:199], v[94:97]
	v_mfma_f32_16x16x32_bf16 v[86:89], v[144:147], v[204:207], v[86:89]
	v_mfma_f32_16x16x32_bf16 v[78:81], v[152:155], v[204:207], v[78:81]
	v_mfma_f32_16x16x32_bf16 v[126:129], v[148:151], v[180:183], v[126:129]
	v_mfma_f32_16x16x32_bf16 v[122:125], v[156:159], v[180:183], v[122:125]
	v_mfma_f32_16x16x32_bf16 v[118:121], v[148:151], v[188:191], v[118:121]
	v_mfma_f32_16x16x32_bf16 v[110:113], v[156:159], v[188:191], v[110:113]
	v_mfma_f32_16x16x32_bf16 v[102:105], v[148:151], v[200:203], v[102:105]
	v_mfma_f32_16x16x32_bf16 v[94:97], v[156:159], v[200:203], v[94:97]
	v_mfma_f32_16x16x32_bf16 v[86:89], v[148:151], v[208:211], v[86:89]
	v_mfma_f32_16x16x32_bf16 v[78:81], v[156:159], v[208:211], v[78:81]
	v_mfma_f32_16x16x32_bf16 v[114:117], v[160:163], v[176:179], v[114:117]
	v_mfma_f32_16x16x32_bf16 v[106:109], v[168:171], v[176:179], v[106:109]
	v_mfma_f32_16x16x32_bf16 v[98:101], v[160:163], v[184:187], v[98:101]
	v_mfma_f32_16x16x32_bf16 v[90:93], v[168:171], v[184:187], v[90:93]
	v_mfma_f32_16x16x32_bf16 v[82:85], v[160:163], v[196:199], v[82:85]
	v_mfma_f32_16x16x32_bf16 v[74:77], v[168:171], v[196:199], v[74:77]
	v_mfma_f32_16x16x32_bf16 v[70:73], v[160:163], v[204:207], v[70:73]
	v_mfma_f32_16x16x32_bf16 v[66:69], v[168:171], v[204:207], v[66:69]
	v_mfma_f32_16x16x32_bf16 v[114:117], v[164:167], v[180:183], v[114:117]
	v_mfma_f32_16x16x32_bf16 v[106:109], v[172:175], v[180:183], v[106:109]
	v_mfma_f32_16x16x32_bf16 v[98:101], v[164:167], v[188:191], v[98:101]
	v_mfma_f32_16x16x32_bf16 v[90:93], v[172:175], v[188:191], v[90:93]
	v_mfma_f32_16x16x32_bf16 v[82:85], v[164:167], v[200:203], v[82:85]
	v_mfma_f32_16x16x32_bf16 v[74:77], v[172:175], v[200:203], v[74:77]
	v_mfma_f32_16x16x32_bf16 v[70:73], v[164:167], v[208:211], v[70:73]
	v_mfma_f32_16x16x32_bf16 v[66:69], v[172:175], v[208:211], v[66:69]
	s_setprio 0
	s_barrier
	s_add_i32 s46, s68, s51
	v_lshl_add_u64 v[192:193], v[192:193], 0, s[10:11]
	s_mov_b32 m0, s46
	ds_read_b128 v[176:179], v142 offset:49152
	ds_read_b128 v[180:183], v142 offset:50176
	ds_read_b128 v[184:187], v142 offset:51200
	ds_read_b128 v[188:191], v142 offset:52224
	ds_read_b128 v[196:199], v142 offset:53248
	ds_read_b128 v[200:203], v142 offset:54272
	ds_read_b128 v[204:207], v142 offset:55296
	ds_read_b128 v[208:211], v142 offset:56320
	global_load_lds_dwordx4 v[192:193], off
	s_add_i32 m0, s46, 0x2000
	s_add_u32 s42, s42, 0x100080
	v_lshl_add_u64 v[192:193], v[212:213], 0, s[10:11]
	s_addc_u32 s43, s43, 0
	s_add_i32 s46, s69, s51
	global_load_lds_dwordx4 v[192:193], off
	v_lshl_add_u64 v[192:193], s[42:43], 0, v[130:131]
	s_mov_b32 m0, s46
	s_nop 0
	global_load_lds_dwordx4 v[192:193], off
	v_lshl_add_u64 v[192:193], s[42:43], 0, v[132:133]
	s_add_i32 m0, s46, 0x2000
	s_nop 0
	global_load_lds_dwordx4 v[192:193], off
	v_lshl_add_u64 v[192:193], v[214:215], 0, s[10:11]
	s_mov_b32 m0, s56
	s_nop 0
	global_load_lds_dwordx4 v[192:193], off
	v_lshl_add_u64 v[192:193], v[216:217], 0, s[10:11]
	s_mov_b32 m0, s57
	s_nop 0
	global_load_lds_dwordx4 v[192:193], off
	s_nop 0
	s_waitcnt vmcnt(8)
	s_waitcnt lgkmcnt(0)
	s_barrier
	s_setprio 1
	v_mfma_f32_16x16x32_bf16 v[62:65], v[144:147], v[176:179], v[62:65]
	v_mfma_f32_16x16x32_bf16 v[58:61], v[152:155], v[176:179], v[58:61]
	v_mfma_f32_16x16x32_bf16 v[54:57], v[144:147], v[184:187], v[54:57]
	v_mfma_f32_16x16x32_bf16 v[46:49], v[152:155], v[184:187], v[46:49]
	v_mfma_f32_16x16x32_bf16 v[38:41], v[144:147], v[196:199], v[38:41]
	v_mfma_f32_16x16x32_bf16 v[30:33], v[152:155], v[196:199], v[30:33]
	v_mfma_f32_16x16x32_bf16 v[22:25], v[144:147], v[204:207], v[22:25]
	v_mfma_f32_16x16x32_bf16 v[14:17], v[152:155], v[204:207], v[14:17]
	v_mfma_f32_16x16x32_bf16 v[62:65], v[148:151], v[180:183], v[62:65]
	v_mfma_f32_16x16x32_bf16 v[58:61], v[156:159], v[180:183], v[58:61]
	v_mfma_f32_16x16x32_bf16 v[54:57], v[148:151], v[188:191], v[54:57]
	v_mfma_f32_16x16x32_bf16 v[46:49], v[156:159], v[188:191], v[46:49]
	v_mfma_f32_16x16x32_bf16 v[38:41], v[148:151], v[200:203], v[38:41]
	v_mfma_f32_16x16x32_bf16 v[30:33], v[156:159], v[200:203], v[30:33]
	v_mfma_f32_16x16x32_bf16 v[22:25], v[148:151], v[208:211], v[22:25]
	v_mfma_f32_16x16x32_bf16 v[14:17], v[156:159], v[208:211], v[14:17]
	v_mfma_f32_16x16x32_bf16 v[50:53], v[160:163], v[176:179], v[50:53]
	v_mfma_f32_16x16x32_bf16 v[42:45], v[168:171], v[176:179], v[42:45]
	v_mfma_f32_16x16x32_bf16 v[34:37], v[160:163], v[184:187], v[34:37]
	v_mfma_f32_16x16x32_bf16 v[26:29], v[168:171], v[184:187], v[26:29]
	v_mfma_f32_16x16x32_bf16 v[18:21], v[160:163], v[196:199], v[18:21]
	v_mfma_f32_16x16x32_bf16 v[10:13], v[168:171], v[196:199], v[10:13]
	v_mfma_f32_16x16x32_bf16 v[6:9], v[160:163], v[204:207], v[6:9]
	v_mfma_f32_16x16x32_bf16 v[2:5], v[168:171], v[204:207], v[2:5]
	v_mfma_f32_16x16x32_bf16 v[50:53], v[164:167], v[180:183], v[50:53]
	v_mfma_f32_16x16x32_bf16 v[42:45], v[172:175], v[180:183], v[42:45]
	v_mfma_f32_16x16x32_bf16 v[34:37], v[164:167], v[188:191], v[34:37]
	v_mfma_f32_16x16x32_bf16 v[26:29], v[172:175], v[188:191], v[26:29]
	v_mfma_f32_16x16x32_bf16 v[18:21], v[164:167], v[200:203], v[18:21]
	v_mfma_f32_16x16x32_bf16 v[10:13], v[172:175], v[200:203], v[10:13]
	v_mfma_f32_16x16x32_bf16 v[6:9], v[164:167], v[208:211], v[6:9]
	v_mfma_f32_16x16x32_bf16 v[2:5], v[172:175], v[208:211], v[2:5]
	s_setprio 0
	s_barrier
	s_add_i32 s67, s67, 2
	s_add_u32 s40, s40, 0x100
	s_addc_u32 s41, s41, 0
	s_add_u32 s65, s65, 0x100
	s_addc_u32 s66, s66, 0
	s_cmp_gt_u32 s67, 61
	s_cbranch_scc0 .LBB0_705
	s_and_b64 vcc, exec, s[12:13]
	s_cbranch_vccz .LBB0_708
	s_barrier

.LBB0_967:
	s_add_u32 s30, s28, 0xfff80080
	s_addc_u32 s31, s29, -1
	s_cmp_eq_u32 s57, 28
	s_cselect_b32 s35, s21, s31
	s_cselect_b32 s34, s53, s30
	s_cselect_b32 s31, s19, s56
	s_cselect_b32 s30, s54, s55
	v_lshl_add_u64 v[192:193], s[28:29], 0, v[138:139]
	s_add_i32 m0, s27, 0xc000
	s_nop 0
	global_load_lds_dwordx4 v[192:193], off
	v_lshl_add_u64 v[192:193], s[28:29], 0, v[140:141]
	s_add_i32 m0, s27, 0xe000
	s_nop 0
	global_load_lds_dwordx4 v[192:193], off
	ds_read_b128 v[146:149], v152
	ds_read_b128 v[156:159], v152 offset:1024
	ds_read_b128 v[160:163], v152 offset:2048
	ds_read_b128 v[164:167], v152 offset:3072
	ds_read_b128 v[168:171], v153
	ds_read_b128 v[172:175], v153 offset:1024
	ds_read_b128 v[176:179], v153 offset:2048
	ds_read_b128 v[180:183], v153 offset:3072
	ds_read_b128 v[184:187], v154
	ds_read_b128 v[188:191], v154 offset:1024
	ds_read_b128 v[196:199], v154 offset:2048
	ds_read_b128 v[200:203], v154 offset:3072
	ds_read_b128 v[206:209], v154 offset:4096
	ds_read_b128 v[210:213], v154 offset:5120
	ds_read_b128 v[214:217], v154 offset:6144
	ds_read_b128 v[218:221], v154 offset:7168
	s_waitcnt vmcnt(8)
	s_waitcnt lgkmcnt(0)
	s_barrier
	s_setprio 1
	v_mfma_f32_16x16x32_bf16 v[126:129], v[146:149], v[184:187], v[126:129]
	v_mfma_f32_16x16x32_bf16 v[122:125], v[160:163], v[184:187], v[122:125]
	v_mfma_f32_16x16x32_bf16 v[110:113], v[146:149], v[196:199], v[110:113]
	v_mfma_f32_16x16x32_bf16 v[106:109], v[160:163], v[196:199], v[106:109]
	v_mfma_f32_16x16x32_bf16 v[98:101], v[146:149], v[206:209], v[98:101]
	v_mfma_f32_16x16x32_bf16 v[90:93], v[160:163], v[206:209], v[90:93]
	v_mfma_f32_16x16x32_bf16 v[78:81], v[146:149], v[214:217], v[78:81]
	v_mfma_f32_16x16x32_bf16 v[74:77], v[160:163], v[214:217], v[74:77]
	v_mfma_f32_16x16x32_bf16 v[126:129], v[156:159], v[188:191], v[126:129]
	v_mfma_f32_16x16x32_bf16 v[122:125], v[164:167], v[188:191], v[122:125]
	v_mfma_f32_16x16x32_bf16 v[110:113], v[156:159], v[200:203], v[110:113]
	v_mfma_f32_16x16x32_bf16 v[106:109], v[164:167], v[200:203], v[106:109]
	v_mfma_f32_16x16x32_bf16 v[98:101], v[156:159], v[210:213], v[98:101]
	v_mfma_f32_16x16x32_bf16 v[90:93], v[164:167], v[210:213], v[90:93]
	v_mfma_f32_16x16x32_bf16 v[78:81], v[156:159], v[218:221], v[78:81]
	v_mfma_f32_16x16x32_bf16 v[74:77], v[164:167], v[218:221], v[74:77]
	v_mfma_f32_16x16x32_bf16 v[118:121], v[168:171], v[184:187], v[118:121]
	v_mfma_f32_16x16x32_bf16 v[114:117], v[176:179], v[184:187], v[114:117]
	v_mfma_f32_16x16x32_bf16 v[102:105], v[168:171], v[196:199], v[102:105]
	v_mfma_f32_16x16x32_bf16 v[94:97], v[176:179], v[196:199], v[94:97]
	v_mfma_f32_16x16x32_bf16 v[86:89], v[168:171], v[206:209], v[86:89]
	v_mfma_f32_16x16x32_bf16 v[82:85], v[176:179], v[206:209], v[82:85]
	v_mfma_f32_16x16x32_bf16 v[70:73], v[168:171], v[214:217], v[70:73]
	v_mfma_f32_16x16x32_bf16 v[66:69], v[176:179], v[214:217], v[66:69]
	v_mfma_f32_16x16x32_bf16 v[118:121], v[172:175], v[188:191], v[118:121]
	v_mfma_f32_16x16x32_bf16 v[114:117], v[180:183], v[188:191], v[114:117]
	v_mfma_f32_16x16x32_bf16 v[102:105], v[172:175], v[200:203], v[102:105]
	v_mfma_f32_16x16x32_bf16 v[94:97], v[180:183], v[200:203], v[94:97]
	v_mfma_f32_16x16x32_bf16 v[86:89], v[172:175], v[210:213], v[86:89]
	v_mfma_f32_16x16x32_bf16 v[82:85], v[180:183], v[210:213], v[82:85]
	v_mfma_f32_16x16x32_bf16 v[70:73], v[172:175], v[218:221], v[70:73]
	v_mfma_f32_16x16x32_bf16 v[66:69], v[180:183], v[218:221], v[66:69]
	s_setprio 0
	s_barrier
	s_add_i32 s58, s50, s40
	v_lshl_add_u64 v[192:193], s[30:31], 0, v[134:135]
	s_mov_b32 m0, s58
	ds_read_b128 v[184:187], v154 offset:16384
	ds_read_b128 v[188:191], v154 offset:17408
	ds_read_b128 v[196:199], v154 offset:18432
	ds_read_b128 v[200:203], v154 offset:19456
	ds_read_b128 v[206:209], v154 offset:20480
	ds_read_b128 v[210:213], v154 offset:21504
	ds_read_b128 v[214:217], v154 offset:22528
	ds_read_b128 v[218:221], v154 offset:23552
	global_load_lds_dwordx4 v[192:193], off
	s_add_i32 m0, s58, 0x2000
	s_add_u32 s58, s30, 0x80000
	v_lshl_add_u64 v[222:223], s[30:31], 0, v[130:131]
	s_addc_u32 s59, s31, 0
	s_add_i32 s60, s51, s40
	global_load_lds_dwordx4 v[222:223], off
	v_lshl_add_u64 v[224:225], s[58:59], 0, v[134:135]
	s_mov_b32 m0, s60
	v_lshl_add_u64 v[226:227], s[34:35], 0, v[132:133]
	global_load_lds_dwordx4 v[224:225], off
	v_lshl_add_u64 v[224:225], s[58:59], 0, v[130:131]
	s_add_i32 m0, s60, 0x2000
	s_nop 0
	global_load_lds_dwordx4 v[224:225], off
	v_lshl_add_u64 v[224:225], s[34:35], 0, v[136:137]
	s_mov_b32 m0, s27
	s_nop 0
	global_load_lds_dwordx4 v[224:225], off
	s_mov_b32 m0, s42
	s_nop 0
	global_load_lds_dwordx4 v[226:227], off
	s_waitcnt vmcnt(8)
	s_waitcnt lgkmcnt(0)
	s_barrier
	s_setprio 1
	v_mfma_f32_16x16x32_bf16 v[62:65], v[146:149], v[184:187], v[62:65]
	v_mfma_f32_16x16x32_bf16 v[58:61], v[160:163], v[184:187], v[58:61]
	v_mfma_f32_16x16x32_bf16 v[46:49], v[146:149], v[196:199], v[46:49]
	v_mfma_f32_16x16x32_bf16 v[42:45], v[160:163], v[196:199], v[42:45]
	v_mfma_f32_16x16x32_bf16 v[30:33], v[146:149], v[206:209], v[30:33]
	v_mfma_f32_16x16x32_bf16 v[26:29], v[160:163], v[206:209], v[26:29]
	v_mfma_f32_16x16x32_bf16 v[14:17], v[146:149], v[214:217], v[14:17]
	v_mfma_f32_16x16x32_bf16 v[10:13], v[160:163], v[214:217], v[10:13]
	v_mfma_f32_16x16x32_bf16 v[62:65], v[156:159], v[188:191], v[62:65]
	v_mfma_f32_16x16x32_bf16 v[58:61], v[164:167], v[188:191], v[58:61]
	v_mfma_f32_16x16x32_bf16 v[46:49], v[156:159], v[200:203], v[46:49]
	v_mfma_f32_16x16x32_bf16 v[42:45], v[164:167], v[200:203], v[42:45]
	v_mfma_f32_16x16x32_bf16 v[30:33], v[156:159], v[210:213], v[30:33]
	v_mfma_f32_16x16x32_bf16 v[26:29], v[164:167], v[210:213], v[26:29]
	v_mfma_f32_16x16x32_bf16 v[14:17], v[156:159], v[218:221], v[14:17]
	v_mfma_f32_16x16x32_bf16 v[10:13], v[164:167], v[218:221], v[10:13]
	v_mfma_f32_16x16x32_bf16 v[54:57], v[168:171], v[184:187], v[54:57]
	v_mfma_f32_16x16x32_bf16 v[50:53], v[176:179], v[184:187], v[50:53]
	v_mfma_f32_16x16x32_bf16 v[38:41], v[168:171], v[196:199], v[38:41]
	v_mfma_f32_16x16x32_bf16 v[34:37], v[176:179], v[196:199], v[34:37]
	v_mfma_f32_16x16x32_bf16 v[22:25], v[168:171], v[206:209], v[22:25]
	v_mfma_f32_16x16x32_bf16 v[18:21], v[176:179], v[206:209], v[18:21]
	v_mfma_f32_16x16x32_bf16 v[6:9], v[168:171], v[214:217], v[6:9]
	v_mfma_f32_16x16x32_bf16 v[2:5], v[176:179], v[214:217], v[2:5]
	v_mfma_f32_16x16x32_bf16 v[54:57], v[172:175], v[188:191], v[54:57]
	v_mfma_f32_16x16x32_bf16 v[50:53], v[180:183], v[188:191], v[50:53]
	v_mfma_f32_16x16x32_bf16 v[38:41], v[172:175], v[200:203], v[38:41]
	v_mfma_f32_16x16x32_bf16 v[34:37], v[180:183], v[200:203], v[34:37]
	v_mfma_f32_16x16x32_bf16 v[22:25], v[172:175], v[210:213], v[22:25]
	v_mfma_f32_16x16x32_bf16 v[18:21], v[180:183], v[210:213], v[18:21]
	v_mfma_f32_16x16x32_bf16 v[6:9], v[172:175], v[218:221], v[6:9]
	v_mfma_f32_16x16x32_bf16 v[2:5], v[180:183], v[218:221], v[2:5]
	s_setprio 0
	s_barrier
	s_add_u32 s34, s34, 0x80000
	s_addc_u32 s35, s35, 0
	s_mov_b32 m0, s43
	v_lshl_add_u64 v[228:229], s[34:35], 0, v[136:137]
	global_load_lds_dwordx4 v[228:229], off
	v_lshl_add_u64 v[228:229], s[34:35], 0, v[132:133]
	s_mov_b32 m0, s45
	s_nop 0
	global_load_lds_dwordx4 v[228:229], off
	s_add_i32 s58, 0, 0x18000
	v_add_u32_e32 v155, s58, v150
	s_add_i32 s59, 0, 0x1c000
	ds_read_b128 v[146:149], v155
	ds_read_b128 v[156:159], v155 offset:1024
	ds_read_b128 v[160:163], v155 offset:2048
	ds_read_b128 v[164:167], v155 offset:3072
	v_add_u32_e32 v155, s59, v150
	ds_read_b128 v[168:171], v155
	ds_read_b128 v[172:175], v155 offset:1024
	ds_read_b128 v[176:179], v155 offset:2048
	ds_read_b128 v[180:183], v155 offset:3072
	ds_read_b128 v[184:187], v154 offset:32768
	ds_read_b128 v[188:191], v154 offset:33792
	ds_read_b128 v[196:199], v154 offset:34816
	ds_read_b128 v[200:203], v154 offset:35840
	ds_read_b128 v[206:209], v154 offset:36864
	ds_read_b128 v[210:213], v154 offset:37888
	ds_read_b128 v[214:217], v154 offset:38912
	ds_read_b128 v[218:221], v154 offset:39936
	s_waitcnt vmcnt(8)
	s_waitcnt lgkmcnt(0)
	s_barrier
	s_setprio 1
	v_mfma_f32_16x16x32_bf16 v[126:129], v[146:149], v[184:187], v[126:129]
	v_mfma_f32_16x16x32_bf16 v[122:125], v[160:163], v[184:187], v[122:125]
	v_mfma_f32_16x16x32_bf16 v[110:113], v[146:149], v[196:199], v[110:113]
	v_mfma_f32_16x16x32_bf16 v[106:109], v[160:163], v[196:199], v[106:109]
	v_mfma_f32_16x16x32_bf16 v[98:101], v[146:149], v[206:209], v[98:101]
	v_mfma_f32_16x16x32_bf16 v[90:93], v[160:163], v[206:209], v[90:93]
	v_mfma_f32_16x16x32_bf16 v[78:81], v[146:149], v[214:217], v[78:81]
	v_mfma_f32_16x16x32_bf16 v[74:77], v[160:163], v[214:217], v[74:77]
	v_mfma_f32_16x16x32_bf16 v[126:129], v[156:159], v[188:191], v[126:129]
	v_mfma_f32_16x16x32_bf16 v[122:125], v[164:167], v[188:191], v[122:125]
	v_mfma_f32_16x16x32_bf16 v[110:113], v[156:159], v[200:203], v[110:113]
	v_mfma_f32_16x16x32_bf16 v[106:109], v[164:167], v[200:203], v[106:109]
	v_mfma_f32_16x16x32_bf16 v[98:101], v[156:159], v[210:213], v[98:101]
	v_mfma_f32_16x16x32_bf16 v[90:93], v[164:167], v[210:213], v[90:93]
	v_mfma_f32_16x16x32_bf16 v[78:81], v[156:159], v[218:221], v[78:81]
	v_mfma_f32_16x16x32_bf16 v[74:77], v[164:167], v[218:221], v[74:77]
	v_mfma_f32_16x16x32_bf16 v[118:121], v[168:171], v[184:187], v[118:121]
	v_mfma_f32_16x16x32_bf16 v[114:117], v[176:179], v[184:187], v[114:117]
	v_mfma_f32_16x16x32_bf16 v[102:105], v[168:171], v[196:199], v[102:105]
	v_mfma_f32_16x16x32_bf16 v[94:97], v[176:179], v[196:199], v[94:97]
	v_mfma_f32_16x16x32_bf16 v[86:89], v[168:171], v[206:209], v[86:89]
	v_mfma_f32_16x16x32_bf16 v[82:85], v[176:179], v[206:209], v[82:85]
	v_mfma_f32_16x16x32_bf16 v[70:73], v[168:171], v[214:217], v[70:73]
	v_mfma_f32_16x16x32_bf16 v[66:69], v[176:179], v[214:217], v[66:69]
	v_mfma_f32_16x16x32_bf16 v[118:121], v[172:175], v[188:191], v[118:121]
	v_mfma_f32_16x16x32_bf16 v[114:117], v[180:183], v[188:191], v[114:117]
	v_mfma_f32_16x16x32_bf16 v[102:105], v[172:175], v[200:203], v[102:105]
	v_mfma_f32_16x16x32_bf16 v[94:97], v[180:183], v[200:203], v[94:97]
	v_mfma_f32_16x16x32_bf16 v[86:89], v[172:175], v[210:213], v[86:89]
	v_mfma_f32_16x16x32_bf16 v[82:85], v[180:183], v[210:213], v[82:85]
	v_mfma_f32_16x16x32_bf16 v[70:73], v[172:175], v[218:221], v[70:73]
	v_mfma_f32_16x16x32_bf16 v[66:69], v[180:183], v[218:221], v[66:69]
	s_setprio 0
	s_barrier
	s_add_i32 s34, s58, s40
	v_lshl_add_u64 v[192:193], v[192:193], 0, s[14:15]
	s_mov_b32 m0, s34
	ds_read_b128 v[184:187], v154 offset:49152
	ds_read_b128 v[188:191], v154 offset:50176
	ds_read_b128 v[196:199], v154 offset:51200
	ds_read_b128 v[200:203], v154 offset:52224
	ds_read_b128 v[206:209], v154 offset:53248
	ds_read_b128 v[210:213], v154 offset:54272
	ds_read_b128 v[214:217], v154 offset:55296
	ds_read_b128 v[218:221], v154 offset:56320
	global_load_lds_dwordx4 v[192:193], off
	s_add_i32 m0, s34, 0x2000
	s_add_u32 s30, s30, 0x80080
	v_lshl_add_u64 v[192:193], v[222:223], 0, s[14:15]
	s_addc_u32 s31, s31, 0
	s_add_i32 s34, s59, s40
	global_load_lds_dwordx4 v[192:193], off
	v_lshl_add_u64 v[192:193], s[30:31], 0, v[134:135]
	s_mov_b32 m0, s34
	s_nop 0
	global_load_lds_dwordx4 v[192:193], off
	v_lshl_add_u64 v[192:193], s[30:31], 0, v[130:131]
	s_add_i32 m0, s34, 0x2000
	s_nop 0
	global_load_lds_dwordx4 v[192:193], off
	v_lshl_add_u64 v[192:193], v[224:225], 0, s[14:15]
	s_mov_b32 m0, s47
	s_nop 0
	global_load_lds_dwordx4 v[192:193], off
	v_lshl_add_u64 v[192:193], v[226:227], 0, s[14:15]
	s_mov_b32 m0, s48
	s_nop 0
	global_load_lds_dwordx4 v[192:193], off
	s_nop 0
	s_waitcnt vmcnt(8)
	s_waitcnt lgkmcnt(0)
	s_barrier
	s_setprio 1
	v_mfma_f32_16x16x32_bf16 v[62:65], v[146:149], v[184:187], v[62:65]
	v_mfma_f32_16x16x32_bf16 v[58:61], v[160:163], v[184:187], v[58:61]
	v_mfma_f32_16x16x32_bf16 v[46:49], v[146:149], v[196:199], v[46:49]
	v_mfma_f32_16x16x32_bf16 v[42:45], v[160:163], v[196:199], v[42:45]
	v_mfma_f32_16x16x32_bf16 v[30:33], v[146:149], v[206:209], v[30:33]
	v_mfma_f32_16x16x32_bf16 v[26:29], v[160:163], v[206:209], v[26:29]
	v_mfma_f32_16x16x32_bf16 v[14:17], v[146:149], v[214:217], v[14:17]
	v_mfma_f32_16x16x32_bf16 v[10:13], v[160:163], v[214:217], v[10:13]
	v_mfma_f32_16x16x32_bf16 v[62:65], v[156:159], v[188:191], v[62:65]
	v_mfma_f32_16x16x32_bf16 v[58:61], v[164:167], v[188:191], v[58:61]
	v_mfma_f32_16x16x32_bf16 v[46:49], v[156:159], v[200:203], v[46:49]
	v_mfma_f32_16x16x32_bf16 v[42:45], v[164:167], v[200:203], v[42:45]
	v_mfma_f32_16x16x32_bf16 v[30:33], v[156:159], v[210:213], v[30:33]
	v_mfma_f32_16x16x32_bf16 v[26:29], v[164:167], v[210:213], v[26:29]
	v_mfma_f32_16x16x32_bf16 v[14:17], v[156:159], v[218:221], v[14:17]
	v_mfma_f32_16x16x32_bf16 v[10:13], v[164:167], v[218:221], v[10:13]
	v_mfma_f32_16x16x32_bf16 v[54:57], v[168:171], v[184:187], v[54:57]
	v_mfma_f32_16x16x32_bf16 v[50:53], v[176:179], v[184:187], v[50:53]
	v_mfma_f32_16x16x32_bf16 v[38:41], v[168:171], v[196:199], v[38:41]
	v_mfma_f32_16x16x32_bf16 v[34:37], v[176:179], v[196:199], v[34:37]
	v_mfma_f32_16x16x32_bf16 v[22:25], v[168:171], v[206:209], v[22:25]
	v_mfma_f32_16x16x32_bf16 v[18:21], v[176:179], v[206:209], v[18:21]
	v_mfma_f32_16x16x32_bf16 v[6:9], v[168:171], v[214:217], v[6:9]
	v_mfma_f32_16x16x32_bf16 v[2:5], v[176:179], v[214:217], v[2:5]
	v_mfma_f32_16x16x32_bf16 v[54:57], v[172:175], v[188:191], v[54:57]
	v_mfma_f32_16x16x32_bf16 v[50:53], v[180:183], v[188:191], v[50:53]
	v_mfma_f32_16x16x32_bf16 v[38:41], v[172:175], v[200:203], v[38:41]
	v_mfma_f32_16x16x32_bf16 v[34:37], v[180:183], v[200:203], v[34:37]
	v_mfma_f32_16x16x32_bf16 v[22:25], v[172:175], v[210:213], v[22:25]
	v_mfma_f32_16x16x32_bf16 v[18:21], v[180:183], v[210:213], v[18:21]
	v_mfma_f32_16x16x32_bf16 v[6:9], v[172:175], v[218:221], v[6:9]
	v_mfma_f32_16x16x32_bf16 v[2:5], v[180:183], v[218:221], v[2:5]
	s_setprio 0
	s_barrier
	s_add_i32 s57, s57, 2
	s_add_u32 s28, s28, 0x100
	s_addc_u32 s29, s29, 0
	s_add_u32 s55, s55, 0x100
	s_addc_u32 s56, s56, 0
	s_cmp_gt_u32 s57, 29
	s_cbranch_scc0 .LBB0_967
	s_and_b64 vcc, exec, s[16:17]
	s_cbranch_vccz .LBB0_970
	s_barrier

.LBB0_1057:
	s_add_i32 s84, s48, 2
	s_add_u32 s49, s62, 0xfff00080
	s_addc_u32 s64, s63, -1
	s_cmp_eq_u32 s51, s48
	s_cselect_b32 s48, s56, s53
	s_cselect_b32 s65, s9, s64
	s_cselect_b32 s64, s8, s49
	s_cselect_b32 s49, s57, s55
	v_lshl_add_u64 v[154:155], s[62:63], 0, v[138:139]
	s_add_i32 m0, s59, 0xc000
	s_nop 0
	global_load_lds_dwordx4 v[154:155], off
	v_lshl_add_u64 v[154:155], s[62:63], 0, v[140:141]
	s_add_i32 m0, s59, 0xe000
	s_nop 0
	global_load_lds_dwordx4 v[154:155], off
	ds_read_b128 v[150:153], v158
	ds_read_b128 v[162:165], v158 offset:1024
	ds_read_b128 v[166:169], v158 offset:2048
	ds_read_b128 v[170:173], v158 offset:3072
	ds_read_b128 v[174:177], v159
	ds_read_b128 v[178:181], v159 offset:1024
	ds_read_b128 v[182:185], v159 offset:2048
	ds_read_b128 v[186:189], v159 offset:3072
	ds_read_b128 v[190:193], v160
	ds_read_b128 v[196:199], v160 offset:1024
	ds_read_b128 v[200:203], v160 offset:2048
	ds_read_b128 v[206:209], v160 offset:3072
	ds_read_b128 v[210:213], v160 offset:4096
	ds_read_b128 v[214:217], v160 offset:5120
	ds_read_b128 v[218:221], v160 offset:6144
	ds_read_b128 v[222:225], v160 offset:7168
	s_waitcnt vmcnt(8)
	s_waitcnt lgkmcnt(0)
	s_barrier
	s_setprio 1
	v_mfma_f32_16x16x32_bf16 v[126:129], v[150:153], v[190:193], v[126:129]
	v_mfma_f32_16x16x32_bf16 v[122:125], v[166:169], v[190:193], v[122:125]
	v_mfma_f32_16x16x32_bf16 v[110:113], v[150:153], v[200:203], v[110:113]
	v_mfma_f32_16x16x32_bf16 v[106:109], v[166:169], v[200:203], v[106:109]
	v_mfma_f32_16x16x32_bf16 v[94:97], v[150:153], v[210:213], v[94:97]
	v_mfma_f32_16x16x32_bf16 v[90:93], v[166:169], v[210:213], v[90:93]
	v_mfma_f32_16x16x32_bf16 v[78:81], v[150:153], v[218:221], v[78:81]
	v_mfma_f32_16x16x32_bf16 v[74:77], v[166:169], v[218:221], v[74:77]
	v_mfma_f32_16x16x32_bf16 v[126:129], v[162:165], v[196:199], v[126:129]
	v_mfma_f32_16x16x32_bf16 v[122:125], v[170:173], v[196:199], v[122:125]
	v_mfma_f32_16x16x32_bf16 v[110:113], v[162:165], v[206:209], v[110:113]
	v_mfma_f32_16x16x32_bf16 v[106:109], v[170:173], v[206:209], v[106:109]
	v_mfma_f32_16x16x32_bf16 v[94:97], v[162:165], v[214:217], v[94:97]
	v_mfma_f32_16x16x32_bf16 v[90:93], v[170:173], v[214:217], v[90:93]
	v_mfma_f32_16x16x32_bf16 v[78:81], v[162:165], v[222:225], v[78:81]
	v_mfma_f32_16x16x32_bf16 v[74:77], v[170:173], v[222:225], v[74:77]
	v_mfma_f32_16x16x32_bf16 v[118:121], v[174:177], v[190:193], v[118:121]
	v_mfma_f32_16x16x32_bf16 v[114:117], v[182:185], v[190:193], v[114:117]
	v_mfma_f32_16x16x32_bf16 v[102:105], v[174:177], v[200:203], v[102:105]
	v_mfma_f32_16x16x32_bf16 v[98:101], v[182:185], v[200:203], v[98:101]
	v_mfma_f32_16x16x32_bf16 v[86:89], v[174:177], v[210:213], v[86:89]
	v_mfma_f32_16x16x32_bf16 v[82:85], v[182:185], v[210:213], v[82:85]
	v_mfma_f32_16x16x32_bf16 v[70:73], v[174:177], v[218:221], v[70:73]
	v_mfma_f32_16x16x32_bf16 v[66:69], v[182:185], v[218:221], v[66:69]
	v_mfma_f32_16x16x32_bf16 v[118:121], v[178:181], v[196:199], v[118:121]
	v_mfma_f32_16x16x32_bf16 v[114:117], v[186:189], v[196:199], v[114:117]
	v_mfma_f32_16x16x32_bf16 v[102:105], v[178:181], v[206:209], v[102:105]
	v_mfma_f32_16x16x32_bf16 v[98:101], v[186:189], v[206:209], v[98:101]
	v_mfma_f32_16x16x32_bf16 v[86:89], v[178:181], v[214:217], v[86:89]
	v_mfma_f32_16x16x32_bf16 v[82:85], v[186:189], v[214:217], v[82:85]
	v_mfma_f32_16x16x32_bf16 v[70:73], v[178:181], v[222:225], v[70:73]
	v_mfma_f32_16x16x32_bf16 v[66:69], v[186:189], v[222:225], v[66:69]
	s_setprio 0
	s_barrier
	s_add_i32 s85, s75, s66
	v_lshl_add_u64 v[154:155], s[48:49], 0, v[132:133]
	s_mov_b32 m0, s85
	ds_read_b128 v[190:193], v160 offset:16384
	ds_read_b128 v[196:199], v160 offset:17408
	ds_read_b128 v[200:203], v160 offset:18432
	ds_read_b128 v[206:209], v160 offset:19456
	ds_read_b128 v[210:213], v160 offset:20480
	ds_read_b128 v[214:217], v160 offset:21504
	ds_read_b128 v[218:221], v160 offset:22528
	ds_read_b128 v[222:225], v160 offset:23552
	global_load_lds_dwordx4 v[154:155], off
	s_add_i32 m0, s85, 0x2000
	s_add_u32 s86, s48, 0x100000
	v_lshl_add_u64 v[226:227], s[48:49], 0, v[136:137]
	s_addc_u32 s87, s49, 0
	s_add_i32 s85, s76, s66
	global_load_lds_dwordx4 v[226:227], off
	v_lshl_add_u64 v[228:229], s[86:87], 0, v[132:133]
	s_mov_b32 m0, s85
	v_lshl_add_u64 v[230:231], s[64:65], 0, v[134:135]
	global_load_lds_dwordx4 v[228:229], off
	v_lshl_add_u64 v[228:229], s[86:87], 0, v[136:137]
	s_add_i32 m0, s85, 0x2000
	s_nop 0
	global_load_lds_dwordx4 v[228:229], off
	v_lshl_add_u64 v[228:229], s[64:65], 0, v[130:131]
	s_mov_b32 m0, s59
	s_nop 0
	global_load_lds_dwordx4 v[228:229], off
	s_mov_b32 m0, s61
	s_nop 0
	global_load_lds_dwordx4 v[230:231], off
	s_waitcnt vmcnt(8)
	s_waitcnt lgkmcnt(0)
	s_barrier
	s_setprio 1
	v_mfma_f32_16x16x32_bf16 v[62:65], v[150:153], v[190:193], v[62:65]
	v_mfma_f32_16x16x32_bf16 v[58:61], v[166:169], v[190:193], v[58:61]
	v_mfma_f32_16x16x32_bf16 v[46:49], v[150:153], v[200:203], v[46:49]
	v_mfma_f32_16x16x32_bf16 v[42:45], v[166:169], v[200:203], v[42:45]
	v_mfma_f32_16x16x32_bf16 v[30:33], v[150:153], v[210:213], v[30:33]
	v_mfma_f32_16x16x32_bf16 v[26:29], v[166:169], v[210:213], v[26:29]
	v_mfma_f32_16x16x32_bf16 v[14:17], v[150:153], v[218:221], v[14:17]
	v_mfma_f32_16x16x32_bf16 v[10:13], v[166:169], v[218:221], v[10:13]
	v_mfma_f32_16x16x32_bf16 v[62:65], v[162:165], v[196:199], v[62:65]
	v_mfma_f32_16x16x32_bf16 v[58:61], v[170:173], v[196:199], v[58:61]
	v_mfma_f32_16x16x32_bf16 v[46:49], v[162:165], v[206:209], v[46:49]
	v_mfma_f32_16x16x32_bf16 v[42:45], v[170:173], v[206:209], v[42:45]
	v_mfma_f32_16x16x32_bf16 v[30:33], v[162:165], v[214:217], v[30:33]
	v_mfma_f32_16x16x32_bf16 v[26:29], v[170:173], v[214:217], v[26:29]
	v_mfma_f32_16x16x32_bf16 v[14:17], v[162:165], v[222:225], v[14:17]
	v_mfma_f32_16x16x32_bf16 v[10:13], v[170:173], v[222:225], v[10:13]
	v_mfma_f32_16x16x32_bf16 v[54:57], v[174:177], v[190:193], v[54:57]
	v_mfma_f32_16x16x32_bf16 v[50:53], v[182:185], v[190:193], v[50:53]
	v_mfma_f32_16x16x32_bf16 v[38:41], v[174:177], v[200:203], v[38:41]
	v_mfma_f32_16x16x32_bf16 v[34:37], v[182:185], v[200:203], v[34:37]
	v_mfma_f32_16x16x32_bf16 v[22:25], v[174:177], v[210:213], v[22:25]
	v_mfma_f32_16x16x32_bf16 v[18:21], v[182:185], v[210:213], v[18:21]
	v_mfma_f32_16x16x32_bf16 v[6:9], v[174:177], v[218:221], v[6:9]
	v_mfma_f32_16x16x32_bf16 v[2:5], v[182:185], v[218:221], v[2:5]
	v_mfma_f32_16x16x32_bf16 v[54:57], v[178:181], v[196:199], v[54:57]
	v_mfma_f32_16x16x32_bf16 v[50:53], v[186:189], v[196:199], v[50:53]
	v_mfma_f32_16x16x32_bf16 v[38:41], v[178:181], v[206:209], v[38:41]
	v_mfma_f32_16x16x32_bf16 v[34:37], v[186:189], v[206:209], v[34:37]
	v_mfma_f32_16x16x32_bf16 v[22:25], v[178:181], v[214:217], v[22:25]
	v_mfma_f32_16x16x32_bf16 v[18:21], v[186:189], v[214:217], v[18:21]
	v_mfma_f32_16x16x32_bf16 v[6:9], v[178:181], v[222:225], v[6:9]
	v_mfma_f32_16x16x32_bf16 v[2:5], v[186:189], v[222:225], v[2:5]
	s_setprio 0
	s_barrier
	s_add_u32 s64, s64, 0x100000
	s_addc_u32 s65, s65, 0
	s_mov_b32 m0, s67
	v_lshl_add_u64 v[232:233], s[64:65], 0, v[130:131]
	global_load_lds_dwordx4 v[232:233], off
	v_lshl_add_u64 v[232:233], s[64:65], 0, v[134:135]
	s_mov_b32 m0, s68
	s_nop 0
	global_load_lds_dwordx4 v[232:233], off
	s_add_i32 s85, 0, 0x18000
	v_add_u32_e32 v161, s85, v156
	s_add_i32 s86, 0, 0x1c000
	ds_read_b128 v[150:153], v161
	ds_read_b128 v[162:165], v161 offset:1024
	ds_read_b128 v[166:169], v161 offset:2048
	ds_read_b128 v[170:173], v161 offset:3072
	v_add_u32_e32 v161, s86, v156
	ds_read_b128 v[174:177], v161
	ds_read_b128 v[178:181], v161 offset:1024
	ds_read_b128 v[182:185], v161 offset:2048
	ds_read_b128 v[186:189], v161 offset:3072
	ds_read_b128 v[190:193], v160 offset:32768
	ds_read_b128 v[196:199], v160 offset:33792
	ds_read_b128 v[200:203], v160 offset:34816
	ds_read_b128 v[206:209], v160 offset:35840
	ds_read_b128 v[210:213], v160 offset:36864
	ds_read_b128 v[214:217], v160 offset:37888
	ds_read_b128 v[218:221], v160 offset:38912
	ds_read_b128 v[222:225], v160 offset:39936
	s_waitcnt vmcnt(8)
	s_waitcnt lgkmcnt(0)
	s_barrier
	s_setprio 1
	v_mfma_f32_16x16x32_bf16 v[126:129], v[150:153], v[190:193], v[126:129]
	v_mfma_f32_16x16x32_bf16 v[122:125], v[166:169], v[190:193], v[122:125]
	v_mfma_f32_16x16x32_bf16 v[110:113], v[150:153], v[200:203], v[110:113]
	v_mfma_f32_16x16x32_bf16 v[106:109], v[166:169], v[200:203], v[106:109]
	v_mfma_f32_16x16x32_bf16 v[94:97], v[150:153], v[210:213], v[94:97]
	v_mfma_f32_16x16x32_bf16 v[90:93], v[166:169], v[210:213], v[90:93]
	v_mfma_f32_16x16x32_bf16 v[78:81], v[150:153], v[218:221], v[78:81]
	v_mfma_f32_16x16x32_bf16 v[74:77], v[166:169], v[218:221], v[74:77]
	v_mfma_f32_16x16x32_bf16 v[126:129], v[162:165], v[196:199], v[126:129]
	v_mfma_f32_16x16x32_bf16 v[122:125], v[170:173], v[196:199], v[122:125]
	v_mfma_f32_16x16x32_bf16 v[110:113], v[162:165], v[206:209], v[110:113]
	v_mfma_f32_16x16x32_bf16 v[106:109], v[170:173], v[206:209], v[106:109]
	v_mfma_f32_16x16x32_bf16 v[94:97], v[162:165], v[214:217], v[94:97]
	v_mfma_f32_16x16x32_bf16 v[90:93], v[170:173], v[214:217], v[90:93]
	v_mfma_f32_16x16x32_bf16 v[78:81], v[162:165], v[222:225], v[78:81]
	v_mfma_f32_16x16x32_bf16 v[74:77], v[170:173], v[222:225], v[74:77]
	v_mfma_f32_16x16x32_bf16 v[118:121], v[174:177], v[190:193], v[118:121]
	v_mfma_f32_16x16x32_bf16 v[114:117], v[182:185], v[190:193], v[114:117]
	v_mfma_f32_16x16x32_bf16 v[102:105], v[174:177], v[200:203], v[102:105]
	v_mfma_f32_16x16x32_bf16 v[98:101], v[182:185], v[200:203], v[98:101]
	v_mfma_f32_16x16x32_bf16 v[86:89], v[174:177], v[210:213], v[86:89]
	v_mfma_f32_16x16x32_bf16 v[82:85], v[182:185], v[210:213], v[82:85]
	v_mfma_f32_16x16x32_bf16 v[70:73], v[174:177], v[218:221], v[70:73]
	v_mfma_f32_16x16x32_bf16 v[66:69], v[182:185], v[218:221], v[66:69]
	v_mfma_f32_16x16x32_bf16 v[118:121], v[178:181], v[196:199], v[118:121]
	v_mfma_f32_16x16x32_bf16 v[114:117], v[186:189], v[196:199], v[114:117]
	v_mfma_f32_16x16x32_bf16 v[102:105], v[178:181], v[206:209], v[102:105]
	v_mfma_f32_16x16x32_bf16 v[98:101], v[186:189], v[206:209], v[98:101]
	v_mfma_f32_16x16x32_bf16 v[86:89], v[178:181], v[214:217], v[86:89]
	v_mfma_f32_16x16x32_bf16 v[82:85], v[186:189], v[214:217], v[82:85]
	v_mfma_f32_16x16x32_bf16 v[70:73], v[178:181], v[222:225], v[70:73]
	v_mfma_f32_16x16x32_bf16 v[66:69], v[186:189], v[222:225], v[66:69]
	s_setprio 0
	s_barrier
	s_add_i32 s64, s85, s66
	v_lshl_add_u64 v[154:155], v[154:155], 0, s[20:21]
	s_mov_b32 m0, s64
	ds_read_b128 v[190:193], v160 offset:49152
	ds_read_b128 v[196:199], v160 offset:50176
	ds_read_b128 v[200:203], v160 offset:51200
	ds_read_b128 v[206:209], v160 offset:52224
	ds_read_b128 v[210:213], v160 offset:53248
	ds_read_b128 v[214:217], v160 offset:54272
	ds_read_b128 v[218:221], v160 offset:55296
	ds_read_b128 v[222:225], v160 offset:56320
	global_load_lds_dwordx4 v[154:155], off
	s_add_i32 m0, s64, 0x2000
	s_add_u32 s48, s48, 0x100080
	v_lshl_add_u64 v[154:155], v[226:227], 0, s[20:21]
	s_addc_u32 s49, s49, 0
	s_add_i32 s64, s86, s66
	global_load_lds_dwordx4 v[154:155], off
	v_lshl_add_u64 v[154:155], s[48:49], 0, v[132:133]
	s_mov_b32 m0, s64
	s_nop 0
	global_load_lds_dwordx4 v[154:155], off
	v_lshl_add_u64 v[154:155], s[48:49], 0, v[136:137]
	s_add_i32 m0, s64, 0x2000
	s_nop 0
	global_load_lds_dwordx4 v[154:155], off
	v_lshl_add_u64 v[154:155], v[228:229], 0, s[20:21]
	s_mov_b32 m0, s72
	s_nop 0
	global_load_lds_dwordx4 v[154:155], off
	v_lshl_add_u64 v[154:155], v[230:231], 0, s[20:21]
	s_mov_b32 m0, s73
	s_nop 0
	global_load_lds_dwordx4 v[154:155], off
	s_nop 0
	s_waitcnt vmcnt(8)
	s_waitcnt lgkmcnt(0)
	s_barrier
	s_setprio 1
	v_mfma_f32_16x16x32_bf16 v[62:65], v[150:153], v[190:193], v[62:65]
	v_mfma_f32_16x16x32_bf16 v[58:61], v[166:169], v[190:193], v[58:61]
	v_mfma_f32_16x16x32_bf16 v[46:49], v[150:153], v[200:203], v[46:49]
	v_mfma_f32_16x16x32_bf16 v[42:45], v[166:169], v[200:203], v[42:45]
	v_mfma_f32_16x16x32_bf16 v[30:33], v[150:153], v[210:213], v[30:33]
	v_mfma_f32_16x16x32_bf16 v[26:29], v[166:169], v[210:213], v[26:29]
	v_mfma_f32_16x16x32_bf16 v[14:17], v[150:153], v[218:221], v[14:17]
	v_mfma_f32_16x16x32_bf16 v[10:13], v[166:169], v[218:221], v[10:13]
	v_mfma_f32_16x16x32_bf16 v[62:65], v[162:165], v[196:199], v[62:65]
	v_mfma_f32_16x16x32_bf16 v[58:61], v[170:173], v[196:199], v[58:61]
	v_mfma_f32_16x16x32_bf16 v[46:49], v[162:165], v[206:209], v[46:49]
	v_mfma_f32_16x16x32_bf16 v[42:45], v[170:173], v[206:209], v[42:45]
	v_mfma_f32_16x16x32_bf16 v[30:33], v[162:165], v[214:217], v[30:33]
	v_mfma_f32_16x16x32_bf16 v[26:29], v[170:173], v[214:217], v[26:29]
	v_mfma_f32_16x16x32_bf16 v[14:17], v[162:165], v[222:225], v[14:17]
	v_mfma_f32_16x16x32_bf16 v[10:13], v[170:173], v[222:225], v[10:13]
	v_mfma_f32_16x16x32_bf16 v[54:57], v[174:177], v[190:193], v[54:57]
	v_mfma_f32_16x16x32_bf16 v[50:53], v[182:185], v[190:193], v[50:53]
	v_mfma_f32_16x16x32_bf16 v[38:41], v[174:177], v[200:203], v[38:41]
	v_mfma_f32_16x16x32_bf16 v[34:37], v[182:185], v[200:203], v[34:37]
	v_mfma_f32_16x16x32_bf16 v[22:25], v[174:177], v[210:213], v[22:25]
	v_mfma_f32_16x16x32_bf16 v[18:21], v[182:185], v[210:213], v[18:21]
	v_mfma_f32_16x16x32_bf16 v[6:9], v[174:177], v[218:221], v[6:9]
	v_mfma_f32_16x16x32_bf16 v[2:5], v[182:185], v[218:221], v[2:5]
	v_mfma_f32_16x16x32_bf16 v[54:57], v[178:181], v[196:199], v[54:57]
	v_mfma_f32_16x16x32_bf16 v[50:53], v[186:189], v[196:199], v[50:53]
	v_mfma_f32_16x16x32_bf16 v[38:41], v[178:181], v[206:209], v[38:41]
	v_mfma_f32_16x16x32_bf16 v[34:37], v[186:189], v[206:209], v[34:37]
	v_mfma_f32_16x16x32_bf16 v[22:25], v[178:181], v[214:217], v[22:25]
	v_mfma_f32_16x16x32_bf16 v[18:21], v[186:189], v[214:217], v[18:21]
	v_mfma_f32_16x16x32_bf16 v[6:9], v[178:181], v[222:225], v[6:9]
	v_mfma_f32_16x16x32_bf16 v[2:5], v[186:189], v[222:225], v[2:5]
	s_setprio 0
	s_barrier
	s_add_u32 s62, s62, 0x100
	s_addc_u32 s63, s63, 0
	s_add_u32 s53, s53, 0x100
	s_addc_u32 s55, s55, 0
	s_cmp_ge_i32 s84, s83
	s_mov_b32 s48, s84
	s_cbranch_scc0 .LBB0_1057
	s_and_b64 vcc, exec, s[22:23]
	s_cbranch_vccz .LBB0_1060
	s_barrier

.LBB0_1197:
	s_add_i32 s65, s34, 2
	s_add_u32 s35, s30, 0xfff00080
	s_addc_u32 s40, s31, -1
	s_cmp_eq_u32 s62, s34
	s_cselect_b32 s34, s61, s63
	s_cselect_b32 s41, s21, s40
	s_cselect_b32 s40, s25, s35
	s_cselect_b32 s35, s23, s64
	v_lshl_add_u64 v[158:159], s[30:31], 0, v[148:149]
	s_add_i32 m0, s8, 0xc000
	s_nop 0
	global_load_lds_dwordx4 v[158:159], off
	v_lshl_add_u64 v[158:159], s[30:31], 0, v[150:151]
	s_add_i32 m0, s8, 0xe000
	s_nop 0
	global_load_lds_dwordx4 v[158:159], off
	ds_read_b128 v[162:165], v141
	ds_read_b128 v[166:169], v141 offset:1024
	ds_read_b128 v[170:173], v141 offset:2048
	ds_read_b128 v[174:177], v141 offset:3072
	ds_read_b128 v[178:181], v145
	ds_read_b128 v[182:185], v145 offset:1024
	ds_read_b128 v[186:189], v145 offset:2048
	ds_read_b128 v[190:193], v145 offset:3072
	ds_read_b128 v[196:199], v160
	ds_read_b128 v[200:203], v160 offset:1024
	ds_read_b128 v[206:209], v160 offset:2048
	ds_read_b128 v[210:213], v160 offset:3072
	ds_read_b128 v[214:217], v160 offset:4096
	ds_read_b128 v[218:221], v160 offset:5120
	ds_read_b128 v[222:225], v160 offset:6144
	ds_read_b128 v[226:229], v160 offset:7168
	s_waitcnt vmcnt(8)
	s_waitcnt lgkmcnt(0)
	s_barrier
	s_setprio 1
	v_mfma_f32_16x16x32_bf16 v[126:129], v[162:165], v[196:199], v[126:129]
	v_mfma_f32_16x16x32_bf16 v[122:125], v[170:173], v[196:199], v[122:125]
	v_mfma_f32_16x16x32_bf16 v[118:121], v[162:165], v[206:209], v[118:121]
	v_mfma_f32_16x16x32_bf16 v[114:117], v[170:173], v[206:209], v[114:117]
	v_mfma_f32_16x16x32_bf16 v[102:105], v[162:165], v[214:217], v[102:105]
	v_mfma_f32_16x16x32_bf16 v[98:101], v[170:173], v[214:217], v[98:101]
	v_mfma_f32_16x16x32_bf16 v[42:45], v[162:165], v[222:225], v[42:45]
	v_mfma_f32_16x16x32_bf16 v[34:37], v[170:173], v[222:225], v[34:37]
	v_mfma_f32_16x16x32_bf16 v[126:129], v[166:169], v[200:203], v[126:129]
	v_mfma_f32_16x16x32_bf16 v[122:125], v[174:177], v[200:203], v[122:125]
	v_mfma_f32_16x16x32_bf16 v[118:121], v[166:169], v[210:213], v[118:121]
	v_mfma_f32_16x16x32_bf16 v[114:117], v[174:177], v[210:213], v[114:117]
	v_mfma_f32_16x16x32_bf16 v[102:105], v[166:169], v[218:221], v[102:105]
	v_mfma_f32_16x16x32_bf16 v[98:101], v[174:177], v[218:221], v[98:101]
	v_mfma_f32_16x16x32_bf16 v[42:45], v[166:169], v[226:229], v[42:45]
	v_mfma_f32_16x16x32_bf16 v[34:37], v[174:177], v[226:229], v[34:37]
	v_mfma_f32_16x16x32_bf16 v[110:113], v[178:181], v[196:199], v[110:113]
	v_mfma_f32_16x16x32_bf16 v[106:109], v[186:189], v[196:199], v[106:109]
	v_mfma_f32_16x16x32_bf16 v[94:97], v[178:181], v[206:209], v[94:97]
	v_mfma_f32_16x16x32_bf16 v[90:93], v[186:189], v[206:209], v[90:93]
	v_mfma_f32_16x16x32_bf16 v[86:89], v[178:181], v[214:217], v[86:89]
	v_mfma_f32_16x16x32_bf16 v[82:85], v[186:189], v[214:217], v[82:85]
	v_mfma_f32_16x16x32_bf16 v[30:33], v[178:181], v[222:225], v[30:33]
	v_mfma_f32_16x16x32_bf16 v[26:29], v[186:189], v[222:225], v[26:29]
	v_mfma_f32_16x16x32_bf16 v[110:113], v[182:185], v[200:203], v[110:113]
	v_mfma_f32_16x16x32_bf16 v[106:109], v[190:193], v[200:203], v[106:109]
	v_mfma_f32_16x16x32_bf16 v[94:97], v[182:185], v[210:213], v[94:97]
	v_mfma_f32_16x16x32_bf16 v[90:93], v[190:193], v[210:213], v[90:93]
	v_mfma_f32_16x16x32_bf16 v[86:89], v[182:185], v[218:221], v[86:89]
	v_mfma_f32_16x16x32_bf16 v[82:85], v[190:193], v[218:221], v[82:85]
	v_mfma_f32_16x16x32_bf16 v[30:33], v[182:185], v[226:229], v[30:33]
	v_mfma_f32_16x16x32_bf16 v[26:29], v[190:193], v[226:229], v[26:29]
	s_setprio 0
	s_barrier
	s_add_i32 s66, s56, s42
	v_lshl_add_u64 v[158:159], s[34:35], 0, v[134:135]
	s_mov_b32 m0, s66
	ds_read_b128 v[196:199], v160 offset:16384
	ds_read_b128 v[200:203], v160 offset:17408
	ds_read_b128 v[206:209], v160 offset:18432
	ds_read_b128 v[210:213], v160 offset:19456
	ds_read_b128 v[214:217], v160 offset:20480
	ds_read_b128 v[218:221], v160 offset:21504
	ds_read_b128 v[222:225], v160 offset:22528
	ds_read_b128 v[226:229], v160 offset:23552
	global_load_lds_dwordx4 v[158:159], off
	s_add_i32 m0, s66, 0x2000
	s_add_u32 s66, s34, 0x100000
	v_lshl_add_u64 v[230:231], s[34:35], 0, v[132:133]
	s_addc_u32 s67, s35, 0
	s_add_i32 s68, s57, s42
	global_load_lds_dwordx4 v[230:231], off
	v_lshl_add_u64 v[232:233], s[66:67], 0, v[134:135]
	s_mov_b32 m0, s68
	v_lshl_add_u64 v[234:235], s[40:41], 0, v[132:133]
	global_load_lds_dwordx4 v[232:233], off
	v_lshl_add_u64 v[232:233], s[66:67], 0, v[132:133]
	s_add_i32 m0, s68, 0x2000
	s_nop 0
	global_load_lds_dwordx4 v[232:233], off
	v_lshl_add_u64 v[232:233], s[40:41], 0, v[134:135]
	s_mov_b32 m0, s8
	s_nop 0
	global_load_lds_dwordx4 v[232:233], off
	s_mov_b32 m0, s15
	s_nop 0
	global_load_lds_dwordx4 v[234:235], off
	s_waitcnt vmcnt(8)
	s_waitcnt lgkmcnt(0)
	s_barrier
	s_setprio 1
	v_mfma_f32_16x16x32_bf16 v[78:81], v[162:165], v[196:199], v[78:81]
	v_mfma_f32_16x16x32_bf16 v[74:77], v[170:173], v[196:199], v[74:77]
	v_mfma_f32_16x16x32_bf16 v[70:73], v[162:165], v[206:209], v[70:73]
	v_mfma_f32_16x16x32_bf16 v[66:69], v[170:173], v[206:209], v[66:69]
	v_mfma_f32_16x16x32_bf16 v[54:57], v[162:165], v[214:217], v[54:57]
	v_mfma_f32_16x16x32_bf16 v[50:53], v[170:173], v[214:217], v[50:53]
	v_mfma_f32_16x16x32_bf16 v[14:17], v[162:165], v[222:225], v[14:17]
	v_mfma_f32_16x16x32_bf16 v[10:13], v[170:173], v[222:225], v[10:13]
	v_mfma_f32_16x16x32_bf16 v[78:81], v[166:169], v[200:203], v[78:81]
	v_mfma_f32_16x16x32_bf16 v[74:77], v[174:177], v[200:203], v[74:77]
	v_mfma_f32_16x16x32_bf16 v[70:73], v[166:169], v[210:213], v[70:73]
	v_mfma_f32_16x16x32_bf16 v[66:69], v[174:177], v[210:213], v[66:69]
	v_mfma_f32_16x16x32_bf16 v[54:57], v[166:169], v[218:221], v[54:57]
	v_mfma_f32_16x16x32_bf16 v[50:53], v[174:177], v[218:221], v[50:53]
	v_mfma_f32_16x16x32_bf16 v[14:17], v[166:169], v[226:229], v[14:17]
	v_mfma_f32_16x16x32_bf16 v[10:13], v[174:177], v[226:229], v[10:13]
	v_mfma_f32_16x16x32_bf16 v[62:65], v[178:181], v[196:199], v[62:65]
	v_mfma_f32_16x16x32_bf16 v[58:61], v[186:189], v[196:199], v[58:61]
	v_mfma_f32_16x16x32_bf16 v[46:49], v[178:181], v[206:209], v[46:49]
	v_mfma_f32_16x16x32_bf16 v[38:41], v[186:189], v[206:209], v[38:41]
	v_mfma_f32_16x16x32_bf16 v[22:25], v[178:181], v[214:217], v[22:25]
	v_mfma_f32_16x16x32_bf16 v[18:21], v[186:189], v[214:217], v[18:21]
	v_mfma_f32_16x16x32_bf16 v[6:9], v[178:181], v[222:225], v[6:9]
	v_mfma_f32_16x16x32_bf16 v[2:5], v[186:189], v[222:225], v[2:5]
	v_mfma_f32_16x16x32_bf16 v[62:65], v[182:185], v[200:203], v[62:65]
	v_mfma_f32_16x16x32_bf16 v[58:61], v[190:193], v[200:203], v[58:61]
	v_mfma_f32_16x16x32_bf16 v[46:49], v[182:185], v[210:213], v[46:49]
	v_mfma_f32_16x16x32_bf16 v[38:41], v[190:193], v[210:213], v[38:41]
	v_mfma_f32_16x16x32_bf16 v[22:25], v[182:185], v[218:221], v[22:25]
	v_mfma_f32_16x16x32_bf16 v[18:21], v[190:193], v[218:221], v[18:21]
	v_mfma_f32_16x16x32_bf16 v[6:9], v[182:185], v[226:229], v[6:9]
	v_mfma_f32_16x16x32_bf16 v[2:5], v[190:193], v[226:229], v[2:5]
	s_setprio 0
	s_barrier
	s_add_u32 s40, s40, 0x100000
	s_addc_u32 s41, s41, 0
	s_mov_b32 m0, s46
	v_lshl_add_u64 v[236:237], s[40:41], 0, v[134:135]
	global_load_lds_dwordx4 v[236:237], off
	v_lshl_add_u64 v[236:237], s[40:41], 0, v[132:133]
	s_mov_b32 m0, s47
	s_nop 0
	global_load_lds_dwordx4 v[236:237], off
	s_add_i32 s66, 0, 0x18000
	v_add_u32_e32 v161, s66, v1
	s_add_i32 s67, 0, 0x1c000
	ds_read_b128 v[162:165], v161
	ds_read_b128 v[166:169], v161 offset:1024
	ds_read_b128 v[170:173], v161 offset:2048
	ds_read_b128 v[174:177], v161 offset:3072
	v_add_u32_e32 v161, s67, v1
	ds_read_b128 v[178:181], v161
	ds_read_b128 v[182:185], v161 offset:1024
	ds_read_b128 v[186:189], v161 offset:2048
	ds_read_b128 v[190:193], v161 offset:3072
	ds_read_b128 v[196:199], v160 offset:32768
	ds_read_b128 v[200:203], v160 offset:33792
	ds_read_b128 v[206:209], v160 offset:34816
	ds_read_b128 v[210:213], v160 offset:35840
	ds_read_b128 v[214:217], v160 offset:36864
	ds_read_b128 v[218:221], v160 offset:37888
	ds_read_b128 v[222:225], v160 offset:38912
	ds_read_b128 v[226:229], v160 offset:39936
	s_waitcnt vmcnt(8)
	s_waitcnt lgkmcnt(0)
	s_barrier
	s_setprio 1
	v_mfma_f32_16x16x32_bf16 v[126:129], v[162:165], v[196:199], v[126:129]
	v_mfma_f32_16x16x32_bf16 v[122:125], v[170:173], v[196:199], v[122:125]
	v_mfma_f32_16x16x32_bf16 v[118:121], v[162:165], v[206:209], v[118:121]
	v_mfma_f32_16x16x32_bf16 v[114:117], v[170:173], v[206:209], v[114:117]
	v_mfma_f32_16x16x32_bf16 v[102:105], v[162:165], v[214:217], v[102:105]
	v_mfma_f32_16x16x32_bf16 v[98:101], v[170:173], v[214:217], v[98:101]
	v_mfma_f32_16x16x32_bf16 v[42:45], v[162:165], v[222:225], v[42:45]
	v_mfma_f32_16x16x32_bf16 v[34:37], v[170:173], v[222:225], v[34:37]
	v_mfma_f32_16x16x32_bf16 v[126:129], v[166:169], v[200:203], v[126:129]
	v_mfma_f32_16x16x32_bf16 v[122:125], v[174:177], v[200:203], v[122:125]
	v_mfma_f32_16x16x32_bf16 v[118:121], v[166:169], v[210:213], v[118:121]
	v_mfma_f32_16x16x32_bf16 v[114:117], v[174:177], v[210:213], v[114:117]
	v_mfma_f32_16x16x32_bf16 v[102:105], v[166:169], v[218:221], v[102:105]
	v_mfma_f32_16x16x32_bf16 v[98:101], v[174:177], v[218:221], v[98:101]
	v_mfma_f32_16x16x32_bf16 v[42:45], v[166:169], v[226:229], v[42:45]
	v_mfma_f32_16x16x32_bf16 v[34:37], v[174:177], v[226:229], v[34:37]
	v_mfma_f32_16x16x32_bf16 v[110:113], v[178:181], v[196:199], v[110:113]
	v_mfma_f32_16x16x32_bf16 v[106:109], v[186:189], v[196:199], v[106:109]
	v_mfma_f32_16x16x32_bf16 v[94:97], v[178:181], v[206:209], v[94:97]
	v_mfma_f32_16x16x32_bf16 v[90:93], v[186:189], v[206:209], v[90:93]
	v_mfma_f32_16x16x32_bf16 v[86:89], v[178:181], v[214:217], v[86:89]
	v_mfma_f32_16x16x32_bf16 v[82:85], v[186:189], v[214:217], v[82:85]
	v_mfma_f32_16x16x32_bf16 v[30:33], v[178:181], v[222:225], v[30:33]
	v_mfma_f32_16x16x32_bf16 v[26:29], v[186:189], v[222:225], v[26:29]
	v_mfma_f32_16x16x32_bf16 v[110:113], v[182:185], v[200:203], v[110:113]
	v_mfma_f32_16x16x32_bf16 v[106:109], v[190:193], v[200:203], v[106:109]
	v_mfma_f32_16x16x32_bf16 v[94:97], v[182:185], v[210:213], v[94:97]
	v_mfma_f32_16x16x32_bf16 v[90:93], v[190:193], v[210:213], v[90:93]
	v_mfma_f32_16x16x32_bf16 v[86:89], v[182:185], v[218:221], v[86:89]
	v_mfma_f32_16x16x32_bf16 v[82:85], v[190:193], v[218:221], v[82:85]
	v_mfma_f32_16x16x32_bf16 v[30:33], v[182:185], v[226:229], v[30:33]
	v_mfma_f32_16x16x32_bf16 v[26:29], v[190:193], v[226:229], v[26:29]
	s_setprio 0
	s_barrier
	s_add_i32 s40, s66, s42
	v_lshl_add_u64 v[158:159], v[158:159], 0, s[12:13]
	s_mov_b32 m0, s40
	ds_read_b128 v[196:199], v160 offset:49152
	ds_read_b128 v[200:203], v160 offset:50176
	ds_read_b128 v[206:209], v160 offset:51200
	ds_read_b128 v[210:213], v160 offset:52224
	ds_read_b128 v[214:217], v160 offset:53248
	ds_read_b128 v[218:221], v160 offset:54272
	ds_read_b128 v[222:225], v160 offset:55296
	ds_read_b128 v[226:229], v160 offset:56320
	global_load_lds_dwordx4 v[158:159], off
	s_add_i32 m0, s40, 0x2000
	s_add_u32 s34, s34, 0x100080
	v_lshl_add_u64 v[158:159], v[230:231], 0, s[12:13]
	s_addc_u32 s35, s35, 0
	s_add_i32 s40, s67, s42
	global_load_lds_dwordx4 v[158:159], off
	v_lshl_add_u64 v[158:159], s[34:35], 0, v[134:135]
	s_mov_b32 m0, s40
	s_nop 0
	global_load_lds_dwordx4 v[158:159], off
	v_lshl_add_u64 v[158:159], s[34:35], 0, v[132:133]
	s_add_i32 m0, s40, 0x2000
	s_nop 0
	global_load_lds_dwordx4 v[158:159], off
	v_lshl_add_u64 v[158:159], v[232:233], 0, s[12:13]
	s_mov_b32 m0, s52
	s_nop 0
	global_load_lds_dwordx4 v[158:159], off
	v_lshl_add_u64 v[158:159], v[234:235], 0, s[12:13]
	s_mov_b32 m0, s53
	s_nop 0
	global_load_lds_dwordx4 v[158:159], off
	s_nop 0
	s_waitcnt vmcnt(8)
	s_waitcnt lgkmcnt(0)
	s_barrier
	s_setprio 1
	v_mfma_f32_16x16x32_bf16 v[78:81], v[162:165], v[196:199], v[78:81]
	v_mfma_f32_16x16x32_bf16 v[74:77], v[170:173], v[196:199], v[74:77]
	v_mfma_f32_16x16x32_bf16 v[70:73], v[162:165], v[206:209], v[70:73]
	v_mfma_f32_16x16x32_bf16 v[66:69], v[170:173], v[206:209], v[66:69]
	v_mfma_f32_16x16x32_bf16 v[54:57], v[162:165], v[214:217], v[54:57]
	v_mfma_f32_16x16x32_bf16 v[50:53], v[170:173], v[214:217], v[50:53]
	v_mfma_f32_16x16x32_bf16 v[14:17], v[162:165], v[222:225], v[14:17]
	v_mfma_f32_16x16x32_bf16 v[10:13], v[170:173], v[222:225], v[10:13]
	v_mfma_f32_16x16x32_bf16 v[78:81], v[166:169], v[200:203], v[78:81]
	v_mfma_f32_16x16x32_bf16 v[74:77], v[174:177], v[200:203], v[74:77]
	v_mfma_f32_16x16x32_bf16 v[70:73], v[166:169], v[210:213], v[70:73]
	v_mfma_f32_16x16x32_bf16 v[66:69], v[174:177], v[210:213], v[66:69]
	v_mfma_f32_16x16x32_bf16 v[54:57], v[166:169], v[218:221], v[54:57]
	v_mfma_f32_16x16x32_bf16 v[50:53], v[174:177], v[218:221], v[50:53]
	v_mfma_f32_16x16x32_bf16 v[14:17], v[166:169], v[226:229], v[14:17]
	v_mfma_f32_16x16x32_bf16 v[10:13], v[174:177], v[226:229], v[10:13]
	v_mfma_f32_16x16x32_bf16 v[62:65], v[178:181], v[196:199], v[62:65]
	v_mfma_f32_16x16x32_bf16 v[58:61], v[186:189], v[196:199], v[58:61]
	v_mfma_f32_16x16x32_bf16 v[46:49], v[178:181], v[206:209], v[46:49]
	v_mfma_f32_16x16x32_bf16 v[38:41], v[186:189], v[206:209], v[38:41]
	v_mfma_f32_16x16x32_bf16 v[22:25], v[178:181], v[214:217], v[22:25]
	v_mfma_f32_16x16x32_bf16 v[18:21], v[186:189], v[214:217], v[18:21]
	v_mfma_f32_16x16x32_bf16 v[6:9], v[178:181], v[222:225], v[6:9]
	v_mfma_f32_16x16x32_bf16 v[2:5], v[186:189], v[222:225], v[2:5]
	v_mfma_f32_16x16x32_bf16 v[62:65], v[182:185], v[200:203], v[62:65]
	v_mfma_f32_16x16x32_bf16 v[58:61], v[190:193], v[200:203], v[58:61]
	v_mfma_f32_16x16x32_bf16 v[46:49], v[182:185], v[210:213], v[46:49]
	v_mfma_f32_16x16x32_bf16 v[38:41], v[190:193], v[210:213], v[38:41]
	v_mfma_f32_16x16x32_bf16 v[22:25], v[182:185], v[218:221], v[22:25]
	v_mfma_f32_16x16x32_bf16 v[18:21], v[190:193], v[218:221], v[18:21]
	v_mfma_f32_16x16x32_bf16 v[6:9], v[182:185], v[226:229], v[6:9]
	v_mfma_f32_16x16x32_bf16 v[2:5], v[190:193], v[226:229], v[2:5]
	s_setprio 0
	s_barrier
	s_add_u32 s30, s30, 0x100
	s_addc_u32 s31, s31, 0
	s_add_u32 s63, s63, 0x100
	s_addc_u32 s64, s64, 0
	s_cmp_ge_i32 s65, s60
	s_mov_b32 s34, s65
	s_cbranch_scc0 .LBB0_1197
	s_and_b64 vcc, exec, s[18:19]
	s_cbranch_vccz .LBB0_1200
	s_barrier

.LBB0_1391:
	s_add_i32 s82, s48, 2
	s_add_u32 s49, s60, 0xfffe0080
	s_addc_u32 s62, s61, -1
	s_cmp_eq_u32 s47, s48
	s_cselect_b32 s48, s54, s51
	s_cselect_b32 s63, s9, s62
	s_cselect_b32 s62, s8, s49
	s_cselect_b32 s49, s55, s53
	v_lshl_add_u64 v[156:157], s[60:61], 0, v[140:141]
	s_add_i32 m0, s57, 0xc000
	s_nop 0
	global_load_lds_dwordx4 v[156:157], off
	v_lshl_add_u64 v[156:157], s[60:61], 0, v[142:143]
	s_add_i32 m0, s57, 0xe000
	s_nop 0
	global_load_lds_dwordx4 v[156:157], off
	ds_read_b128 v[152:155], v159
	ds_read_b128 v[162:165], v159 offset:1024
	ds_read_b128 v[166:169], v159 offset:2048
	ds_read_b128 v[170:173], v159 offset:3072
	ds_read_b128 v[174:177], v160
	ds_read_b128 v[178:181], v160 offset:1024
	ds_read_b128 v[182:185], v160 offset:2048
	ds_read_b128 v[186:189], v160 offset:3072
	ds_read_b128 v[190:193], v161
	ds_read_b128 v[196:199], v161 offset:1024
	ds_read_b128 v[200:203], v161 offset:2048
	ds_read_b128 v[206:209], v161 offset:3072
	ds_read_b128 v[210:213], v161 offset:4096
	ds_read_b128 v[214:217], v161 offset:5120
	ds_read_b128 v[218:221], v161 offset:6144
	ds_read_b128 v[222:225], v161 offset:7168
	s_waitcnt vmcnt(8)
	s_waitcnt lgkmcnt(0)
	s_barrier
	s_setprio 1
	v_mfma_f32_16x16x32_bf16 v[126:129], v[152:155], v[190:193], v[126:129]
	v_mfma_f32_16x16x32_bf16 v[122:125], v[166:169], v[190:193], v[122:125]
	v_mfma_f32_16x16x32_bf16 v[110:113], v[152:155], v[200:203], v[110:113]
	v_mfma_f32_16x16x32_bf16 v[106:109], v[166:169], v[200:203], v[106:109]
	v_mfma_f32_16x16x32_bf16 v[94:97], v[152:155], v[210:213], v[94:97]
	v_mfma_f32_16x16x32_bf16 v[90:93], v[166:169], v[210:213], v[90:93]
	v_mfma_f32_16x16x32_bf16 v[78:81], v[152:155], v[218:221], v[78:81]
	v_mfma_f32_16x16x32_bf16 v[74:77], v[166:169], v[218:221], v[74:77]
	v_mfma_f32_16x16x32_bf16 v[126:129], v[162:165], v[196:199], v[126:129]
	v_mfma_f32_16x16x32_bf16 v[122:125], v[170:173], v[196:199], v[122:125]
	v_mfma_f32_16x16x32_bf16 v[110:113], v[162:165], v[206:209], v[110:113]
	v_mfma_f32_16x16x32_bf16 v[106:109], v[170:173], v[206:209], v[106:109]
	v_mfma_f32_16x16x32_bf16 v[94:97], v[162:165], v[214:217], v[94:97]
	v_mfma_f32_16x16x32_bf16 v[90:93], v[170:173], v[214:217], v[90:93]
	v_mfma_f32_16x16x32_bf16 v[78:81], v[162:165], v[222:225], v[78:81]
	v_mfma_f32_16x16x32_bf16 v[74:77], v[170:173], v[222:225], v[74:77]
	v_mfma_f32_16x16x32_bf16 v[118:121], v[174:177], v[190:193], v[118:121]
	v_mfma_f32_16x16x32_bf16 v[114:117], v[182:185], v[190:193], v[114:117]
	v_mfma_f32_16x16x32_bf16 v[102:105], v[174:177], v[200:203], v[102:105]
	v_mfma_f32_16x16x32_bf16 v[98:101], v[182:185], v[200:203], v[98:101]
	v_mfma_f32_16x16x32_bf16 v[86:89], v[174:177], v[210:213], v[86:89]
	v_mfma_f32_16x16x32_bf16 v[82:85], v[182:185], v[210:213], v[82:85]
	v_mfma_f32_16x16x32_bf16 v[70:73], v[174:177], v[218:221], v[70:73]
	v_mfma_f32_16x16x32_bf16 v[66:69], v[182:185], v[218:221], v[66:69]
	v_mfma_f32_16x16x32_bf16 v[118:121], v[178:181], v[196:199], v[118:121]
	v_mfma_f32_16x16x32_bf16 v[114:117], v[186:189], v[196:199], v[114:117]
	v_mfma_f32_16x16x32_bf16 v[102:105], v[178:181], v[206:209], v[102:105]
	v_mfma_f32_16x16x32_bf16 v[98:101], v[186:189], v[206:209], v[98:101]
	v_mfma_f32_16x16x32_bf16 v[86:89], v[178:181], v[214:217], v[86:89]
	v_mfma_f32_16x16x32_bf16 v[82:85], v[186:189], v[214:217], v[82:85]
	v_mfma_f32_16x16x32_bf16 v[70:73], v[178:181], v[222:225], v[70:73]
	v_mfma_f32_16x16x32_bf16 v[66:69], v[186:189], v[222:225], v[66:69]
	s_setprio 0
	s_barrier
	s_add_i32 s83, s73, s64
	v_lshl_add_u64 v[156:157], s[48:49], 0, v[134:135]
	s_mov_b32 m0, s83
	ds_read_b128 v[190:193], v161 offset:16384
	ds_read_b128 v[196:199], v161 offset:17408
	ds_read_b128 v[200:203], v161 offset:18432
	ds_read_b128 v[206:209], v161 offset:19456
	ds_read_b128 v[210:213], v161 offset:20480
	ds_read_b128 v[214:217], v161 offset:21504
	ds_read_b128 v[218:221], v161 offset:22528
	ds_read_b128 v[222:225], v161 offset:23552
	global_load_lds_dwordx4 v[156:157], off
	s_add_i32 m0, s83, 0x2000
	s_add_u32 s84, s48, 0x20000
	v_lshl_add_u64 v[226:227], s[48:49], 0, v[138:139]
	s_addc_u32 s85, s49, 0
	s_add_i32 s83, s74, s64
	global_load_lds_dwordx4 v[226:227], off
	v_lshl_add_u64 v[228:229], s[84:85], 0, v[134:135]
	s_mov_b32 m0, s83
	v_lshl_add_u64 v[230:231], s[62:63], 0, v[136:137]
	global_load_lds_dwordx4 v[228:229], off
	v_lshl_add_u64 v[228:229], s[84:85], 0, v[138:139]
	s_add_i32 m0, s83, 0x2000
	s_nop 0
	global_load_lds_dwordx4 v[228:229], off
	v_lshl_add_u64 v[228:229], s[62:63], 0, v[132:133]
	s_mov_b32 m0, s57
	s_nop 0
	global_load_lds_dwordx4 v[228:229], off
	s_mov_b32 m0, s59
	s_nop 0
	global_load_lds_dwordx4 v[230:231], off
	s_waitcnt vmcnt(8)
	s_waitcnt lgkmcnt(0)
	s_barrier
	s_setprio 1
	v_mfma_f32_16x16x32_bf16 v[62:65], v[152:155], v[190:193], v[62:65]
	v_mfma_f32_16x16x32_bf16 v[58:61], v[166:169], v[190:193], v[58:61]
	v_mfma_f32_16x16x32_bf16 v[46:49], v[152:155], v[200:203], v[46:49]
	v_mfma_f32_16x16x32_bf16 v[42:45], v[166:169], v[200:203], v[42:45]
	v_mfma_f32_16x16x32_bf16 v[30:33], v[152:155], v[210:213], v[30:33]
	v_mfma_f32_16x16x32_bf16 v[26:29], v[166:169], v[210:213], v[26:29]
	v_mfma_f32_16x16x32_bf16 v[14:17], v[152:155], v[218:221], v[14:17]
	v_mfma_f32_16x16x32_bf16 v[10:13], v[166:169], v[218:221], v[10:13]
	v_mfma_f32_16x16x32_bf16 v[62:65], v[162:165], v[196:199], v[62:65]
	v_mfma_f32_16x16x32_bf16 v[58:61], v[170:173], v[196:199], v[58:61]
	v_mfma_f32_16x16x32_bf16 v[46:49], v[162:165], v[206:209], v[46:49]
	v_mfma_f32_16x16x32_bf16 v[42:45], v[170:173], v[206:209], v[42:45]
	v_mfma_f32_16x16x32_bf16 v[30:33], v[162:165], v[214:217], v[30:33]
	v_mfma_f32_16x16x32_bf16 v[26:29], v[170:173], v[214:217], v[26:29]
	v_mfma_f32_16x16x32_bf16 v[14:17], v[162:165], v[222:225], v[14:17]
	v_mfma_f32_16x16x32_bf16 v[10:13], v[170:173], v[222:225], v[10:13]
	v_mfma_f32_16x16x32_bf16 v[54:57], v[174:177], v[190:193], v[54:57]
	v_mfma_f32_16x16x32_bf16 v[50:53], v[182:185], v[190:193], v[50:53]
	v_mfma_f32_16x16x32_bf16 v[38:41], v[174:177], v[200:203], v[38:41]
	v_mfma_f32_16x16x32_bf16 v[34:37], v[182:185], v[200:203], v[34:37]
	v_mfma_f32_16x16x32_bf16 v[22:25], v[174:177], v[210:213], v[22:25]
	v_mfma_f32_16x16x32_bf16 v[18:21], v[182:185], v[210:213], v[18:21]
	v_mfma_f32_16x16x32_bf16 v[6:9], v[174:177], v[218:221], v[6:9]
	v_mfma_f32_16x16x32_bf16 v[2:5], v[182:185], v[218:221], v[2:5]
	v_mfma_f32_16x16x32_bf16 v[54:57], v[178:181], v[196:199], v[54:57]
	v_mfma_f32_16x16x32_bf16 v[50:53], v[186:189], v[196:199], v[50:53]
	v_mfma_f32_16x16x32_bf16 v[38:41], v[178:181], v[206:209], v[38:41]
	v_mfma_f32_16x16x32_bf16 v[34:37], v[186:189], v[206:209], v[34:37]
	v_mfma_f32_16x16x32_bf16 v[22:25], v[178:181], v[214:217], v[22:25]
	v_mfma_f32_16x16x32_bf16 v[18:21], v[186:189], v[214:217], v[18:21]
	v_mfma_f32_16x16x32_bf16 v[6:9], v[178:181], v[222:225], v[6:9]
	v_mfma_f32_16x16x32_bf16 v[2:5], v[186:189], v[222:225], v[2:5]
	s_setprio 0
	s_barrier
	s_add_u32 s62, s62, 0x20000
	s_addc_u32 s63, s63, 0
	s_mov_b32 m0, s65
	v_lshl_add_u64 v[232:233], s[62:63], 0, v[132:133]
	global_load_lds_dwordx4 v[232:233], off
	v_lshl_add_u64 v[232:233], s[62:63], 0, v[136:137]
	s_mov_b32 m0, s66
	s_nop 0
	global_load_lds_dwordx4 v[232:233], off
	s_add_i32 s83, 0, 0x18000
	s_add_i32 s84, 0, 0x1c000
	v_add_u32_e32 v170, s83, v131
	v_add_u32_e32 v186, s84, v131
	ds_read_b128 v[152:155], v170
	ds_read_b128 v[162:165], v170 offset:1024
	ds_read_b128 v[166:169], v170 offset:2048
	ds_read_b128 v[170:173], v170 offset:3072
	ds_read_b128 v[174:177], v186
	ds_read_b128 v[178:181], v186 offset:1024
	ds_read_b128 v[182:185], v186 offset:2048
	ds_read_b128 v[186:189], v186 offset:3072
	ds_read_b128 v[190:193], v161 offset:32768
	ds_read_b128 v[196:199], v161 offset:33792
	ds_read_b128 v[200:203], v161 offset:34816
	ds_read_b128 v[206:209], v161 offset:35840
	ds_read_b128 v[210:213], v161 offset:36864
	ds_read_b128 v[214:217], v161 offset:37888
	ds_read_b128 v[218:221], v161 offset:38912
	ds_read_b128 v[222:225], v161 offset:39936
	s_waitcnt vmcnt(8)
	s_waitcnt lgkmcnt(0)
	s_barrier
	s_setprio 1
	v_mfma_f32_16x16x32_bf16 v[126:129], v[152:155], v[190:193], v[126:129]
	v_mfma_f32_16x16x32_bf16 v[122:125], v[166:169], v[190:193], v[122:125]
	v_mfma_f32_16x16x32_bf16 v[110:113], v[152:155], v[200:203], v[110:113]
	v_mfma_f32_16x16x32_bf16 v[106:109], v[166:169], v[200:203], v[106:109]
	v_mfma_f32_16x16x32_bf16 v[94:97], v[152:155], v[210:213], v[94:97]
	v_mfma_f32_16x16x32_bf16 v[90:93], v[166:169], v[210:213], v[90:93]
	v_mfma_f32_16x16x32_bf16 v[78:81], v[152:155], v[218:221], v[78:81]
	v_mfma_f32_16x16x32_bf16 v[74:77], v[166:169], v[218:221], v[74:77]
	v_mfma_f32_16x16x32_bf16 v[126:129], v[162:165], v[196:199], v[126:129]
	v_mfma_f32_16x16x32_bf16 v[122:125], v[170:173], v[196:199], v[122:125]
	v_mfma_f32_16x16x32_bf16 v[110:113], v[162:165], v[206:209], v[110:113]
	v_mfma_f32_16x16x32_bf16 v[106:109], v[170:173], v[206:209], v[106:109]
	v_mfma_f32_16x16x32_bf16 v[94:97], v[162:165], v[214:217], v[94:97]
	v_mfma_f32_16x16x32_bf16 v[90:93], v[170:173], v[214:217], v[90:93]
	v_mfma_f32_16x16x32_bf16 v[78:81], v[162:165], v[222:225], v[78:81]
	v_mfma_f32_16x16x32_bf16 v[74:77], v[170:173], v[222:225], v[74:77]
	v_mfma_f32_16x16x32_bf16 v[118:121], v[174:177], v[190:193], v[118:121]
	v_mfma_f32_16x16x32_bf16 v[114:117], v[182:185], v[190:193], v[114:117]
	v_mfma_f32_16x16x32_bf16 v[102:105], v[174:177], v[200:203], v[102:105]
	v_mfma_f32_16x16x32_bf16 v[98:101], v[182:185], v[200:203], v[98:101]
	v_mfma_f32_16x16x32_bf16 v[86:89], v[174:177], v[210:213], v[86:89]
	v_mfma_f32_16x16x32_bf16 v[82:85], v[182:185], v[210:213], v[82:85]
	v_mfma_f32_16x16x32_bf16 v[70:73], v[174:177], v[218:221], v[70:73]
	v_mfma_f32_16x16x32_bf16 v[66:69], v[182:185], v[218:221], v[66:69]
	v_mfma_f32_16x16x32_bf16 v[118:121], v[178:181], v[196:199], v[118:121]
	v_mfma_f32_16x16x32_bf16 v[114:117], v[186:189], v[196:199], v[114:117]
	v_mfma_f32_16x16x32_bf16 v[102:105], v[178:181], v[206:209], v[102:105]
	v_mfma_f32_16x16x32_bf16 v[98:101], v[186:189], v[206:209], v[98:101]
	v_mfma_f32_16x16x32_bf16 v[86:89], v[178:181], v[214:217], v[86:89]
	v_mfma_f32_16x16x32_bf16 v[82:85], v[186:189], v[214:217], v[82:85]
	v_mfma_f32_16x16x32_bf16 v[70:73], v[178:181], v[222:225], v[70:73]
	v_mfma_f32_16x16x32_bf16 v[66:69], v[186:189], v[222:225], v[66:69]
	s_setprio 0
	s_barrier
	s_add_i32 s62, s83, s64
	v_lshl_add_u64 v[156:157], v[156:157], 0, s[18:19]
	s_mov_b32 m0, s62
	ds_read_b128 v[190:193], v161 offset:49152
	ds_read_b128 v[196:199], v161 offset:50176
	ds_read_b128 v[200:203], v161 offset:51200
	ds_read_b128 v[206:209], v161 offset:52224
	ds_read_b128 v[210:213], v161 offset:53248
	ds_read_b128 v[214:217], v161 offset:54272
	ds_read_b128 v[218:221], v161 offset:55296
	ds_read_b128 v[222:225], v161 offset:56320
	global_load_lds_dwordx4 v[156:157], off
	s_add_i32 m0, s62, 0x2000
	s_add_u32 s48, s48, 0x20080
	v_lshl_add_u64 v[156:157], v[226:227], 0, s[18:19]
	s_addc_u32 s49, s49, 0
	s_add_i32 s62, s84, s64
	global_load_lds_dwordx4 v[156:157], off
	v_lshl_add_u64 v[156:157], s[48:49], 0, v[134:135]
	s_mov_b32 m0, s62
	s_nop 0
	global_load_lds_dwordx4 v[156:157], off
	v_lshl_add_u64 v[156:157], s[48:49], 0, v[138:139]
	s_add_i32 m0, s62, 0x2000
	s_nop 0
	global_load_lds_dwordx4 v[156:157], off
	v_lshl_add_u64 v[156:157], v[228:229], 0, s[18:19]
	s_mov_b32 m0, s70
	s_nop 0
	global_load_lds_dwordx4 v[156:157], off
	v_lshl_add_u64 v[156:157], v[230:231], 0, s[18:19]
	s_mov_b32 m0, s71
	s_nop 0
	global_load_lds_dwordx4 v[156:157], off
	s_nop 0
	s_waitcnt vmcnt(8)
	s_waitcnt lgkmcnt(0)
	s_barrier
	s_setprio 1
	v_mfma_f32_16x16x32_bf16 v[62:65], v[152:155], v[190:193], v[62:65]
	v_mfma_f32_16x16x32_bf16 v[58:61], v[166:169], v[190:193], v[58:61]
	v_mfma_f32_16x16x32_bf16 v[46:49], v[152:155], v[200:203], v[46:49]
	v_mfma_f32_16x16x32_bf16 v[42:45], v[166:169], v[200:203], v[42:45]
	v_mfma_f32_16x16x32_bf16 v[30:33], v[152:155], v[210:213], v[30:33]
	v_mfma_f32_16x16x32_bf16 v[26:29], v[166:169], v[210:213], v[26:29]
	v_mfma_f32_16x16x32_bf16 v[14:17], v[152:155], v[218:221], v[14:17]
	v_mfma_f32_16x16x32_bf16 v[10:13], v[166:169], v[218:221], v[10:13]
	v_mfma_f32_16x16x32_bf16 v[62:65], v[162:165], v[196:199], v[62:65]
	v_mfma_f32_16x16x32_bf16 v[58:61], v[170:173], v[196:199], v[58:61]
	v_mfma_f32_16x16x32_bf16 v[46:49], v[162:165], v[206:209], v[46:49]
	v_mfma_f32_16x16x32_bf16 v[42:45], v[170:173], v[206:209], v[42:45]
	v_mfma_f32_16x16x32_bf16 v[30:33], v[162:165], v[214:217], v[30:33]
	v_mfma_f32_16x16x32_bf16 v[26:29], v[170:173], v[214:217], v[26:29]
	v_mfma_f32_16x16x32_bf16 v[14:17], v[162:165], v[222:225], v[14:17]
	v_mfma_f32_16x16x32_bf16 v[10:13], v[170:173], v[222:225], v[10:13]
	v_mfma_f32_16x16x32_bf16 v[54:57], v[174:177], v[190:193], v[54:57]
	v_mfma_f32_16x16x32_bf16 v[50:53], v[182:185], v[190:193], v[50:53]
	v_mfma_f32_16x16x32_bf16 v[38:41], v[174:177], v[200:203], v[38:41]
	v_mfma_f32_16x16x32_bf16 v[34:37], v[182:185], v[200:203], v[34:37]
	v_mfma_f32_16x16x32_bf16 v[22:25], v[174:177], v[210:213], v[22:25]
	v_mfma_f32_16x16x32_bf16 v[18:21], v[182:185], v[210:213], v[18:21]
	v_mfma_f32_16x16x32_bf16 v[6:9], v[174:177], v[218:221], v[6:9]
	v_mfma_f32_16x16x32_bf16 v[2:5], v[182:185], v[218:221], v[2:5]
	v_mfma_f32_16x16x32_bf16 v[54:57], v[178:181], v[196:199], v[54:57]
	v_mfma_f32_16x16x32_bf16 v[50:53], v[186:189], v[196:199], v[50:53]
	v_mfma_f32_16x16x32_bf16 v[38:41], v[178:181], v[206:209], v[38:41]
	v_mfma_f32_16x16x32_bf16 v[34:37], v[186:189], v[206:209], v[34:37]
	v_mfma_f32_16x16x32_bf16 v[22:25], v[178:181], v[214:217], v[22:25]
	v_mfma_f32_16x16x32_bf16 v[18:21], v[186:189], v[214:217], v[18:21]
	v_mfma_f32_16x16x32_bf16 v[6:9], v[178:181], v[222:225], v[6:9]
	v_mfma_f32_16x16x32_bf16 v[2:5], v[186:189], v[222:225], v[2:5]
	s_setprio 0
	s_barrier
	s_add_u32 s60, s60, 0x100
	s_addc_u32 s61, s61, 0
	s_add_u32 s51, s51, 0x100
	s_addc_u32 s53, s53, 0
	s_cmp_ge_i32 s82, s81
	s_mov_b32 s48, s82
	s_cbranch_scc0 .LBB0_1391
	s_and_b64 vcc, exec, s[20:21]
	s_cbranch_vccz .LBB0_1394
	s_barrier

.LBB0_1553:
	s_add_i32 s76, s48, 2
	s_add_u32 s49, s46, 0xfff00080
	s_addc_u32 s50, s47, -1
	s_cmp_eq_u32 s73, s48
	s_cselect_b32 s48, s29, s74
	s_cselect_b32 s51, s9, s50
	s_cselect_b32 s50, s27, s49
	s_cselect_b32 s49, s25, s75
	v_lshl_add_u64 v[192:193], s[46:47], 0, v[148:149]
	s_add_i32 m0, s43, 0xc000
	s_nop 0
	global_load_lds_dwordx4 v[192:193], off
	v_lshl_add_u64 v[192:193], s[46:47], 0, v[150:151]
	s_add_i32 m0, s43, 0xe000
	s_nop 0
	global_load_lds_dwordx4 v[192:193], off
	ds_read_b128 v[156:159], v161
	ds_read_b128 v[164:167], v161 offset:1024
	ds_read_b128 v[168:171], v161 offset:2048
	ds_read_b128 v[172:175], v161 offset:3072
	ds_read_b128 v[176:179], v162
	ds_read_b128 v[180:183], v162 offset:1024
	ds_read_b128 v[184:187], v162 offset:2048
	ds_read_b128 v[188:191], v162 offset:3072
	ds_read_b128 v[196:199], v163
	ds_read_b128 v[200:203], v163 offset:1024
	ds_read_b128 v[206:209], v163 offset:2048
	ds_read_b128 v[210:213], v163 offset:3072
	ds_read_b128 v[214:217], v163 offset:4096
	ds_read_b128 v[218:221], v163 offset:5120
	ds_read_b128 v[222:225], v163 offset:6144
	ds_read_b128 v[226:229], v163 offset:7168
	s_waitcnt vmcnt(8)
	s_waitcnt lgkmcnt(0)
	s_barrier
	s_setprio 1
	v_mfma_f32_16x16x32_bf16 v[78:81], v[156:159], v[196:199], v[78:81]
	v_mfma_f32_16x16x32_bf16 v[74:77], v[168:171], v[196:199], v[74:77]
	v_mfma_f32_16x16x32_bf16 v[70:73], v[156:159], v[206:209], v[70:73]
	v_mfma_f32_16x16x32_bf16 v[62:65], v[168:171], v[206:209], v[62:65]
	v_mfma_f32_16x16x32_bf16 v[58:61], v[156:159], v[214:217], v[58:61]
	v_mfma_f32_16x16x32_bf16 v[54:57], v[168:171], v[214:217], v[54:57]
	v_mfma_f32_16x16x32_bf16 v[46:49], v[156:159], v[222:225], v[46:49]
	v_mfma_f32_16x16x32_bf16 v[38:41], v[168:171], v[222:225], v[38:41]
	v_mfma_f32_16x16x32_bf16 v[78:81], v[164:167], v[200:203], v[78:81]
	v_mfma_f32_16x16x32_bf16 v[74:77], v[172:175], v[200:203], v[74:77]
	v_mfma_f32_16x16x32_bf16 v[70:73], v[164:167], v[210:213], v[70:73]
	v_mfma_f32_16x16x32_bf16 v[62:65], v[172:175], v[210:213], v[62:65]
	v_mfma_f32_16x16x32_bf16 v[58:61], v[164:167], v[218:221], v[58:61]
	v_mfma_f32_16x16x32_bf16 v[54:57], v[172:175], v[218:221], v[54:57]
	v_mfma_f32_16x16x32_bf16 v[46:49], v[164:167], v[226:229], v[46:49]
	v_mfma_f32_16x16x32_bf16 v[38:41], v[172:175], v[226:229], v[38:41]
	v_mfma_f32_16x16x32_bf16 v[50:53], v[176:179], v[196:199], v[50:53]
	v_mfma_f32_16x16x32_bf16 v[42:45], v[184:187], v[196:199], v[42:45]
	v_mfma_f32_16x16x32_bf16 v[34:37], v[176:179], v[206:209], v[34:37]
	v_mfma_f32_16x16x32_bf16 v[26:29], v[184:187], v[206:209], v[26:29]
	v_mfma_f32_16x16x32_bf16 v[18:21], v[176:179], v[214:217], v[18:21]
	v_mfma_f32_16x16x32_bf16 v[14:17], v[184:187], v[214:217], v[14:17]
	v_mfma_f32_16x16x32_bf16 v[10:13], v[176:179], v[222:225], v[10:13]
	v_mfma_f32_16x16x32_bf16 v[6:9], v[184:187], v[222:225], v[6:9]
	v_mfma_f32_16x16x32_bf16 v[50:53], v[180:183], v[200:203], v[50:53]
	v_mfma_f32_16x16x32_bf16 v[42:45], v[188:191], v[200:203], v[42:45]
	v_mfma_f32_16x16x32_bf16 v[34:37], v[180:183], v[210:213], v[34:37]
	v_mfma_f32_16x16x32_bf16 v[26:29], v[188:191], v[210:213], v[26:29]
	v_mfma_f32_16x16x32_bf16 v[18:21], v[180:183], v[218:221], v[18:21]
	v_mfma_f32_16x16x32_bf16 v[14:17], v[188:191], v[218:221], v[14:17]
	v_mfma_f32_16x16x32_bf16 v[10:13], v[180:183], v[226:229], v[10:13]
	v_mfma_f32_16x16x32_bf16 v[6:9], v[188:191], v[226:229], v[6:9]
	s_setprio 0
	s_barrier
	s_add_i32 s77, s66, s53
	v_lshl_add_u64 v[192:193], s[48:49], 0, v[134:135]
	s_mov_b32 m0, s77
	ds_read_b128 v[196:199], v163 offset:16384
	ds_read_b128 v[200:203], v163 offset:17408
	ds_read_b128 v[206:209], v163 offset:18432
	ds_read_b128 v[210:213], v163 offset:19456
	ds_read_b128 v[214:217], v163 offset:20480
	ds_read_b128 v[218:221], v163 offset:21504
	ds_read_b128 v[222:225], v163 offset:22528
	ds_read_b128 v[226:229], v163 offset:23552
	global_load_lds_dwordx4 v[192:193], off
	s_add_i32 m0, s77, 0x2000
	s_add_u32 s78, s48, 0x100000
	v_lshl_add_u64 v[230:231], s[48:49], 0, v[138:139]
	s_addc_u32 s79, s49, 0
	s_add_i32 s77, s67, s53
	global_load_lds_dwordx4 v[230:231], off
	v_lshl_add_u64 v[232:233], s[78:79], 0, v[134:135]
	s_mov_b32 m0, s77
	v_lshl_add_u64 v[234:235], s[50:51], 0, v[136:137]
	global_load_lds_dwordx4 v[232:233], off
	v_lshl_add_u64 v[232:233], s[78:79], 0, v[138:139]
	s_add_i32 m0, s77, 0x2000
	s_nop 0
	global_load_lds_dwordx4 v[232:233], off
	v_lshl_add_u64 v[232:233], s[50:51], 0, v[132:133]
	s_mov_b32 m0, s43
	s_nop 0
	global_load_lds_dwordx4 v[232:233], off
	s_mov_b32 m0, s54
	s_nop 0
	global_load_lds_dwordx4 v[234:235], off
	s_waitcnt vmcnt(8)
	s_waitcnt lgkmcnt(0)
	s_barrier
	s_setprio 1
	v_mfma_f32_16x16x32_bf16 v[126:129], v[156:159], v[196:199], v[126:129]
	v_mfma_f32_16x16x32_bf16 v[118:121], v[168:171], v[196:199], v[118:121]
	v_mfma_f32_16x16x32_bf16 v[110:113], v[156:159], v[206:209], v[110:113]
	v_mfma_f32_16x16x32_bf16 v[102:105], v[168:171], v[206:209], v[102:105]
	v_mfma_f32_16x16x32_bf16 v[94:97], v[156:159], v[214:217], v[94:97]
	v_mfma_f32_16x16x32_bf16 v[86:89], v[168:171], v[214:217], v[86:89]
	v_mfma_f32_16x16x32_bf16 v[66:69], v[156:159], v[222:225], v[66:69]
	v_mfma_f32_16x16x32_bf16 v[22:25], v[168:171], v[222:225], v[22:25]
	v_mfma_f32_16x16x32_bf16 v[126:129], v[164:167], v[200:203], v[126:129]
	v_mfma_f32_16x16x32_bf16 v[118:121], v[172:175], v[200:203], v[118:121]
	v_mfma_f32_16x16x32_bf16 v[110:113], v[164:167], v[210:213], v[110:113]
	v_mfma_f32_16x16x32_bf16 v[102:105], v[172:175], v[210:213], v[102:105]
	v_mfma_f32_16x16x32_bf16 v[94:97], v[164:167], v[218:221], v[94:97]
	v_mfma_f32_16x16x32_bf16 v[86:89], v[172:175], v[218:221], v[86:89]
	v_mfma_f32_16x16x32_bf16 v[66:69], v[164:167], v[226:229], v[66:69]
	v_mfma_f32_16x16x32_bf16 v[22:25], v[172:175], v[226:229], v[22:25]
	v_mfma_f32_16x16x32_bf16 v[122:125], v[176:179], v[196:199], v[122:125]
	v_mfma_f32_16x16x32_bf16 v[114:117], v[184:187], v[196:199], v[114:117]
	v_mfma_f32_16x16x32_bf16 v[106:109], v[176:179], v[206:209], v[106:109]
	v_mfma_f32_16x16x32_bf16 v[98:101], v[184:187], v[206:209], v[98:101]
	v_mfma_f32_16x16x32_bf16 v[90:93], v[176:179], v[214:217], v[90:93]
	v_mfma_f32_16x16x32_bf16 v[82:85], v[184:187], v[214:217], v[82:85]
	v_mfma_f32_16x16x32_bf16 v[30:33], v[176:179], v[222:225], v[30:33]
	v_mfma_f32_16x16x32_bf16 v[2:5], v[184:187], v[222:225], v[2:5]
	v_mfma_f32_16x16x32_bf16 v[122:125], v[180:183], v[200:203], v[122:125]
	v_mfma_f32_16x16x32_bf16 v[114:117], v[188:191], v[200:203], v[114:117]
	v_mfma_f32_16x16x32_bf16 v[106:109], v[180:183], v[210:213], v[106:109]
	v_mfma_f32_16x16x32_bf16 v[98:101], v[188:191], v[210:213], v[98:101]
	v_mfma_f32_16x16x32_bf16 v[90:93], v[180:183], v[218:221], v[90:93]
	v_mfma_f32_16x16x32_bf16 v[82:85], v[188:191], v[218:221], v[82:85]
	v_mfma_f32_16x16x32_bf16 v[30:33], v[180:183], v[226:229], v[30:33]
	v_mfma_f32_16x16x32_bf16 v[2:5], v[188:191], v[226:229], v[2:5]
	s_setprio 0
	s_barrier
	s_add_u32 s50, s50, 0x100000
	s_addc_u32 s51, s51, 0
	s_mov_b32 m0, s55
	v_lshl_add_u64 v[236:237], s[50:51], 0, v[132:133]
	global_load_lds_dwordx4 v[236:237], off
	v_lshl_add_u64 v[236:237], s[50:51], 0, v[136:137]
	s_mov_b32 m0, s56
	s_nop 0
	global_load_lds_dwordx4 v[236:237], off
	s_add_i32 s77, 0, 0x18000
	s_add_i32 s78, 0, 0x1c000
	v_add_u32_e32 v172, s77, v131
	v_add_u32_e32 v188, s78, v131
	ds_read_b128 v[156:159], v172
	ds_read_b128 v[164:167], v172 offset:1024
	ds_read_b128 v[168:171], v172 offset:2048
	ds_read_b128 v[172:175], v172 offset:3072
	ds_read_b128 v[176:179], v188
	ds_read_b128 v[180:183], v188 offset:1024
	ds_read_b128 v[184:187], v188 offset:2048
	ds_read_b128 v[188:191], v188 offset:3072
	ds_read_b128 v[196:199], v163 offset:32768
	ds_read_b128 v[200:203], v163 offset:33792
	ds_read_b128 v[206:209], v163 offset:34816
	ds_read_b128 v[210:213], v163 offset:35840
	ds_read_b128 v[214:217], v163 offset:36864
	ds_read_b128 v[218:221], v163 offset:37888
	ds_read_b128 v[222:225], v163 offset:38912
	ds_read_b128 v[226:229], v163 offset:39936
	s_waitcnt vmcnt(8)
	s_waitcnt lgkmcnt(0)
	s_barrier
	s_setprio 1
	v_mfma_f32_16x16x32_bf16 v[78:81], v[156:159], v[196:199], v[78:81]
	v_mfma_f32_16x16x32_bf16 v[74:77], v[168:171], v[196:199], v[74:77]
	v_mfma_f32_16x16x32_bf16 v[70:73], v[156:159], v[206:209], v[70:73]
	v_mfma_f32_16x16x32_bf16 v[62:65], v[168:171], v[206:209], v[62:65]
	v_mfma_f32_16x16x32_bf16 v[58:61], v[156:159], v[214:217], v[58:61]
	v_mfma_f32_16x16x32_bf16 v[54:57], v[168:171], v[214:217], v[54:57]
	v_mfma_f32_16x16x32_bf16 v[46:49], v[156:159], v[222:225], v[46:49]
	v_mfma_f32_16x16x32_bf16 v[38:41], v[168:171], v[222:225], v[38:41]
	v_mfma_f32_16x16x32_bf16 v[78:81], v[164:167], v[200:203], v[78:81]
	v_mfma_f32_16x16x32_bf16 v[74:77], v[172:175], v[200:203], v[74:77]
	v_mfma_f32_16x16x32_bf16 v[70:73], v[164:167], v[210:213], v[70:73]
	v_mfma_f32_16x16x32_bf16 v[62:65], v[172:175], v[210:213], v[62:65]
	v_mfma_f32_16x16x32_bf16 v[58:61], v[164:167], v[218:221], v[58:61]
	v_mfma_f32_16x16x32_bf16 v[54:57], v[172:175], v[218:221], v[54:57]
	v_mfma_f32_16x16x32_bf16 v[46:49], v[164:167], v[226:229], v[46:49]
	v_mfma_f32_16x16x32_bf16 v[38:41], v[172:175], v[226:229], v[38:41]
	v_mfma_f32_16x16x32_bf16 v[50:53], v[176:179], v[196:199], v[50:53]
	v_mfma_f32_16x16x32_bf16 v[42:45], v[184:187], v[196:199], v[42:45]
	v_mfma_f32_16x16x32_bf16 v[34:37], v[176:179], v[206:209], v[34:37]
	v_mfma_f32_16x16x32_bf16 v[26:29], v[184:187], v[206:209], v[26:29]
	v_mfma_f32_16x16x32_bf16 v[18:21], v[176:179], v[214:217], v[18:21]
	v_mfma_f32_16x16x32_bf16 v[14:17], v[184:187], v[214:217], v[14:17]
	v_mfma_f32_16x16x32_bf16 v[10:13], v[176:179], v[222:225], v[10:13]
	v_mfma_f32_16x16x32_bf16 v[6:9], v[184:187], v[222:225], v[6:9]
	v_mfma_f32_16x16x32_bf16 v[50:53], v[180:183], v[200:203], v[50:53]
	v_mfma_f32_16x16x32_bf16 v[42:45], v[188:191], v[200:203], v[42:45]
	v_mfma_f32_16x16x32_bf16 v[34:37], v[180:183], v[210:213], v[34:37]
	v_mfma_f32_16x16x32_bf16 v[26:29], v[188:191], v[210:213], v[26:29]
	v_mfma_f32_16x16x32_bf16 v[18:21], v[180:183], v[218:221], v[18:21]
	v_mfma_f32_16x16x32_bf16 v[14:17], v[188:191], v[218:221], v[14:17]
	v_mfma_f32_16x16x32_bf16 v[10:13], v[180:183], v[226:229], v[10:13]
	v_mfma_f32_16x16x32_bf16 v[6:9], v[188:191], v[226:229], v[6:9]
	s_setprio 0
	s_barrier
	s_add_i32 s50, s77, s53
	v_lshl_add_u64 v[192:193], v[192:193], 0, s[14:15]
	s_mov_b32 m0, s50
	ds_read_b128 v[196:199], v163 offset:49152
	ds_read_b128 v[200:203], v163 offset:50176
	ds_read_b128 v[206:209], v163 offset:51200
	ds_read_b128 v[210:213], v163 offset:52224
	ds_read_b128 v[214:217], v163 offset:53248
	ds_read_b128 v[218:221], v163 offset:54272
	ds_read_b128 v[222:225], v163 offset:55296
	ds_read_b128 v[226:229], v163 offset:56320
	global_load_lds_dwordx4 v[192:193], off
	s_add_i32 m0, s50, 0x2000
	s_add_u32 s48, s48, 0x100080
	v_lshl_add_u64 v[192:193], v[230:231], 0, s[14:15]
	s_addc_u32 s49, s49, 0
	s_add_i32 s50, s78, s53
	global_load_lds_dwordx4 v[192:193], off
	v_lshl_add_u64 v[192:193], s[48:49], 0, v[134:135]
	s_mov_b32 m0, s50
	s_nop 0
	global_load_lds_dwordx4 v[192:193], off
	v_lshl_add_u64 v[192:193], s[48:49], 0, v[138:139]
	s_add_i32 m0, s50, 0x2000
	s_nop 0
	global_load_lds_dwordx4 v[192:193], off
	v_lshl_add_u64 v[192:193], v[232:233], 0, s[14:15]
	s_mov_b32 m0, s59
	s_nop 0
	global_load_lds_dwordx4 v[192:193], off
	v_lshl_add_u64 v[192:193], v[234:235], 0, s[14:15]
	s_mov_b32 m0, s60
	s_nop 0
	global_load_lds_dwordx4 v[192:193], off
	s_nop 0
	s_waitcnt vmcnt(8)
	s_waitcnt lgkmcnt(0)
	s_barrier
	s_setprio 1
	v_mfma_f32_16x16x32_bf16 v[126:129], v[156:159], v[196:199], v[126:129]
	v_mfma_f32_16x16x32_bf16 v[118:121], v[168:171], v[196:199], v[118:121]
	v_mfma_f32_16x16x32_bf16 v[110:113], v[156:159], v[206:209], v[110:113]
	v_mfma_f32_16x16x32_bf16 v[102:105], v[168:171], v[206:209], v[102:105]
	v_mfma_f32_16x16x32_bf16 v[94:97], v[156:159], v[214:217], v[94:97]
	v_mfma_f32_16x16x32_bf16 v[86:89], v[168:171], v[214:217], v[86:89]
	v_mfma_f32_16x16x32_bf16 v[66:69], v[156:159], v[222:225], v[66:69]
	v_mfma_f32_16x16x32_bf16 v[22:25], v[168:171], v[222:225], v[22:25]
	v_mfma_f32_16x16x32_bf16 v[126:129], v[164:167], v[200:203], v[126:129]
	v_mfma_f32_16x16x32_bf16 v[118:121], v[172:175], v[200:203], v[118:121]
	v_mfma_f32_16x16x32_bf16 v[110:113], v[164:167], v[210:213], v[110:113]
	v_mfma_f32_16x16x32_bf16 v[102:105], v[172:175], v[210:213], v[102:105]
	v_mfma_f32_16x16x32_bf16 v[94:97], v[164:167], v[218:221], v[94:97]
	v_mfma_f32_16x16x32_bf16 v[86:89], v[172:175], v[218:221], v[86:89]
	v_mfma_f32_16x16x32_bf16 v[66:69], v[164:167], v[226:229], v[66:69]
	v_mfma_f32_16x16x32_bf16 v[22:25], v[172:175], v[226:229], v[22:25]
	v_mfma_f32_16x16x32_bf16 v[122:125], v[176:179], v[196:199], v[122:125]
	v_mfma_f32_16x16x32_bf16 v[114:117], v[184:187], v[196:199], v[114:117]
	v_mfma_f32_16x16x32_bf16 v[106:109], v[176:179], v[206:209], v[106:109]
	v_mfma_f32_16x16x32_bf16 v[98:101], v[184:187], v[206:209], v[98:101]
	v_mfma_f32_16x16x32_bf16 v[90:93], v[176:179], v[214:217], v[90:93]
	v_mfma_f32_16x16x32_bf16 v[82:85], v[184:187], v[214:217], v[82:85]
	v_mfma_f32_16x16x32_bf16 v[30:33], v[176:179], v[222:225], v[30:33]
	v_mfma_f32_16x16x32_bf16 v[2:5], v[184:187], v[222:225], v[2:5]
	v_mfma_f32_16x16x32_bf16 v[122:125], v[180:183], v[200:203], v[122:125]
	v_mfma_f32_16x16x32_bf16 v[114:117], v[188:191], v[200:203], v[114:117]
	v_mfma_f32_16x16x32_bf16 v[106:109], v[180:183], v[210:213], v[106:109]
	v_mfma_f32_16x16x32_bf16 v[98:101], v[188:191], v[210:213], v[98:101]
	v_mfma_f32_16x16x32_bf16 v[90:93], v[180:183], v[218:221], v[90:93]
	v_mfma_f32_16x16x32_bf16 v[82:85], v[188:191], v[218:221], v[82:85]
	v_mfma_f32_16x16x32_bf16 v[30:33], v[180:183], v[226:229], v[30:33]
	v_mfma_f32_16x16x32_bf16 v[2:5], v[188:191], v[226:229], v[2:5]
	s_setprio 0
	s_barrier
	s_add_u32 s46, s46, 0x100
	s_addc_u32 s47, s47, 0
	s_add_u32 s74, s74, 0x100
	s_addc_u32 s75, s75, 0
	s_cmp_ge_i32 s76, s72
	s_mov_b32 s48, s76
	s_cbranch_scc0 .LBB0_1553
	s_and_b64 vcc, exec, s[16:17]
	s_cbranch_vccz .LBB0_1558
	s_barrier
	s_cmp_lt_i32 s52, 0
	s_mov_b64 s[46:47], -1
	s_cbranch_scc1 .LBB0_1559

.LBB0_1712:
	s_add_i32 s82, s48, 2
	s_add_u32 s49, s52, 0xffd50080
	s_addc_u32 s54, s53, -1
	s_cmp_eq_u32 s47, s48
	s_cselect_b32 s48, s50, s80
	s_cselect_b32 s55, s9, s54
	s_cselect_b32 s54, s8, s49
	s_cselect_b32 s49, s51, s81
	v_lshl_add_u64 v[156:157], s[52:53], 0, v[140:141]
	s_add_i32 m0, s57, 0xc000
	s_nop 0
	global_load_lds_dwordx4 v[156:157], off
	v_lshl_add_u64 v[156:157], s[52:53], 0, v[142:143]
	s_add_i32 m0, s57, 0xe000
	s_nop 0
	global_load_lds_dwordx4 v[156:157], off
	ds_read_b128 v[152:155], v160
	ds_read_b128 v[164:167], v160 offset:1024
	ds_read_b128 v[168:171], v160 offset:2048
	ds_read_b128 v[172:175], v160 offset:3072
	ds_read_b128 v[176:179], v161
	ds_read_b128 v[180:183], v161 offset:1024
	ds_read_b128 v[184:187], v161 offset:2048
	ds_read_b128 v[188:191], v161 offset:3072
	ds_read_b128 v[196:199], v162
	ds_read_b128 v[200:203], v162 offset:1024
	ds_read_b128 v[206:209], v162 offset:2048
	ds_read_b128 v[210:213], v162 offset:3072
	ds_read_b128 v[214:217], v162 offset:4096
	ds_read_b128 v[218:221], v162 offset:5120
	ds_read_b128 v[222:225], v162 offset:6144
	ds_read_b128 v[226:229], v162 offset:7168
	s_nop 0
	s_waitcnt vmcnt(8)
	s_waitcnt lgkmcnt(0)
	s_barrier
	s_setprio 1
	v_mfma_f32_16x16x32_bf16 v[126:129], v[152:155], v[196:199], v[126:129]
	v_mfma_f32_16x16x32_bf16 v[122:125], v[168:171], v[196:199], v[122:125]
	v_mfma_f32_16x16x32_bf16 v[110:113], v[152:155], v[206:209], v[110:113]
	v_mfma_f32_16x16x32_bf16 v[106:109], v[168:171], v[206:209], v[106:109]
	v_mfma_f32_16x16x32_bf16 v[94:97], v[152:155], v[214:217], v[94:97]
	v_mfma_f32_16x16x32_bf16 v[90:93], v[168:171], v[214:217], v[90:93]
	v_mfma_f32_16x16x32_bf16 v[78:81], v[152:155], v[222:225], v[78:81]
	v_mfma_f32_16x16x32_bf16 v[74:77], v[168:171], v[222:225], v[74:77]
	v_mfma_f32_16x16x32_bf16 v[126:129], v[164:167], v[200:203], v[126:129]
	v_mfma_f32_16x16x32_bf16 v[122:125], v[172:175], v[200:203], v[122:125]
	v_mfma_f32_16x16x32_bf16 v[110:113], v[164:167], v[210:213], v[110:113]
	v_mfma_f32_16x16x32_bf16 v[106:109], v[172:175], v[210:213], v[106:109]
	v_mfma_f32_16x16x32_bf16 v[94:97], v[164:167], v[218:221], v[94:97]
	v_mfma_f32_16x16x32_bf16 v[90:93], v[172:175], v[218:221], v[90:93]
	v_mfma_f32_16x16x32_bf16 v[78:81], v[164:167], v[226:229], v[78:81]
	v_mfma_f32_16x16x32_bf16 v[74:77], v[172:175], v[226:229], v[74:77]
	v_mfma_f32_16x16x32_bf16 v[118:121], v[176:179], v[196:199], v[118:121]
	v_mfma_f32_16x16x32_bf16 v[114:117], v[184:187], v[196:199], v[114:117]
	v_mfma_f32_16x16x32_bf16 v[102:105], v[176:179], v[206:209], v[102:105]
	v_mfma_f32_16x16x32_bf16 v[98:101], v[184:187], v[206:209], v[98:101]
	v_mfma_f32_16x16x32_bf16 v[86:89], v[176:179], v[214:217], v[86:89]
	v_mfma_f32_16x16x32_bf16 v[82:85], v[184:187], v[214:217], v[82:85]
	v_mfma_f32_16x16x32_bf16 v[70:73], v[176:179], v[222:225], v[70:73]
	v_mfma_f32_16x16x32_bf16 v[66:69], v[184:187], v[222:225], v[66:69]
	v_mfma_f32_16x16x32_bf16 v[118:121], v[180:183], v[200:203], v[118:121]
	v_mfma_f32_16x16x32_bf16 v[114:117], v[188:191], v[200:203], v[114:117]
	v_mfma_f32_16x16x32_bf16 v[102:105], v[180:183], v[210:213], v[102:105]
	v_mfma_f32_16x16x32_bf16 v[98:101], v[188:191], v[210:213], v[98:101]
	v_mfma_f32_16x16x32_bf16 v[86:89], v[180:183], v[218:221], v[86:89]
	v_mfma_f32_16x16x32_bf16 v[82:85], v[188:191], v[218:221], v[82:85]
	v_mfma_f32_16x16x32_bf16 v[70:73], v[180:183], v[226:229], v[70:73]
	v_mfma_f32_16x16x32_bf16 v[66:69], v[188:191], v[226:229], v[66:69]
	s_setprio 0
	s_barrier
	s_add_i32 s83, s67, s56
	v_lshl_add_u64 v[156:157], s[48:49], 0, v[134:135]
	s_mov_b32 m0, s83
	ds_read_b128 v[196:199], v162 offset:16384
	ds_read_b128 v[200:203], v162 offset:17408
	ds_read_b128 v[206:209], v162 offset:18432
	ds_read_b128 v[210:213], v162 offset:19456
	ds_read_b128 v[214:217], v162 offset:20480
	ds_read_b128 v[218:221], v162 offset:21504
	ds_read_b128 v[222:225], v162 offset:22528
	ds_read_b128 v[226:229], v162 offset:23552
	global_load_lds_dwordx4 v[156:157], off
	s_add_i32 m0, s83, 0x2000
	s_add_u32 s84, s48, 0x2b0000
	v_lshl_add_u64 v[192:193], s[48:49], 0, v[138:139]
	s_addc_u32 s85, s49, 0
	s_add_i32 s83, s68, s56
	global_load_lds_dwordx4 v[192:193], off
	v_lshl_add_u64 v[230:231], s[84:85], 0, v[134:135]
	s_mov_b32 m0, s83
	v_lshl_add_u64 v[232:233], s[54:55], 0, v[136:137]
	global_load_lds_dwordx4 v[230:231], off
	v_lshl_add_u64 v[230:231], s[84:85], 0, v[138:139]
	s_add_i32 m0, s83, 0x2000
	s_nop 0
	global_load_lds_dwordx4 v[230:231], off
	v_lshl_add_u64 v[230:231], s[54:55], 0, v[132:133]
	s_mov_b32 m0, s57
	s_nop 0
	global_load_lds_dwordx4 v[230:231], off
	s_mov_b32 m0, s58
	s_nop 0
	global_load_lds_dwordx4 v[232:233], off
	s_waitcnt vmcnt(8)
	s_waitcnt lgkmcnt(0)
	s_barrier
	s_setprio 1
	v_mfma_f32_16x16x32_bf16 v[62:65], v[152:155], v[196:199], v[62:65]
	v_mfma_f32_16x16x32_bf16 v[58:61], v[168:171], v[196:199], v[58:61]
	v_mfma_f32_16x16x32_bf16 v[46:49], v[152:155], v[206:209], v[46:49]
	v_mfma_f32_16x16x32_bf16 v[42:45], v[168:171], v[206:209], v[42:45]
	v_mfma_f32_16x16x32_bf16 v[30:33], v[152:155], v[214:217], v[30:33]
	v_mfma_f32_16x16x32_bf16 v[26:29], v[168:171], v[214:217], v[26:29]
	v_mfma_f32_16x16x32_bf16 v[14:17], v[152:155], v[222:225], v[14:17]
	v_mfma_f32_16x16x32_bf16 v[10:13], v[168:171], v[222:225], v[10:13]
	v_mfma_f32_16x16x32_bf16 v[62:65], v[164:167], v[200:203], v[62:65]
	v_mfma_f32_16x16x32_bf16 v[58:61], v[172:175], v[200:203], v[58:61]
	v_mfma_f32_16x16x32_bf16 v[46:49], v[164:167], v[210:213], v[46:49]
	v_mfma_f32_16x16x32_bf16 v[42:45], v[172:175], v[210:213], v[42:45]
	v_mfma_f32_16x16x32_bf16 v[30:33], v[164:167], v[218:221], v[30:33]
	v_mfma_f32_16x16x32_bf16 v[26:29], v[172:175], v[218:221], v[26:29]
	v_mfma_f32_16x16x32_bf16 v[14:17], v[164:167], v[226:229], v[14:17]
	v_mfma_f32_16x16x32_bf16 v[10:13], v[172:175], v[226:229], v[10:13]
	v_mfma_f32_16x16x32_bf16 v[54:57], v[176:179], v[196:199], v[54:57]
	v_mfma_f32_16x16x32_bf16 v[50:53], v[184:187], v[196:199], v[50:53]
	v_mfma_f32_16x16x32_bf16 v[38:41], v[176:179], v[206:209], v[38:41]
	v_mfma_f32_16x16x32_bf16 v[34:37], v[184:187], v[206:209], v[34:37]
	v_mfma_f32_16x16x32_bf16 v[22:25], v[176:179], v[214:217], v[22:25]
	v_mfma_f32_16x16x32_bf16 v[18:21], v[184:187], v[214:217], v[18:21]
	v_mfma_f32_16x16x32_bf16 v[6:9], v[176:179], v[222:225], v[6:9]
	v_mfma_f32_16x16x32_bf16 v[2:5], v[184:187], v[222:225], v[2:5]
	v_mfma_f32_16x16x32_bf16 v[54:57], v[180:183], v[200:203], v[54:57]
	v_mfma_f32_16x16x32_bf16 v[50:53], v[188:191], v[200:203], v[50:53]
	v_mfma_f32_16x16x32_bf16 v[38:41], v[180:183], v[210:213], v[38:41]
	v_mfma_f32_16x16x32_bf16 v[34:37], v[188:191], v[210:213], v[34:37]
	v_mfma_f32_16x16x32_bf16 v[22:25], v[180:183], v[218:221], v[22:25]
	v_mfma_f32_16x16x32_bf16 v[18:21], v[188:191], v[218:221], v[18:21]
	v_mfma_f32_16x16x32_bf16 v[6:9], v[180:183], v[226:229], v[6:9]
	v_mfma_f32_16x16x32_bf16 v[2:5], v[188:191], v[226:229], v[2:5]
	s_setprio 0
	s_barrier
	s_add_u32 s54, s54, 0x2b0000
	s_addc_u32 s55, s55, 0
	s_mov_b32 m0, s59
	v_lshl_add_u64 v[234:235], s[54:55], 0, v[132:133]
	global_load_lds_dwordx4 v[234:235], off
	v_lshl_add_u64 v[234:235], s[54:55], 0, v[136:137]
	s_mov_b32 m0, s60
	s_nop 0
	global_load_lds_dwordx4 v[234:235], off
	s_add_i32 s83, 0, 0x18000
	v_add_u32_e32 v163, s83, v158
	s_add_i32 s84, 0, 0x1c000
	ds_read_b128 v[152:155], v163
	ds_read_b128 v[164:167], v163 offset:1024
	ds_read_b128 v[168:171], v163 offset:2048
	ds_read_b128 v[172:175], v163 offset:3072
	v_add_u32_e32 v163, s84, v158
	ds_read_b128 v[176:179], v163
	ds_read_b128 v[180:183], v163 offset:1024
	ds_read_b128 v[184:187], v163 offset:2048
	ds_read_b128 v[188:191], v163 offset:3072
	ds_read_b128 v[196:199], v162 offset:32768
	ds_read_b128 v[200:203], v162 offset:33792
	ds_read_b128 v[206:209], v162 offset:34816
	ds_read_b128 v[210:213], v162 offset:35840
	ds_read_b128 v[214:217], v162 offset:36864
	ds_read_b128 v[218:221], v162 offset:37888
	ds_read_b128 v[222:225], v162 offset:38912
	ds_read_b128 v[226:229], v162 offset:39936
	s_waitcnt vmcnt(8)
	s_waitcnt lgkmcnt(0)
	s_barrier
	s_setprio 1
	v_mfma_f32_16x16x32_bf16 v[126:129], v[152:155], v[196:199], v[126:129]
	v_mfma_f32_16x16x32_bf16 v[122:125], v[168:171], v[196:199], v[122:125]
	v_mfma_f32_16x16x32_bf16 v[110:113], v[152:155], v[206:209], v[110:113]
	v_mfma_f32_16x16x32_bf16 v[106:109], v[168:171], v[206:209], v[106:109]
	v_mfma_f32_16x16x32_bf16 v[94:97], v[152:155], v[214:217], v[94:97]
	v_mfma_f32_16x16x32_bf16 v[90:93], v[168:171], v[214:217], v[90:93]
	v_mfma_f32_16x16x32_bf16 v[78:81], v[152:155], v[222:225], v[78:81]
	v_mfma_f32_16x16x32_bf16 v[74:77], v[168:171], v[222:225], v[74:77]
	v_mfma_f32_16x16x32_bf16 v[126:129], v[164:167], v[200:203], v[126:129]
	v_mfma_f32_16x16x32_bf16 v[122:125], v[172:175], v[200:203], v[122:125]
	v_mfma_f32_16x16x32_bf16 v[110:113], v[164:167], v[210:213], v[110:113]
	v_mfma_f32_16x16x32_bf16 v[106:109], v[172:175], v[210:213], v[106:109]
	v_mfma_f32_16x16x32_bf16 v[94:97], v[164:167], v[218:221], v[94:97]
	v_mfma_f32_16x16x32_bf16 v[90:93], v[172:175], v[218:221], v[90:93]
	v_mfma_f32_16x16x32_bf16 v[78:81], v[164:167], v[226:229], v[78:81]
	v_mfma_f32_16x16x32_bf16 v[74:77], v[172:175], v[226:229], v[74:77]
	v_mfma_f32_16x16x32_bf16 v[118:121], v[176:179], v[196:199], v[118:121]
	v_mfma_f32_16x16x32_bf16 v[114:117], v[184:187], v[196:199], v[114:117]
	v_mfma_f32_16x16x32_bf16 v[102:105], v[176:179], v[206:209], v[102:105]
	v_mfma_f32_16x16x32_bf16 v[98:101], v[184:187], v[206:209], v[98:101]
	v_mfma_f32_16x16x32_bf16 v[86:89], v[176:179], v[214:217], v[86:89]
	v_mfma_f32_16x16x32_bf16 v[82:85], v[184:187], v[214:217], v[82:85]
	v_mfma_f32_16x16x32_bf16 v[70:73], v[176:179], v[222:225], v[70:73]
	v_mfma_f32_16x16x32_bf16 v[66:69], v[184:187], v[222:225], v[66:69]
	v_mfma_f32_16x16x32_bf16 v[118:121], v[180:183], v[200:203], v[118:121]
	v_mfma_f32_16x16x32_bf16 v[114:117], v[188:191], v[200:203], v[114:117]
	v_mfma_f32_16x16x32_bf16 v[102:105], v[180:183], v[210:213], v[102:105]
	v_mfma_f32_16x16x32_bf16 v[98:101], v[188:191], v[210:213], v[98:101]
	v_mfma_f32_16x16x32_bf16 v[86:89], v[180:183], v[218:221], v[86:89]
	v_mfma_f32_16x16x32_bf16 v[82:85], v[188:191], v[218:221], v[82:85]
	v_mfma_f32_16x16x32_bf16 v[70:73], v[180:183], v[226:229], v[70:73]
	v_mfma_f32_16x16x32_bf16 v[66:69], v[188:191], v[226:229], v[66:69]
	s_setprio 0
	s_barrier
	s_add_i32 s54, s83, s56
	v_lshl_add_u64 v[156:157], v[156:157], 0, s[18:19]
	s_mov_b32 m0, s54
	ds_read_b128 v[196:199], v162 offset:49152
	ds_read_b128 v[200:203], v162 offset:50176
	ds_read_b128 v[206:209], v162 offset:51200
	ds_read_b128 v[210:213], v162 offset:52224
	ds_read_b128 v[214:217], v162 offset:53248
	ds_read_b128 v[218:221], v162 offset:54272
	ds_read_b128 v[222:225], v162 offset:55296
	ds_read_b128 v[226:229], v162 offset:56320
	global_load_lds_dwordx4 v[156:157], off
	s_add_i32 m0, s54, 0x2000
	s_add_u32 s48, s48, 0x2b0080
	v_lshl_add_u64 v[156:157], v[192:193], 0, s[18:19]
	s_addc_u32 s49, s49, 0
	s_add_i32 s54, s84, s56
	global_load_lds_dwordx4 v[156:157], off
	v_lshl_add_u64 v[156:157], s[48:49], 0, v[134:135]
	s_mov_b32 m0, s54
	s_nop 0
	global_load_lds_dwordx4 v[156:157], off
	v_lshl_add_u64 v[156:157], s[48:49], 0, v[138:139]
	s_add_i32 m0, s54, 0x2000
	s_nop 0
	global_load_lds_dwordx4 v[156:157], off
	v_lshl_add_u64 v[156:157], v[230:231], 0, s[18:19]
	s_mov_b32 m0, s64
	s_nop 0
	global_load_lds_dwordx4 v[156:157], off
	v_lshl_add_u64 v[156:157], v[232:233], 0, s[18:19]
	s_mov_b32 m0, s65
	s_nop 0
	global_load_lds_dwordx4 v[156:157], off
	s_nop 0
	s_waitcnt vmcnt(8)
	s_waitcnt lgkmcnt(0)
	s_barrier
	s_setprio 1
	v_mfma_f32_16x16x32_bf16 v[62:65], v[152:155], v[196:199], v[62:65]
	v_mfma_f32_16x16x32_bf16 v[58:61], v[168:171], v[196:199], v[58:61]
	v_mfma_f32_16x16x32_bf16 v[46:49], v[152:155], v[206:209], v[46:49]
	v_mfma_f32_16x16x32_bf16 v[42:45], v[168:171], v[206:209], v[42:45]
	v_mfma_f32_16x16x32_bf16 v[30:33], v[152:155], v[214:217], v[30:33]
	v_mfma_f32_16x16x32_bf16 v[26:29], v[168:171], v[214:217], v[26:29]
	v_mfma_f32_16x16x32_bf16 v[14:17], v[152:155], v[222:225], v[14:17]
	v_mfma_f32_16x16x32_bf16 v[10:13], v[168:171], v[222:225], v[10:13]
	v_mfma_f32_16x16x32_bf16 v[62:65], v[164:167], v[200:203], v[62:65]
	v_mfma_f32_16x16x32_bf16 v[58:61], v[172:175], v[200:203], v[58:61]
	v_mfma_f32_16x16x32_bf16 v[46:49], v[164:167], v[210:213], v[46:49]
	v_mfma_f32_16x16x32_bf16 v[42:45], v[172:175], v[210:213], v[42:45]
	v_mfma_f32_16x16x32_bf16 v[30:33], v[164:167], v[218:221], v[30:33]
	v_mfma_f32_16x16x32_bf16 v[26:29], v[172:175], v[218:221], v[26:29]
	v_mfma_f32_16x16x32_bf16 v[14:17], v[164:167], v[226:229], v[14:17]
	v_mfma_f32_16x16x32_bf16 v[10:13], v[172:175], v[226:229], v[10:13]
	v_mfma_f32_16x16x32_bf16 v[54:57], v[176:179], v[196:199], v[54:57]
	v_mfma_f32_16x16x32_bf16 v[50:53], v[184:187], v[196:199], v[50:53]
	v_mfma_f32_16x16x32_bf16 v[38:41], v[176:179], v[206:209], v[38:41]
	v_mfma_f32_16x16x32_bf16 v[34:37], v[184:187], v[206:209], v[34:37]
	v_mfma_f32_16x16x32_bf16 v[22:25], v[176:179], v[214:217], v[22:25]
	v_mfma_f32_16x16x32_bf16 v[18:21], v[184:187], v[214:217], v[18:21]
	v_mfma_f32_16x16x32_bf16 v[6:9], v[176:179], v[222:225], v[6:9]
	v_mfma_f32_16x16x32_bf16 v[2:5], v[184:187], v[222:225], v[2:5]
	v_mfma_f32_16x16x32_bf16 v[54:57], v[180:183], v[200:203], v[54:57]
	v_mfma_f32_16x16x32_bf16 v[50:53], v[188:191], v[200:203], v[50:53]
	v_mfma_f32_16x16x32_bf16 v[38:41], v[180:183], v[210:213], v[38:41]
	v_mfma_f32_16x16x32_bf16 v[34:37], v[188:191], v[210:213], v[34:37]
	v_mfma_f32_16x16x32_bf16 v[22:25], v[180:183], v[218:221], v[22:25]
	v_mfma_f32_16x16x32_bf16 v[18:21], v[188:191], v[218:221], v[18:21]
	v_mfma_f32_16x16x32_bf16 v[6:9], v[180:183], v[226:229], v[6:9]
	v_mfma_f32_16x16x32_bf16 v[2:5], v[188:191], v[226:229], v[2:5]
	s_setprio 0
	s_barrier
	s_add_u32 s52, s52, 0x100
	s_addc_u32 s53, s53, 0
	s_add_u32 s80, s80, 0x100
	s_addc_u32 s81, s81, 0
	s_cmp_ge_i32 s82, s78
	s_mov_b32 s48, s82
	s_cbranch_scc0 .LBB0_1712
	s_and_b64 vcc, exec, s[20:21]
	s_cbranch_vccz .LBB0_1715
	s_barrier

.LBB0_1869:
	s_waitcnt vmcnt(0)
	s_add_i32 s55, s42, 2
	s_add_u32 s43, s8, 0xfff00080
	s_addc_u32 s46, s9, -1
	s_cmp_eq_u32 s48, s42
	s_cselect_b32 s42, s41, s49
	s_cselect_b32 s47, s31, s46
	s_cselect_b32 s46, s33, s43
	s_cselect_b32 s43, s35, s53
	v_lshl_add_u64 v[166:167], s[8:9], 0, v[150:151]
	s_add_i32 m0, s62, 0xc000
	s_nop 0
	global_load_lds_dwordx4 v[166:167], off
	v_lshl_add_u64 v[166:167], s[8:9], 0, v[152:153]
	s_add_i32 m0, s62, 0xe000
	s_nop 0
	global_load_lds_dwordx4 v[166:167], off
	ds_read_b128 v[162:165], v168
	ds_read_b128 v[172:175], v168 offset:1024
	ds_read_b128 v[176:179], v168 offset:2048
	ds_read_b128 v[180:183], v168 offset:3072
	ds_read_b128 v[184:187], v169
	ds_read_b128 v[188:191], v169 offset:1024
	ds_read_b128 v[196:199], v169 offset:2048
	ds_read_b128 v[200:203], v169 offset:3072
	ds_read_b128 v[206:209], v170
	ds_read_b128 v[210:213], v170 offset:1024
	ds_read_b128 v[214:217], v170 offset:2048
	ds_read_b128 v[218:221], v170 offset:3072
	ds_read_b128 v[222:225], v170 offset:4096
	ds_read_b128 v[226:229], v170 offset:5120
	ds_read_b128 v[230:233], v170 offset:6144
	ds_read_b128 v[234:237], v170 offset:7168
	s_nop 0
	s_waitcnt vmcnt(8)
	s_waitcnt lgkmcnt(0)
	s_barrier
	s_setprio 1
	v_mfma_f32_16x16x32_bf16 v[66:69], v[162:165], v[206:209], v[66:69]
	v_mfma_f32_16x16x32_bf16 v[62:65], v[176:179], v[206:209], v[62:65]
	v_mfma_f32_16x16x32_bf16 v[58:61], v[162:165], v[214:217], v[58:61]
	v_mfma_f32_16x16x32_bf16 v[54:57], v[176:179], v[214:217], v[54:57]
	v_mfma_f32_16x16x32_bf16 v[50:53], v[162:165], v[222:225], v[50:53]
	v_mfma_f32_16x16x32_bf16 v[46:49], v[176:179], v[222:225], v[46:49]
	v_mfma_f32_16x16x32_bf16 v[38:41], v[162:165], v[230:233], v[38:41]
	v_mfma_f32_16x16x32_bf16 v[30:33], v[176:179], v[230:233], v[30:33]
	v_mfma_f32_16x16x32_bf16 v[66:69], v[172:175], v[210:213], v[66:69]
	v_mfma_f32_16x16x32_bf16 v[62:65], v[180:183], v[210:213], v[62:65]
	v_mfma_f32_16x16x32_bf16 v[58:61], v[172:175], v[218:221], v[58:61]
	v_mfma_f32_16x16x32_bf16 v[54:57], v[180:183], v[218:221], v[54:57]
	v_mfma_f32_16x16x32_bf16 v[50:53], v[172:175], v[226:229], v[50:53]
	v_mfma_f32_16x16x32_bf16 v[46:49], v[180:183], v[226:229], v[46:49]
	v_mfma_f32_16x16x32_bf16 v[38:41], v[172:175], v[234:237], v[38:41]
	v_mfma_f32_16x16x32_bf16 v[30:33], v[180:183], v[234:237], v[30:33]
	v_mfma_f32_16x16x32_bf16 v[42:45], v[184:187], v[206:209], v[42:45]
	v_mfma_f32_16x16x32_bf16 v[34:37], v[196:199], v[206:209], v[34:37]
	v_mfma_f32_16x16x32_bf16 v[26:29], v[184:187], v[214:217], v[26:29]
	v_mfma_f32_16x16x32_bf16 v[22:25], v[196:199], v[214:217], v[22:25]
	v_mfma_f32_16x16x32_bf16 v[18:21], v[184:187], v[222:225], v[18:21]
	v_mfma_f32_16x16x32_bf16 v[14:17], v[196:199], v[222:225], v[14:17]
	v_mfma_f32_16x16x32_bf16 v[10:13], v[184:187], v[230:233], v[10:13]
	v_mfma_f32_16x16x32_bf16 v[6:9], v[196:199], v[230:233], v[6:9]
	v_mfma_f32_16x16x32_bf16 v[42:45], v[188:191], v[210:213], v[42:45]
	v_mfma_f32_16x16x32_bf16 v[34:37], v[200:203], v[210:213], v[34:37]
	v_mfma_f32_16x16x32_bf16 v[26:29], v[188:191], v[218:221], v[26:29]
	v_mfma_f32_16x16x32_bf16 v[22:25], v[200:203], v[218:221], v[22:25]
	v_mfma_f32_16x16x32_bf16 v[18:21], v[188:191], v[226:229], v[18:21]
	v_mfma_f32_16x16x32_bf16 v[14:17], v[200:203], v[226:229], v[14:17]
	v_mfma_f32_16x16x32_bf16 v[10:13], v[188:191], v[234:237], v[10:13]
	v_mfma_f32_16x16x32_bf16 v[6:9], v[200:203], v[234:237], v[6:9]
	s_setprio 0
	s_barrier
	s_add_i32 s80, s72, s61
	v_lshl_add_u64 v[166:167], s[42:43], 0, v[134:135]
	s_mov_b32 m0, s80
	ds_read_b128 v[206:209], v170 offset:16384
	ds_read_b128 v[210:213], v170 offset:17408
	ds_read_b128 v[214:217], v170 offset:18432
	ds_read_b128 v[218:221], v170 offset:19456
	ds_read_b128 v[222:225], v170 offset:20480
	ds_read_b128 v[226:229], v170 offset:21504
	ds_read_b128 v[230:233], v170 offset:22528
	ds_read_b128 v[234:237], v170 offset:23552
	global_load_lds_dwordx4 v[166:167], off
	s_add_i32 m0, s80, 0x2000
	s_add_u32 s80, s42, 0x100000
	v_lshl_add_u64 v[192:193], s[42:43], 0, v[138:139]
	s_addc_u32 s81, s43, 0
	s_add_i32 s82, s73, s61
	global_load_lds_dwordx4 v[192:193], off
	v_lshl_add_u64 v[238:239], s[80:81], 0, v[134:135]
	s_mov_b32 m0, s82
	v_lshl_add_u64 v[240:241], s[46:47], 0, v[136:137]
	global_load_lds_dwordx4 v[238:239], off
	v_lshl_add_u64 v[238:239], s[80:81], 0, v[138:139]
	s_add_i32 m0, s82, 0x2000
	s_nop 0
	global_load_lds_dwordx4 v[238:239], off
	v_lshl_add_u64 v[238:239], s[46:47], 0, v[132:133]
	s_mov_b32 m0, s62
	s_nop 0
	global_load_lds_dwordx4 v[238:239], off
	s_mov_b32 m0, s63
	s_nop 0
	global_load_lds_dwordx4 v[240:241], off
	s_waitcnt vmcnt(8)
	s_waitcnt lgkmcnt(0)
	s_barrier
	s_setprio 1
	v_mfma_f32_16x16x32_bf16 v[126:129], v[162:165], v[206:209], v[126:129]
	v_mfma_f32_16x16x32_bf16 v[122:125], v[176:179], v[206:209], v[122:125]
	v_mfma_f32_16x16x32_bf16 v[110:113], v[162:165], v[214:217], v[110:113]
	v_mfma_f32_16x16x32_bf16 v[106:109], v[176:179], v[214:217], v[106:109]
	v_mfma_f32_16x16x32_bf16 v[94:97], v[162:165], v[222:225], v[94:97]
	v_mfma_f32_16x16x32_bf16 v[90:93], v[176:179], v[222:225], v[90:93]
	v_mfma_f32_16x16x32_bf16 v[78:81], v[162:165], v[230:233], v[78:81]
	v_mfma_f32_16x16x32_bf16 v[74:77], v[176:179], v[230:233], v[74:77]
	v_mfma_f32_16x16x32_bf16 v[126:129], v[172:175], v[210:213], v[126:129]
	v_mfma_f32_16x16x32_bf16 v[122:125], v[180:183], v[210:213], v[122:125]
	v_mfma_f32_16x16x32_bf16 v[110:113], v[172:175], v[218:221], v[110:113]
	v_mfma_f32_16x16x32_bf16 v[106:109], v[180:183], v[218:221], v[106:109]
	v_mfma_f32_16x16x32_bf16 v[94:97], v[172:175], v[226:229], v[94:97]
	v_mfma_f32_16x16x32_bf16 v[90:93], v[180:183], v[226:229], v[90:93]
	v_mfma_f32_16x16x32_bf16 v[78:81], v[172:175], v[234:237], v[78:81]
	v_mfma_f32_16x16x32_bf16 v[74:77], v[180:183], v[234:237], v[74:77]
	v_mfma_f32_16x16x32_bf16 v[118:121], v[184:187], v[206:209], v[118:121]
	v_mfma_f32_16x16x32_bf16 v[114:117], v[196:199], v[206:209], v[114:117]
	v_mfma_f32_16x16x32_bf16 v[102:105], v[184:187], v[214:217], v[102:105]
	v_mfma_f32_16x16x32_bf16 v[98:101], v[196:199], v[214:217], v[98:101]
	v_mfma_f32_16x16x32_bf16 v[86:89], v[184:187], v[222:225], v[86:89]
	v_mfma_f32_16x16x32_bf16 v[82:85], v[196:199], v[222:225], v[82:85]
	v_mfma_f32_16x16x32_bf16 v[70:73], v[184:187], v[230:233], v[70:73]
	v_mfma_f32_16x16x32_bf16 v[2:5], v[196:199], v[230:233], v[2:5]
	v_mfma_f32_16x16x32_bf16 v[118:121], v[188:191], v[210:213], v[118:121]
	v_mfma_f32_16x16x32_bf16 v[114:117], v[200:203], v[210:213], v[114:117]
	v_mfma_f32_16x16x32_bf16 v[102:105], v[188:191], v[218:221], v[102:105]
	v_mfma_f32_16x16x32_bf16 v[98:101], v[200:203], v[218:221], v[98:101]
	v_mfma_f32_16x16x32_bf16 v[86:89], v[188:191], v[226:229], v[86:89]
	v_mfma_f32_16x16x32_bf16 v[82:85], v[200:203], v[226:229], v[82:85]
	v_mfma_f32_16x16x32_bf16 v[70:73], v[188:191], v[234:237], v[70:73]
	v_mfma_f32_16x16x32_bf16 v[2:5], v[200:203], v[234:237], v[2:5]
	s_setprio 0
	s_barrier
	s_add_u32 s46, s46, 0x100000
	s_addc_u32 s47, s47, 0
	s_mov_b32 m0, s64
	v_lshl_add_u64 v[242:243], s[46:47], 0, v[132:133]
	global_load_lds_dwordx4 v[242:243], off
	v_lshl_add_u64 v[242:243], s[46:47], 0, v[136:137]
	s_mov_b32 m0, s65
	s_nop 0
	global_load_lds_dwordx4 v[242:243], off
	s_add_i32 s80, 0, 0x18000
	s_add_i32 s81, 0, 0x1c000
	v_add_u32_e32 v180, s80, v131
	v_add_u32_e32 v200, s81, v131
	ds_read_b128 v[162:165], v180
	ds_read_b128 v[172:175], v180 offset:1024
	ds_read_b128 v[176:179], v180 offset:2048
	ds_read_b128 v[180:183], v180 offset:3072
	ds_read_b128 v[184:187], v200
	ds_read_b128 v[188:191], v200 offset:1024
	ds_read_b128 v[196:199], v200 offset:2048
	ds_read_b128 v[200:203], v200 offset:3072
	ds_read_b128 v[206:209], v170 offset:32768
	ds_read_b128 v[210:213], v170 offset:33792
	ds_read_b128 v[214:217], v170 offset:34816
	ds_read_b128 v[218:221], v170 offset:35840
	ds_read_b128 v[222:225], v170 offset:36864
	ds_read_b128 v[226:229], v170 offset:37888
	ds_read_b128 v[230:233], v170 offset:38912
	ds_read_b128 v[234:237], v170 offset:39936
	s_waitcnt vmcnt(8)
	s_waitcnt lgkmcnt(0)
	s_barrier
	s_setprio 1
	v_mfma_f32_16x16x32_bf16 v[66:69], v[162:165], v[206:209], v[66:69]
	v_mfma_f32_16x16x32_bf16 v[62:65], v[176:179], v[206:209], v[62:65]
	v_mfma_f32_16x16x32_bf16 v[58:61], v[162:165], v[214:217], v[58:61]
	v_mfma_f32_16x16x32_bf16 v[54:57], v[176:179], v[214:217], v[54:57]
	v_mfma_f32_16x16x32_bf16 v[50:53], v[162:165], v[222:225], v[50:53]
	v_mfma_f32_16x16x32_bf16 v[46:49], v[176:179], v[222:225], v[46:49]
	v_mfma_f32_16x16x32_bf16 v[38:41], v[162:165], v[230:233], v[38:41]
	v_mfma_f32_16x16x32_bf16 v[30:33], v[176:179], v[230:233], v[30:33]
	v_mfma_f32_16x16x32_bf16 v[66:69], v[172:175], v[210:213], v[66:69]
	v_mfma_f32_16x16x32_bf16 v[62:65], v[180:183], v[210:213], v[62:65]
	v_mfma_f32_16x16x32_bf16 v[58:61], v[172:175], v[218:221], v[58:61]
	v_mfma_f32_16x16x32_bf16 v[54:57], v[180:183], v[218:221], v[54:57]
	v_mfma_f32_16x16x32_bf16 v[50:53], v[172:175], v[226:229], v[50:53]
	v_mfma_f32_16x16x32_bf16 v[46:49], v[180:183], v[226:229], v[46:49]
	v_mfma_f32_16x16x32_bf16 v[38:41], v[172:175], v[234:237], v[38:41]
	v_mfma_f32_16x16x32_bf16 v[30:33], v[180:183], v[234:237], v[30:33]
	v_mfma_f32_16x16x32_bf16 v[42:45], v[184:187], v[206:209], v[42:45]
	v_mfma_f32_16x16x32_bf16 v[34:37], v[196:199], v[206:209], v[34:37]
	v_mfma_f32_16x16x32_bf16 v[26:29], v[184:187], v[214:217], v[26:29]
	v_mfma_f32_16x16x32_bf16 v[22:25], v[196:199], v[214:217], v[22:25]
	v_mfma_f32_16x16x32_bf16 v[18:21], v[184:187], v[222:225], v[18:21]
	v_mfma_f32_16x16x32_bf16 v[14:17], v[196:199], v[222:225], v[14:17]
	v_mfma_f32_16x16x32_bf16 v[10:13], v[184:187], v[230:233], v[10:13]
	v_mfma_f32_16x16x32_bf16 v[6:9], v[196:199], v[230:233], v[6:9]
	v_mfma_f32_16x16x32_bf16 v[42:45], v[188:191], v[210:213], v[42:45]
	v_mfma_f32_16x16x32_bf16 v[34:37], v[200:203], v[210:213], v[34:37]
	v_mfma_f32_16x16x32_bf16 v[26:29], v[188:191], v[218:221], v[26:29]
	v_mfma_f32_16x16x32_bf16 v[22:25], v[200:203], v[218:221], v[22:25]
	v_mfma_f32_16x16x32_bf16 v[18:21], v[188:191], v[226:229], v[18:21]
	v_mfma_f32_16x16x32_bf16 v[14:17], v[200:203], v[226:229], v[14:17]
	v_mfma_f32_16x16x32_bf16 v[10:13], v[188:191], v[234:237], v[10:13]
	v_mfma_f32_16x16x32_bf16 v[6:9], v[200:203], v[234:237], v[6:9]
	s_setprio 0
	s_barrier
	s_add_i32 s46, s80, s61
	v_lshl_add_u64 v[166:167], v[166:167], 0, s[18:19]
	s_mov_b32 m0, s46
	ds_read_b128 v[206:209], v170 offset:49152
	ds_read_b128 v[210:213], v170 offset:50176
	ds_read_b128 v[214:217], v170 offset:51200
	ds_read_b128 v[218:221], v170 offset:52224
	ds_read_b128 v[222:225], v170 offset:53248
	ds_read_b128 v[226:229], v170 offset:54272
	ds_read_b128 v[230:233], v170 offset:55296
	ds_read_b128 v[234:237], v170 offset:56320
	global_load_lds_dwordx4 v[166:167], off
	s_add_i32 m0, s46, 0x2000
	s_add_u32 s42, s42, 0x100080
	v_lshl_add_u64 v[166:167], v[192:193], 0, s[18:19]
	s_addc_u32 s43, s43, 0
	s_add_i32 s46, s81, s61
	global_load_lds_dwordx4 v[166:167], off
	v_lshl_add_u64 v[166:167], s[42:43], 0, v[134:135]
	s_mov_b32 m0, s46
	s_nop 0
	global_load_lds_dwordx4 v[166:167], off
	v_lshl_add_u64 v[166:167], s[42:43], 0, v[138:139]
	s_add_i32 m0, s46, 0x2000
	s_nop 0
	global_load_lds_dwordx4 v[166:167], off
	v_lshl_add_u64 v[166:167], v[238:239], 0, s[18:19]
	s_mov_b32 m0, s69
	s_nop 0
	global_load_lds_dwordx4 v[166:167], off
	v_lshl_add_u64 v[166:167], v[240:241], 0, s[18:19]
	s_mov_b32 m0, s70
	s_nop 0
	global_load_lds_dwordx4 v[166:167], off
	s_nop 0
	s_waitcnt vmcnt(8)
	s_waitcnt lgkmcnt(0)
	s_barrier
	s_setprio 1
	v_mfma_f32_16x16x32_bf16 v[126:129], v[162:165], v[206:209], v[126:129]
	v_mfma_f32_16x16x32_bf16 v[122:125], v[176:179], v[206:209], v[122:125]
	v_mfma_f32_16x16x32_bf16 v[110:113], v[162:165], v[214:217], v[110:113]
	v_mfma_f32_16x16x32_bf16 v[106:109], v[176:179], v[214:217], v[106:109]
	v_mfma_f32_16x16x32_bf16 v[94:97], v[162:165], v[222:225], v[94:97]
	v_mfma_f32_16x16x32_bf16 v[90:93], v[176:179], v[222:225], v[90:93]
	v_mfma_f32_16x16x32_bf16 v[78:81], v[162:165], v[230:233], v[78:81]
	v_mfma_f32_16x16x32_bf16 v[74:77], v[176:179], v[230:233], v[74:77]
	v_mfma_f32_16x16x32_bf16 v[126:129], v[172:175], v[210:213], v[126:129]
	v_mfma_f32_16x16x32_bf16 v[122:125], v[180:183], v[210:213], v[122:125]
	v_mfma_f32_16x16x32_bf16 v[110:113], v[172:175], v[218:221], v[110:113]
	v_mfma_f32_16x16x32_bf16 v[106:109], v[180:183], v[218:221], v[106:109]
	v_mfma_f32_16x16x32_bf16 v[94:97], v[172:175], v[226:229], v[94:97]
	v_mfma_f32_16x16x32_bf16 v[90:93], v[180:183], v[226:229], v[90:93]
	v_mfma_f32_16x16x32_bf16 v[78:81], v[172:175], v[234:237], v[78:81]
	v_mfma_f32_16x16x32_bf16 v[74:77], v[180:183], v[234:237], v[74:77]
	v_mfma_f32_16x16x32_bf16 v[118:121], v[184:187], v[206:209], v[118:121]
	v_mfma_f32_16x16x32_bf16 v[114:117], v[196:199], v[206:209], v[114:117]
	v_mfma_f32_16x16x32_bf16 v[102:105], v[184:187], v[214:217], v[102:105]
	v_mfma_f32_16x16x32_bf16 v[98:101], v[196:199], v[214:217], v[98:101]
	v_mfma_f32_16x16x32_bf16 v[86:89], v[184:187], v[222:225], v[86:89]
	v_mfma_f32_16x16x32_bf16 v[82:85], v[196:199], v[222:225], v[82:85]
	v_mfma_f32_16x16x32_bf16 v[70:73], v[184:187], v[230:233], v[70:73]
	v_mfma_f32_16x16x32_bf16 v[2:5], v[196:199], v[230:233], v[2:5]
	v_mfma_f32_16x16x32_bf16 v[118:121], v[188:191], v[210:213], v[118:121]
	v_mfma_f32_16x16x32_bf16 v[114:117], v[200:203], v[210:213], v[114:117]
	v_mfma_f32_16x16x32_bf16 v[102:105], v[188:191], v[218:221], v[102:105]
	v_mfma_f32_16x16x32_bf16 v[98:101], v[200:203], v[218:221], v[98:101]
	v_mfma_f32_16x16x32_bf16 v[86:89], v[188:191], v[226:229], v[86:89]
	v_mfma_f32_16x16x32_bf16 v[82:85], v[200:203], v[226:229], v[82:85]
	v_mfma_f32_16x16x32_bf16 v[70:73], v[188:191], v[234:237], v[70:73]
	v_mfma_f32_16x16x32_bf16 v[2:5], v[200:203], v[234:237], v[2:5]
	s_setprio 0
	s_barrier
	s_add_u32 s8, s8, 0x100
	s_addc_u32 s9, s9, 0
	s_add_u32 s49, s49, 0x100
	s_addc_u32 s53, s53, 0
	s_cmp_ge_i32 s55, s3
	s_mov_b32 s42, s55
	s_cbranch_scc0 .LBB0_1869
	s_and_b64 vcc, exec, s[20:21]
	s_cbranch_vccz .LBB0_1874
	s_barrier
	v_lshl_or_b32 v162, s40, 8, v141
	s_cmp_lt_i32 s10, 0
	s_mov_b64 s[8:9], -1
	s_cbranch_scc1 .LBB0_1875

.LBB0_3649:
	s_add_i32 s86, s48, 2
	s_add_u32 s49, s6, 0xfff00080
	s_addc_u32 s64, s7, -1
	s_cmp_eq_u32 s51, s48
	s_cselect_b32 s48, s58, s53
	s_cselect_b32 s65, s57, s64
	s_cselect_b32 s64, s56, s49
	s_cselect_b32 s49, s59, s55
	v_lshl_add_u64 v[192:193], s[6:7], 0, v[140:141]
	s_add_i32 m0, s61, 0xc000
	s_nop 0
	global_load_lds_dwordx4 v[192:193], off
	v_lshl_add_u64 v[192:193], s[6:7], 0, v[142:143]
	s_add_i32 m0, s61, 0xe000
	s_nop 0
	global_load_lds_dwordx4 v[192:193], off
	ds_read_b128 v[152:155], v162
	ds_read_b128 v[156:159], v162 offset:1024
	ds_read_b128 v[168:171], v162 offset:2048
	ds_read_b128 v[172:175], v162 offset:3072
	ds_read_b128 v[176:179], v163
	ds_read_b128 v[180:183], v163 offset:1024
	ds_read_b128 v[184:187], v163 offset:2048
	ds_read_b128 v[188:191], v163 offset:3072
	ds_read_b128 v[196:199], v164
	ds_read_b128 v[200:203], v164 offset:1024
	ds_read_b128 v[206:209], v164 offset:2048
	ds_read_b128 v[210:213], v164 offset:3072
	ds_read_b128 v[214:217], v164 offset:4096
	ds_read_b128 v[218:221], v164 offset:5120
	ds_read_b128 v[222:225], v164 offset:6144
	ds_read_b128 v[226:229], v164 offset:7168
	s_waitcnt vmcnt(8)
	s_waitcnt lgkmcnt(0)
	s_barrier
	s_setprio 1
	v_mfma_f32_16x16x32_bf16 v[126:129], v[152:155], v[196:199], v[126:129]
	v_mfma_f32_16x16x32_bf16 v[122:125], v[168:171], v[196:199], v[122:125]
	v_mfma_f32_16x16x32_bf16 v[110:113], v[152:155], v[206:209], v[110:113]
	v_mfma_f32_16x16x32_bf16 v[106:109], v[168:171], v[206:209], v[106:109]
	v_mfma_f32_16x16x32_bf16 v[94:97], v[152:155], v[214:217], v[94:97]
	v_mfma_f32_16x16x32_bf16 v[90:93], v[168:171], v[214:217], v[90:93]
	v_mfma_f32_16x16x32_bf16 v[78:81], v[152:155], v[222:225], v[78:81]
	v_mfma_f32_16x16x32_bf16 v[74:77], v[168:171], v[222:225], v[74:77]
	v_mfma_f32_16x16x32_bf16 v[126:129], v[156:159], v[200:203], v[126:129]
	v_mfma_f32_16x16x32_bf16 v[122:125], v[172:175], v[200:203], v[122:125]
	v_mfma_f32_16x16x32_bf16 v[110:113], v[156:159], v[210:213], v[110:113]
	v_mfma_f32_16x16x32_bf16 v[106:109], v[172:175], v[210:213], v[106:109]
	v_mfma_f32_16x16x32_bf16 v[94:97], v[156:159], v[218:221], v[94:97]
	v_mfma_f32_16x16x32_bf16 v[90:93], v[172:175], v[218:221], v[90:93]
	v_mfma_f32_16x16x32_bf16 v[78:81], v[156:159], v[226:229], v[78:81]
	v_mfma_f32_16x16x32_bf16 v[74:77], v[172:175], v[226:229], v[74:77]
	v_mfma_f32_16x16x32_bf16 v[118:121], v[176:179], v[196:199], v[118:121]
	v_mfma_f32_16x16x32_bf16 v[114:117], v[184:187], v[196:199], v[114:117]
	v_mfma_f32_16x16x32_bf16 v[102:105], v[176:179], v[206:209], v[102:105]
	v_mfma_f32_16x16x32_bf16 v[98:101], v[184:187], v[206:209], v[98:101]
	v_mfma_f32_16x16x32_bf16 v[86:89], v[176:179], v[214:217], v[86:89]
	v_mfma_f32_16x16x32_bf16 v[82:85], v[184:187], v[214:217], v[82:85]
	v_mfma_f32_16x16x32_bf16 v[70:73], v[176:179], v[222:225], v[70:73]
	v_mfma_f32_16x16x32_bf16 v[66:69], v[184:187], v[222:225], v[66:69]
	v_mfma_f32_16x16x32_bf16 v[118:121], v[180:183], v[200:203], v[118:121]
	v_mfma_f32_16x16x32_bf16 v[114:117], v[188:191], v[200:203], v[114:117]
	v_mfma_f32_16x16x32_bf16 v[102:105], v[180:183], v[210:213], v[102:105]
	v_mfma_f32_16x16x32_bf16 v[98:101], v[188:191], v[210:213], v[98:101]
	v_mfma_f32_16x16x32_bf16 v[86:89], v[180:183], v[218:221], v[86:89]
	v_mfma_f32_16x16x32_bf16 v[82:85], v[188:191], v[218:221], v[82:85]
	v_mfma_f32_16x16x32_bf16 v[70:73], v[180:183], v[226:229], v[70:73]
	v_mfma_f32_16x16x32_bf16 v[66:69], v[188:191], v[226:229], v[66:69]
	s_setprio 0
	s_barrier
	s_add_i32 s87, s75, s66
	v_lshl_add_u64 v[192:193], s[48:49], 0, v[134:135]
	s_mov_b32 m0, s87
	ds_read_b128 v[196:199], v164 offset:16384
	ds_read_b128 v[200:203], v164 offset:17408
	ds_read_b128 v[206:209], v164 offset:18432
	ds_read_b128 v[210:213], v164 offset:19456
	ds_read_b128 v[214:217], v164 offset:20480
	ds_read_b128 v[218:221], v164 offset:21504
	ds_read_b128 v[222:225], v164 offset:22528
	ds_read_b128 v[226:229], v164 offset:23552
	global_load_lds_dwordx4 v[192:193], off
	s_add_i32 m0, s87, 0x2000
	s_add_u32 s88, s48, 0x100000
	v_lshl_add_u64 v[230:231], s[48:49], 0, v[138:139]
	s_addc_u32 s89, s49, 0
	s_add_i32 s87, s76, s66
	global_load_lds_dwordx4 v[230:231], off
	v_lshl_add_u64 v[232:233], s[88:89], 0, v[134:135]
	s_mov_b32 m0, s87
	v_lshl_add_u64 v[234:235], s[64:65], 0, v[136:137]
	global_load_lds_dwordx4 v[232:233], off
	v_lshl_add_u64 v[232:233], s[88:89], 0, v[138:139]
	s_add_i32 m0, s87, 0x2000
	s_nop 0
	global_load_lds_dwordx4 v[232:233], off
	v_lshl_add_u64 v[232:233], s[64:65], 0, v[132:133]
	s_mov_b32 m0, s61
	s_nop 0
	global_load_lds_dwordx4 v[232:233], off
	s_mov_b32 m0, s63
	s_nop 0
	global_load_lds_dwordx4 v[234:235], off
	s_waitcnt vmcnt(8)
	s_waitcnt lgkmcnt(0)
	s_barrier
	s_setprio 1
	v_mfma_f32_16x16x32_bf16 v[62:65], v[152:155], v[196:199], v[62:65]
	v_mfma_f32_16x16x32_bf16 v[58:61], v[168:171], v[196:199], v[58:61]
	v_mfma_f32_16x16x32_bf16 v[46:49], v[152:155], v[206:209], v[46:49]
	v_mfma_f32_16x16x32_bf16 v[42:45], v[168:171], v[206:209], v[42:45]
	v_mfma_f32_16x16x32_bf16 v[30:33], v[152:155], v[214:217], v[30:33]
	v_mfma_f32_16x16x32_bf16 v[26:29], v[168:171], v[214:217], v[26:29]
	v_mfma_f32_16x16x32_bf16 v[14:17], v[152:155], v[222:225], v[14:17]
	v_mfma_f32_16x16x32_bf16 v[10:13], v[168:171], v[222:225], v[10:13]
	v_mfma_f32_16x16x32_bf16 v[62:65], v[156:159], v[200:203], v[62:65]
	v_mfma_f32_16x16x32_bf16 v[58:61], v[172:175], v[200:203], v[58:61]
	v_mfma_f32_16x16x32_bf16 v[46:49], v[156:159], v[210:213], v[46:49]
	v_mfma_f32_16x16x32_bf16 v[42:45], v[172:175], v[210:213], v[42:45]
	v_mfma_f32_16x16x32_bf16 v[30:33], v[156:159], v[218:221], v[30:33]
	v_mfma_f32_16x16x32_bf16 v[26:29], v[172:175], v[218:221], v[26:29]
	v_mfma_f32_16x16x32_bf16 v[14:17], v[156:159], v[226:229], v[14:17]
	v_mfma_f32_16x16x32_bf16 v[10:13], v[172:175], v[226:229], v[10:13]
	v_mfma_f32_16x16x32_bf16 v[54:57], v[176:179], v[196:199], v[54:57]
	v_mfma_f32_16x16x32_bf16 v[50:53], v[184:187], v[196:199], v[50:53]
	v_mfma_f32_16x16x32_bf16 v[38:41], v[176:179], v[206:209], v[38:41]
	v_mfma_f32_16x16x32_bf16 v[34:37], v[184:187], v[206:209], v[34:37]
	v_mfma_f32_16x16x32_bf16 v[22:25], v[176:179], v[214:217], v[22:25]
	v_mfma_f32_16x16x32_bf16 v[18:21], v[184:187], v[214:217], v[18:21]
	v_mfma_f32_16x16x32_bf16 v[6:9], v[176:179], v[222:225], v[6:9]
	v_mfma_f32_16x16x32_bf16 v[2:5], v[184:187], v[222:225], v[2:5]
	v_mfma_f32_16x16x32_bf16 v[54:57], v[180:183], v[200:203], v[54:57]
	v_mfma_f32_16x16x32_bf16 v[50:53], v[188:191], v[200:203], v[50:53]
	v_mfma_f32_16x16x32_bf16 v[38:41], v[180:183], v[210:213], v[38:41]
	v_mfma_f32_16x16x32_bf16 v[34:37], v[188:191], v[210:213], v[34:37]
	v_mfma_f32_16x16x32_bf16 v[22:25], v[180:183], v[218:221], v[22:25]
	v_mfma_f32_16x16x32_bf16 v[18:21], v[188:191], v[218:221], v[18:21]
	v_mfma_f32_16x16x32_bf16 v[6:9], v[180:183], v[226:229], v[6:9]
	v_mfma_f32_16x16x32_bf16 v[2:5], v[188:191], v[226:229], v[2:5]
	s_setprio 0
	s_barrier
	s_add_u32 s64, s64, 0x100000
	s_addc_u32 s65, s65, 0
	s_mov_b32 m0, s67
	v_lshl_add_u64 v[236:237], s[64:65], 0, v[132:133]
	global_load_lds_dwordx4 v[236:237], off
	v_lshl_add_u64 v[236:237], s[64:65], 0, v[136:137]
	s_mov_b32 m0, s68
	s_nop 0
	global_load_lds_dwordx4 v[236:237], off
	s_add_i32 s87, 0, 0x18000
	v_add_u32_e32 v167, s87, v160
	s_add_i32 s88, 0, 0x1c000
	ds_read_b128 v[152:155], v167
	ds_read_b128 v[156:159], v167 offset:1024
	ds_read_b128 v[168:171], v167 offset:2048
	ds_read_b128 v[172:175], v167 offset:3072
	v_add_u32_e32 v167, s88, v160
	ds_read_b128 v[176:179], v167
	ds_read_b128 v[180:183], v167 offset:1024
	ds_read_b128 v[184:187], v167 offset:2048
	ds_read_b128 v[188:191], v167 offset:3072
	ds_read_b128 v[196:199], v164 offset:32768
	ds_read_b128 v[200:203], v164 offset:33792
	ds_read_b128 v[206:209], v164 offset:34816
	ds_read_b128 v[210:213], v164 offset:35840
	ds_read_b128 v[214:217], v164 offset:36864
	ds_read_b128 v[218:221], v164 offset:37888
	ds_read_b128 v[222:225], v164 offset:38912
	ds_read_b128 v[226:229], v164 offset:39936
	s_waitcnt vmcnt(8)
	s_waitcnt lgkmcnt(0)
	s_barrier
	s_setprio 1
	v_mfma_f32_16x16x32_bf16 v[126:129], v[152:155], v[196:199], v[126:129]
	v_mfma_f32_16x16x32_bf16 v[122:125], v[168:171], v[196:199], v[122:125]
	v_mfma_f32_16x16x32_bf16 v[110:113], v[152:155], v[206:209], v[110:113]
	v_mfma_f32_16x16x32_bf16 v[106:109], v[168:171], v[206:209], v[106:109]
	v_mfma_f32_16x16x32_bf16 v[94:97], v[152:155], v[214:217], v[94:97]
	v_mfma_f32_16x16x32_bf16 v[90:93], v[168:171], v[214:217], v[90:93]
	v_mfma_f32_16x16x32_bf16 v[78:81], v[152:155], v[222:225], v[78:81]
	v_mfma_f32_16x16x32_bf16 v[74:77], v[168:171], v[222:225], v[74:77]
	v_mfma_f32_16x16x32_bf16 v[126:129], v[156:159], v[200:203], v[126:129]
	v_mfma_f32_16x16x32_bf16 v[122:125], v[172:175], v[200:203], v[122:125]
	v_mfma_f32_16x16x32_bf16 v[110:113], v[156:159], v[210:213], v[110:113]
	v_mfma_f32_16x16x32_bf16 v[106:109], v[172:175], v[210:213], v[106:109]
	v_mfma_f32_16x16x32_bf16 v[94:97], v[156:159], v[218:221], v[94:97]
	v_mfma_f32_16x16x32_bf16 v[90:93], v[172:175], v[218:221], v[90:93]
	v_mfma_f32_16x16x32_bf16 v[78:81], v[156:159], v[226:229], v[78:81]
	v_mfma_f32_16x16x32_bf16 v[74:77], v[172:175], v[226:229], v[74:77]
	v_mfma_f32_16x16x32_bf16 v[118:121], v[176:179], v[196:199], v[118:121]
	v_mfma_f32_16x16x32_bf16 v[114:117], v[184:187], v[196:199], v[114:117]
	v_mfma_f32_16x16x32_bf16 v[102:105], v[176:179], v[206:209], v[102:105]
	v_mfma_f32_16x16x32_bf16 v[98:101], v[184:187], v[206:209], v[98:101]
	v_mfma_f32_16x16x32_bf16 v[86:89], v[176:179], v[214:217], v[86:89]
	v_mfma_f32_16x16x32_bf16 v[82:85], v[184:187], v[214:217], v[82:85]
	v_mfma_f32_16x16x32_bf16 v[70:73], v[176:179], v[222:225], v[70:73]
	v_mfma_f32_16x16x32_bf16 v[66:69], v[184:187], v[222:225], v[66:69]
	v_mfma_f32_16x16x32_bf16 v[118:121], v[180:183], v[200:203], v[118:121]
	v_mfma_f32_16x16x32_bf16 v[114:117], v[188:191], v[200:203], v[114:117]
	v_mfma_f32_16x16x32_bf16 v[102:105], v[180:183], v[210:213], v[102:105]
	v_mfma_f32_16x16x32_bf16 v[98:101], v[188:191], v[210:213], v[98:101]
	v_mfma_f32_16x16x32_bf16 v[86:89], v[180:183], v[218:221], v[86:89]
	v_mfma_f32_16x16x32_bf16 v[82:85], v[188:191], v[218:221], v[82:85]
	v_mfma_f32_16x16x32_bf16 v[70:73], v[180:183], v[226:229], v[70:73]
	v_mfma_f32_16x16x32_bf16 v[66:69], v[188:191], v[226:229], v[66:69]
	s_setprio 0
	s_barrier
	s_add_i32 s64, s87, s66
	v_lshl_add_u64 v[192:193], v[192:193], 0, s[20:21]
	s_mov_b32 m0, s64
	ds_read_b128 v[196:199], v164 offset:49152
	ds_read_b128 v[200:203], v164 offset:50176
	ds_read_b128 v[206:209], v164 offset:51200
	ds_read_b128 v[210:213], v164 offset:52224
	ds_read_b128 v[214:217], v164 offset:53248
	ds_read_b128 v[218:221], v164 offset:54272
	ds_read_b128 v[222:225], v164 offset:55296
	ds_read_b128 v[226:229], v164 offset:56320
	global_load_lds_dwordx4 v[192:193], off
	s_add_i32 m0, s64, 0x2000
	s_add_u32 s48, s48, 0x100080
	v_lshl_add_u64 v[192:193], v[230:231], 0, s[20:21]
	s_addc_u32 s49, s49, 0
	s_add_i32 s64, s88, s66
	global_load_lds_dwordx4 v[192:193], off
	v_lshl_add_u64 v[192:193], s[48:49], 0, v[134:135]
	s_mov_b32 m0, s64
	s_nop 0
	global_load_lds_dwordx4 v[192:193], off
	v_lshl_add_u64 v[192:193], s[48:49], 0, v[138:139]
	s_add_i32 m0, s64, 0x2000
	s_nop 0
	global_load_lds_dwordx4 v[192:193], off
	v_lshl_add_u64 v[192:193], v[232:233], 0, s[20:21]
	s_mov_b32 m0, s72
	s_nop 0
	global_load_lds_dwordx4 v[192:193], off
	v_lshl_add_u64 v[192:193], v[234:235], 0, s[20:21]
	s_mov_b32 m0, s73
	s_nop 0
	global_load_lds_dwordx4 v[192:193], off
	s_nop 0
	s_waitcnt vmcnt(8)
	s_waitcnt lgkmcnt(0)
	s_barrier
	s_setprio 1
	v_mfma_f32_16x16x32_bf16 v[62:65], v[152:155], v[196:199], v[62:65]
	v_mfma_f32_16x16x32_bf16 v[58:61], v[168:171], v[196:199], v[58:61]
	v_mfma_f32_16x16x32_bf16 v[46:49], v[152:155], v[206:209], v[46:49]
	v_mfma_f32_16x16x32_bf16 v[42:45], v[168:171], v[206:209], v[42:45]
	v_mfma_f32_16x16x32_bf16 v[30:33], v[152:155], v[214:217], v[30:33]
	v_mfma_f32_16x16x32_bf16 v[26:29], v[168:171], v[214:217], v[26:29]
	v_mfma_f32_16x16x32_bf16 v[14:17], v[152:155], v[222:225], v[14:17]
	v_mfma_f32_16x16x32_bf16 v[10:13], v[168:171], v[222:225], v[10:13]
	v_mfma_f32_16x16x32_bf16 v[62:65], v[156:159], v[200:203], v[62:65]
	v_mfma_f32_16x16x32_bf16 v[58:61], v[172:175], v[200:203], v[58:61]
	v_mfma_f32_16x16x32_bf16 v[46:49], v[156:159], v[210:213], v[46:49]
	v_mfma_f32_16x16x32_bf16 v[42:45], v[172:175], v[210:213], v[42:45]
	v_mfma_f32_16x16x32_bf16 v[30:33], v[156:159], v[218:221], v[30:33]
	v_mfma_f32_16x16x32_bf16 v[26:29], v[172:175], v[218:221], v[26:29]
	v_mfma_f32_16x16x32_bf16 v[14:17], v[156:159], v[226:229], v[14:17]
	v_mfma_f32_16x16x32_bf16 v[10:13], v[172:175], v[226:229], v[10:13]
	v_mfma_f32_16x16x32_bf16 v[54:57], v[176:179], v[196:199], v[54:57]
	v_mfma_f32_16x16x32_bf16 v[50:53], v[184:187], v[196:199], v[50:53]
	v_mfma_f32_16x16x32_bf16 v[38:41], v[176:179], v[206:209], v[38:41]
	v_mfma_f32_16x16x32_bf16 v[34:37], v[184:187], v[206:209], v[34:37]
	v_mfma_f32_16x16x32_bf16 v[22:25], v[176:179], v[214:217], v[22:25]
	v_mfma_f32_16x16x32_bf16 v[18:21], v[184:187], v[214:217], v[18:21]
	v_mfma_f32_16x16x32_bf16 v[6:9], v[176:179], v[222:225], v[6:9]
	v_mfma_f32_16x16x32_bf16 v[2:5], v[184:187], v[222:225], v[2:5]
	v_mfma_f32_16x16x32_bf16 v[54:57], v[180:183], v[200:203], v[54:57]
	v_mfma_f32_16x16x32_bf16 v[50:53], v[188:191], v[200:203], v[50:53]
	v_mfma_f32_16x16x32_bf16 v[38:41], v[180:183], v[210:213], v[38:41]
	v_mfma_f32_16x16x32_bf16 v[34:37], v[188:191], v[210:213], v[34:37]
	v_mfma_f32_16x16x32_bf16 v[22:25], v[180:183], v[218:221], v[22:25]
	v_mfma_f32_16x16x32_bf16 v[18:21], v[188:191], v[218:221], v[18:21]
	v_mfma_f32_16x16x32_bf16 v[6:9], v[180:183], v[226:229], v[6:9]
	v_mfma_f32_16x16x32_bf16 v[2:5], v[188:191], v[226:229], v[2:5]
	s_setprio 0
	s_barrier
	s_add_u32 s6, s6, 0x100
	s_addc_u32 s7, s7, 0
	s_add_u32 s53, s53, 0x100
	s_addc_u32 s55, s55, 0
	s_cmp_ge_i32 s86, s85
	s_mov_b32 s48, s86
	s_cbranch_scc0 .LBB0_3649
	s_and_b64 vcc, exec, s[22:23]
	s_cbranch_vccz .LBB0_3652
	s_barrier

.LBB0_3789:
	s_add_i32 s63, s30, 2
	s_add_u32 s31, s28, 0xfff00080
	s_addc_u32 s34, s29, -1
	s_cmp_eq_u32 s60, s30
	s_cselect_b32 s30, s59, s61
	s_cselect_b32 s35, s19, s34
	s_cselect_b32 s34, s23, s31
	s_cselect_b32 s31, s21, s62
	v_lshl_add_u64 v[158:159], s[28:29], 0, v[148:149]
	s_add_i32 m0, s6, 0xc000
	s_nop 0
	global_load_lds_dwordx4 v[158:159], off
	v_lshl_add_u64 v[158:159], s[28:29], 0, v[150:151]
	s_add_i32 m0, s6, 0xe000
	s_nop 0
	global_load_lds_dwordx4 v[158:159], off
	ds_read_b128 v[162:165], v145
	ds_read_b128 v[166:169], v145 offset:1024
	ds_read_b128 v[170:173], v145 offset:2048
	ds_read_b128 v[174:177], v145 offset:3072
	ds_read_b128 v[178:181], v160
	ds_read_b128 v[182:185], v160 offset:1024
	ds_read_b128 v[186:189], v160 offset:2048
	ds_read_b128 v[190:193], v160 offset:3072
	ds_read_b128 v[196:199], v161
	ds_read_b128 v[200:203], v161 offset:1024
	ds_read_b128 v[206:209], v161 offset:2048
	ds_read_b128 v[210:213], v161 offset:3072
	ds_read_b128 v[214:217], v161 offset:4096
	ds_read_b128 v[218:221], v161 offset:5120
	ds_read_b128 v[222:225], v161 offset:6144
	ds_read_b128 v[226:229], v161 offset:7168
	s_nop 0
	s_waitcnt vmcnt(8)
	s_waitcnt lgkmcnt(0)
	s_barrier
	s_setprio 1
	v_mfma_f32_16x16x32_bf16 v[126:129], v[162:165], v[196:199], v[126:129]
	v_mfma_f32_16x16x32_bf16 v[122:125], v[170:173], v[196:199], v[122:125]
	v_mfma_f32_16x16x32_bf16 v[118:121], v[162:165], v[206:209], v[118:121]
	v_mfma_f32_16x16x32_bf16 v[114:117], v[170:173], v[206:209], v[114:117]
	v_mfma_f32_16x16x32_bf16 v[102:105], v[162:165], v[214:217], v[102:105]
	v_mfma_f32_16x16x32_bf16 v[98:101], v[170:173], v[214:217], v[98:101]
	v_mfma_f32_16x16x32_bf16 v[42:45], v[162:165], v[222:225], v[42:45]
	v_mfma_f32_16x16x32_bf16 v[34:37], v[170:173], v[222:225], v[34:37]
	v_mfma_f32_16x16x32_bf16 v[126:129], v[166:169], v[200:203], v[126:129]
	v_mfma_f32_16x16x32_bf16 v[122:125], v[174:177], v[200:203], v[122:125]
	v_mfma_f32_16x16x32_bf16 v[118:121], v[166:169], v[210:213], v[118:121]
	v_mfma_f32_16x16x32_bf16 v[114:117], v[174:177], v[210:213], v[114:117]
	v_mfma_f32_16x16x32_bf16 v[102:105], v[166:169], v[218:221], v[102:105]
	v_mfma_f32_16x16x32_bf16 v[98:101], v[174:177], v[218:221], v[98:101]
	v_mfma_f32_16x16x32_bf16 v[42:45], v[166:169], v[226:229], v[42:45]
	v_mfma_f32_16x16x32_bf16 v[34:37], v[174:177], v[226:229], v[34:37]
	v_mfma_f32_16x16x32_bf16 v[110:113], v[178:181], v[196:199], v[110:113]
	v_mfma_f32_16x16x32_bf16 v[106:109], v[186:189], v[196:199], v[106:109]
	v_mfma_f32_16x16x32_bf16 v[94:97], v[178:181], v[206:209], v[94:97]
	v_mfma_f32_16x16x32_bf16 v[90:93], v[186:189], v[206:209], v[90:93]
	v_mfma_f32_16x16x32_bf16 v[86:89], v[178:181], v[214:217], v[86:89]
	v_mfma_f32_16x16x32_bf16 v[82:85], v[186:189], v[214:217], v[82:85]
	v_mfma_f32_16x16x32_bf16 v[30:33], v[178:181], v[222:225], v[30:33]
	v_mfma_f32_16x16x32_bf16 v[26:29], v[186:189], v[222:225], v[26:29]
	v_mfma_f32_16x16x32_bf16 v[110:113], v[182:185], v[200:203], v[110:113]
	v_mfma_f32_16x16x32_bf16 v[106:109], v[190:193], v[200:203], v[106:109]
	v_mfma_f32_16x16x32_bf16 v[94:97], v[182:185], v[210:213], v[94:97]
	v_mfma_f32_16x16x32_bf16 v[90:93], v[190:193], v[210:213], v[90:93]
	v_mfma_f32_16x16x32_bf16 v[86:89], v[182:185], v[218:221], v[86:89]
	v_mfma_f32_16x16x32_bf16 v[82:85], v[190:193], v[218:221], v[82:85]
	v_mfma_f32_16x16x32_bf16 v[30:33], v[182:185], v[226:229], v[30:33]
	v_mfma_f32_16x16x32_bf16 v[26:29], v[190:193], v[226:229], v[26:29]
	s_setprio 0
	s_barrier
	s_add_i32 s64, s54, s40
	v_lshl_add_u64 v[158:159], s[30:31], 0, v[134:135]
	s_mov_b32 m0, s64
	ds_read_b128 v[196:199], v161 offset:16384
	ds_read_b128 v[200:203], v161 offset:17408
	ds_read_b128 v[206:209], v161 offset:18432
	ds_read_b128 v[210:213], v161 offset:19456
	ds_read_b128 v[214:217], v161 offset:20480
	ds_read_b128 v[218:221], v161 offset:21504
	ds_read_b128 v[222:225], v161 offset:22528
	ds_read_b128 v[226:229], v161 offset:23552
	global_load_lds_dwordx4 v[158:159], off
	s_add_i32 m0, s64, 0x2000
	s_add_u32 s64, s30, 0x100000
	v_lshl_add_u64 v[230:231], s[30:31], 0, v[132:133]
	s_addc_u32 s65, s31, 0
	s_add_i32 s66, s55, s40
	global_load_lds_dwordx4 v[230:231], off
	v_lshl_add_u64 v[232:233], s[64:65], 0, v[134:135]
	s_mov_b32 m0, s66
	v_lshl_add_u64 v[234:235], s[34:35], 0, v[132:133]
	global_load_lds_dwordx4 v[232:233], off
	v_lshl_add_u64 v[232:233], s[64:65], 0, v[132:133]
	s_add_i32 m0, s66, 0x2000
	s_nop 0
	global_load_lds_dwordx4 v[232:233], off
	v_lshl_add_u64 v[232:233], s[34:35], 0, v[134:135]
	s_mov_b32 m0, s6
	s_nop 0
	global_load_lds_dwordx4 v[232:233], off
	s_mov_b32 m0, s13
	s_nop 0
	global_load_lds_dwordx4 v[234:235], off
	s_waitcnt vmcnt(8)
	s_waitcnt lgkmcnt(0)
	s_barrier
	s_setprio 1
	v_mfma_f32_16x16x32_bf16 v[78:81], v[162:165], v[196:199], v[78:81]
	v_mfma_f32_16x16x32_bf16 v[74:77], v[170:173], v[196:199], v[74:77]
	v_mfma_f32_16x16x32_bf16 v[70:73], v[162:165], v[206:209], v[70:73]
	v_mfma_f32_16x16x32_bf16 v[66:69], v[170:173], v[206:209], v[66:69]
	v_mfma_f32_16x16x32_bf16 v[54:57], v[162:165], v[214:217], v[54:57]
	v_mfma_f32_16x16x32_bf16 v[50:53], v[170:173], v[214:217], v[50:53]
	v_mfma_f32_16x16x32_bf16 v[14:17], v[162:165], v[222:225], v[14:17]
	v_mfma_f32_16x16x32_bf16 v[10:13], v[170:173], v[222:225], v[10:13]
	v_mfma_f32_16x16x32_bf16 v[78:81], v[166:169], v[200:203], v[78:81]
	v_mfma_f32_16x16x32_bf16 v[74:77], v[174:177], v[200:203], v[74:77]
	v_mfma_f32_16x16x32_bf16 v[70:73], v[166:169], v[210:213], v[70:73]
	v_mfma_f32_16x16x32_bf16 v[66:69], v[174:177], v[210:213], v[66:69]
	v_mfma_f32_16x16x32_bf16 v[54:57], v[166:169], v[218:221], v[54:57]
	v_mfma_f32_16x16x32_bf16 v[50:53], v[174:177], v[218:221], v[50:53]
	v_mfma_f32_16x16x32_bf16 v[14:17], v[166:169], v[226:229], v[14:17]
	v_mfma_f32_16x16x32_bf16 v[10:13], v[174:177], v[226:229], v[10:13]
	v_mfma_f32_16x16x32_bf16 v[62:65], v[178:181], v[196:199], v[62:65]
	v_mfma_f32_16x16x32_bf16 v[58:61], v[186:189], v[196:199], v[58:61]
	v_mfma_f32_16x16x32_bf16 v[46:49], v[178:181], v[206:209], v[46:49]
	v_mfma_f32_16x16x32_bf16 v[38:41], v[186:189], v[206:209], v[38:41]
	v_mfma_f32_16x16x32_bf16 v[22:25], v[178:181], v[214:217], v[22:25]
	v_mfma_f32_16x16x32_bf16 v[18:21], v[186:189], v[214:217], v[18:21]
	v_mfma_f32_16x16x32_bf16 v[6:9], v[178:181], v[222:225], v[6:9]
	v_mfma_f32_16x16x32_bf16 v[2:5], v[186:189], v[222:225], v[2:5]
	v_mfma_f32_16x16x32_bf16 v[62:65], v[182:185], v[200:203], v[62:65]
	v_mfma_f32_16x16x32_bf16 v[58:61], v[190:193], v[200:203], v[58:61]
	v_mfma_f32_16x16x32_bf16 v[46:49], v[182:185], v[210:213], v[46:49]
	v_mfma_f32_16x16x32_bf16 v[38:41], v[190:193], v[210:213], v[38:41]
	v_mfma_f32_16x16x32_bf16 v[22:25], v[182:185], v[218:221], v[22:25]
	v_mfma_f32_16x16x32_bf16 v[18:21], v[190:193], v[218:221], v[18:21]
	v_mfma_f32_16x16x32_bf16 v[6:9], v[182:185], v[226:229], v[6:9]
	v_mfma_f32_16x16x32_bf16 v[2:5], v[190:193], v[226:229], v[2:5]
	s_setprio 0
	s_barrier
	s_add_u32 s34, s34, 0x100000
	s_addc_u32 s35, s35, 0
	s_mov_b32 m0, s43
	v_lshl_add_u64 v[236:237], s[34:35], 0, v[134:135]
	global_load_lds_dwordx4 v[236:237], off
	v_lshl_add_u64 v[236:237], s[34:35], 0, v[132:133]
	s_mov_b32 m0, s45
	s_nop 0
	global_load_lds_dwordx4 v[236:237], off
	s_add_i32 s64, 0, 0x18000
	s_add_i32 s65, 0, 0x1c000
	v_add_u32_e32 v174, s64, v131
	v_add_u32_e32 v190, s65, v131
	ds_read_b128 v[162:165], v174
	ds_read_b128 v[166:169], v174 offset:1024
	ds_read_b128 v[170:173], v174 offset:2048
	ds_read_b128 v[174:177], v174 offset:3072
	ds_read_b128 v[178:181], v190
	ds_read_b128 v[182:185], v190 offset:1024
	ds_read_b128 v[186:189], v190 offset:2048
	ds_read_b128 v[190:193], v190 offset:3072
	ds_read_b128 v[196:199], v161 offset:32768
	ds_read_b128 v[200:203], v161 offset:33792
	ds_read_b128 v[206:209], v161 offset:34816
	ds_read_b128 v[210:213], v161 offset:35840
	ds_read_b128 v[214:217], v161 offset:36864
	ds_read_b128 v[218:221], v161 offset:37888
	ds_read_b128 v[222:225], v161 offset:38912
	ds_read_b128 v[226:229], v161 offset:39936
	s_waitcnt vmcnt(8)
	s_waitcnt lgkmcnt(0)
	s_barrier
	s_setprio 1
	v_mfma_f32_16x16x32_bf16 v[126:129], v[162:165], v[196:199], v[126:129]
	v_mfma_f32_16x16x32_bf16 v[122:125], v[170:173], v[196:199], v[122:125]
	v_mfma_f32_16x16x32_bf16 v[118:121], v[162:165], v[206:209], v[118:121]
	v_mfma_f32_16x16x32_bf16 v[114:117], v[170:173], v[206:209], v[114:117]
	v_mfma_f32_16x16x32_bf16 v[102:105], v[162:165], v[214:217], v[102:105]
	v_mfma_f32_16x16x32_bf16 v[98:101], v[170:173], v[214:217], v[98:101]
	v_mfma_f32_16x16x32_bf16 v[42:45], v[162:165], v[222:225], v[42:45]
	v_mfma_f32_16x16x32_bf16 v[34:37], v[170:173], v[222:225], v[34:37]
	v_mfma_f32_16x16x32_bf16 v[126:129], v[166:169], v[200:203], v[126:129]
	v_mfma_f32_16x16x32_bf16 v[122:125], v[174:177], v[200:203], v[122:125]
	v_mfma_f32_16x16x32_bf16 v[118:121], v[166:169], v[210:213], v[118:121]
	v_mfma_f32_16x16x32_bf16 v[114:117], v[174:177], v[210:213], v[114:117]
	v_mfma_f32_16x16x32_bf16 v[102:105], v[166:169], v[218:221], v[102:105]
	v_mfma_f32_16x16x32_bf16 v[98:101], v[174:177], v[218:221], v[98:101]
	v_mfma_f32_16x16x32_bf16 v[42:45], v[166:169], v[226:229], v[42:45]
	v_mfma_f32_16x16x32_bf16 v[34:37], v[174:177], v[226:229], v[34:37]
	v_mfma_f32_16x16x32_bf16 v[110:113], v[178:181], v[196:199], v[110:113]
	v_mfma_f32_16x16x32_bf16 v[106:109], v[186:189], v[196:199], v[106:109]
	v_mfma_f32_16x16x32_bf16 v[94:97], v[178:181], v[206:209], v[94:97]
	v_mfma_f32_16x16x32_bf16 v[90:93], v[186:189], v[206:209], v[90:93]
	v_mfma_f32_16x16x32_bf16 v[86:89], v[178:181], v[214:217], v[86:89]
	v_mfma_f32_16x16x32_bf16 v[82:85], v[186:189], v[214:217], v[82:85]
	v_mfma_f32_16x16x32_bf16 v[30:33], v[178:181], v[222:225], v[30:33]
	v_mfma_f32_16x16x32_bf16 v[26:29], v[186:189], v[222:225], v[26:29]
	v_mfma_f32_16x16x32_bf16 v[110:113], v[182:185], v[200:203], v[110:113]
	v_mfma_f32_16x16x32_bf16 v[106:109], v[190:193], v[200:203], v[106:109]
	v_mfma_f32_16x16x32_bf16 v[94:97], v[182:185], v[210:213], v[94:97]
	v_mfma_f32_16x16x32_bf16 v[90:93], v[190:193], v[210:213], v[90:93]
	v_mfma_f32_16x16x32_bf16 v[86:89], v[182:185], v[218:221], v[86:89]
	v_mfma_f32_16x16x32_bf16 v[82:85], v[190:193], v[218:221], v[82:85]
	v_mfma_f32_16x16x32_bf16 v[30:33], v[182:185], v[226:229], v[30:33]
	v_mfma_f32_16x16x32_bf16 v[26:29], v[190:193], v[226:229], v[26:29]
	s_setprio 0
	s_barrier
	s_add_i32 s34, s64, s40
	v_lshl_add_u64 v[158:159], v[158:159], 0, s[10:11]
	s_mov_b32 m0, s34
	ds_read_b128 v[196:199], v161 offset:49152
	ds_read_b128 v[200:203], v161 offset:50176
	ds_read_b128 v[206:209], v161 offset:51200
	ds_read_b128 v[210:213], v161 offset:52224
	ds_read_b128 v[214:217], v161 offset:53248
	ds_read_b128 v[218:221], v161 offset:54272
	ds_read_b128 v[222:225], v161 offset:55296
	ds_read_b128 v[226:229], v161 offset:56320
	global_load_lds_dwordx4 v[158:159], off
	s_add_i32 m0, s34, 0x2000
	s_add_u32 s30, s30, 0x100080
	v_lshl_add_u64 v[158:159], v[230:231], 0, s[10:11]
	s_addc_u32 s31, s31, 0
	s_add_i32 s34, s65, s40
	global_load_lds_dwordx4 v[158:159], off
	v_lshl_add_u64 v[158:159], s[30:31], 0, v[134:135]
	s_mov_b32 m0, s34
	s_nop 0
	global_load_lds_dwordx4 v[158:159], off
	v_lshl_add_u64 v[158:159], s[30:31], 0, v[132:133]
	s_add_i32 m0, s34, 0x2000
	s_nop 0
	global_load_lds_dwordx4 v[158:159], off
	v_lshl_add_u64 v[158:159], v[232:233], 0, s[10:11]
	s_mov_b32 m0, s50
	s_nop 0
	global_load_lds_dwordx4 v[158:159], off
	v_lshl_add_u64 v[158:159], v[234:235], 0, s[10:11]
	s_mov_b32 m0, s51
	s_nop 0
	global_load_lds_dwordx4 v[158:159], off
	s_nop 0
	s_waitcnt vmcnt(8)
	s_waitcnt lgkmcnt(0)
	s_barrier
	s_setprio 1
	v_mfma_f32_16x16x32_bf16 v[78:81], v[162:165], v[196:199], v[78:81]
	v_mfma_f32_16x16x32_bf16 v[74:77], v[170:173], v[196:199], v[74:77]
	v_mfma_f32_16x16x32_bf16 v[70:73], v[162:165], v[206:209], v[70:73]
	v_mfma_f32_16x16x32_bf16 v[66:69], v[170:173], v[206:209], v[66:69]
	v_mfma_f32_16x16x32_bf16 v[54:57], v[162:165], v[214:217], v[54:57]
	v_mfma_f32_16x16x32_bf16 v[50:53], v[170:173], v[214:217], v[50:53]
	v_mfma_f32_16x16x32_bf16 v[14:17], v[162:165], v[222:225], v[14:17]
	v_mfma_f32_16x16x32_bf16 v[10:13], v[170:173], v[222:225], v[10:13]
	v_mfma_f32_16x16x32_bf16 v[78:81], v[166:169], v[200:203], v[78:81]
	v_mfma_f32_16x16x32_bf16 v[74:77], v[174:177], v[200:203], v[74:77]
	v_mfma_f32_16x16x32_bf16 v[70:73], v[166:169], v[210:213], v[70:73]
	v_mfma_f32_16x16x32_bf16 v[66:69], v[174:177], v[210:213], v[66:69]
	v_mfma_f32_16x16x32_bf16 v[54:57], v[166:169], v[218:221], v[54:57]
	v_mfma_f32_16x16x32_bf16 v[50:53], v[174:177], v[218:221], v[50:53]
	v_mfma_f32_16x16x32_bf16 v[14:17], v[166:169], v[226:229], v[14:17]
	v_mfma_f32_16x16x32_bf16 v[10:13], v[174:177], v[226:229], v[10:13]
	v_mfma_f32_16x16x32_bf16 v[62:65], v[178:181], v[196:199], v[62:65]
	v_mfma_f32_16x16x32_bf16 v[58:61], v[186:189], v[196:199], v[58:61]
	v_mfma_f32_16x16x32_bf16 v[46:49], v[178:181], v[206:209], v[46:49]
	v_mfma_f32_16x16x32_bf16 v[38:41], v[186:189], v[206:209], v[38:41]
	v_mfma_f32_16x16x32_bf16 v[22:25], v[178:181], v[214:217], v[22:25]
	v_mfma_f32_16x16x32_bf16 v[18:21], v[186:189], v[214:217], v[18:21]
	v_mfma_f32_16x16x32_bf16 v[6:9], v[178:181], v[222:225], v[6:9]
	v_mfma_f32_16x16x32_bf16 v[2:5], v[186:189], v[222:225], v[2:5]
	v_mfma_f32_16x16x32_bf16 v[62:65], v[182:185], v[200:203], v[62:65]
	v_mfma_f32_16x16x32_bf16 v[58:61], v[190:193], v[200:203], v[58:61]
	v_mfma_f32_16x16x32_bf16 v[46:49], v[182:185], v[210:213], v[46:49]
	v_mfma_f32_16x16x32_bf16 v[38:41], v[190:193], v[210:213], v[38:41]
	v_mfma_f32_16x16x32_bf16 v[22:25], v[182:185], v[218:221], v[22:25]
	v_mfma_f32_16x16x32_bf16 v[18:21], v[190:193], v[218:221], v[18:21]
	v_mfma_f32_16x16x32_bf16 v[6:9], v[182:185], v[226:229], v[6:9]
	v_mfma_f32_16x16x32_bf16 v[2:5], v[190:193], v[226:229], v[2:5]
	s_setprio 0
	s_barrier
	s_add_u32 s28, s28, 0x100
	s_addc_u32 s29, s29, 0
	s_add_u32 s61, s61, 0x100
	s_addc_u32 s62, s62, 0
	s_cmp_ge_i32 s63, s58
	s_mov_b32 s30, s63
	s_cbranch_scc0 .LBB0_3789
	s_and_b64 vcc, exec, s[16:17]
	s_cbranch_vccz .LBB0_3792
	s_barrier

.LBB0_3983:
	s_add_i32 s80, s48, 2
	s_add_u32 s49, s58, 0xfffe0080
	s_addc_u32 s60, s59, -1
	s_cmp_eq_u32 s43, s48
	s_cselect_b32 s48, s52, s47
	s_cselect_b32 s61, s5, s60
	s_cselect_b32 s60, s4, s49
	s_cselect_b32 s49, s53, s51
	v_lshl_add_u64 v[156:157], s[58:59], 0, v[140:141]
	s_add_i32 m0, s55, 0xc000
	s_nop 0
	global_load_lds_dwordx4 v[156:157], off
	v_lshl_add_u64 v[156:157], s[58:59], 0, v[142:143]
	s_add_i32 m0, s55, 0xe000
	s_nop 0
	global_load_lds_dwordx4 v[156:157], off
	ds_read_b128 v[152:155], v160
	ds_read_b128 v[164:167], v160 offset:1024
	ds_read_b128 v[168:171], v160 offset:2048
	ds_read_b128 v[172:175], v160 offset:3072
	ds_read_b128 v[176:179], v161
	ds_read_b128 v[180:183], v161 offset:1024
	ds_read_b128 v[184:187], v161 offset:2048
	ds_read_b128 v[188:191], v161 offset:3072
	ds_read_b128 v[196:199], v162
	ds_read_b128 v[200:203], v162 offset:1024
	ds_read_b128 v[204:207], v162 offset:2048
	ds_read_b128 v[208:211], v162 offset:3072
	ds_read_b128 v[212:215], v162 offset:4096
	ds_read_b128 v[216:219], v162 offset:5120
	ds_read_b128 v[220:223], v162 offset:6144
	ds_read_b128 v[224:227], v162 offset:7168
	s_nop 0
	s_waitcnt vmcnt(8)
	s_waitcnt lgkmcnt(0)
	s_barrier
	s_setprio 1
	v_mfma_f32_16x16x32_bf16 v[126:129], v[152:155], v[196:199], v[126:129]
	v_mfma_f32_16x16x32_bf16 v[122:125], v[168:171], v[196:199], v[122:125]
	v_mfma_f32_16x16x32_bf16 v[110:113], v[152:155], v[204:207], v[110:113]
	v_mfma_f32_16x16x32_bf16 v[106:109], v[168:171], v[204:207], v[106:109]
	v_mfma_f32_16x16x32_bf16 v[94:97], v[152:155], v[212:215], v[94:97]
	v_mfma_f32_16x16x32_bf16 v[90:93], v[168:171], v[212:215], v[90:93]
	v_mfma_f32_16x16x32_bf16 v[78:81], v[152:155], v[220:223], v[78:81]
	v_mfma_f32_16x16x32_bf16 v[74:77], v[168:171], v[220:223], v[74:77]
	v_mfma_f32_16x16x32_bf16 v[126:129], v[164:167], v[200:203], v[126:129]
	v_mfma_f32_16x16x32_bf16 v[122:125], v[172:175], v[200:203], v[122:125]
	v_mfma_f32_16x16x32_bf16 v[110:113], v[164:167], v[208:211], v[110:113]
	v_mfma_f32_16x16x32_bf16 v[106:109], v[172:175], v[208:211], v[106:109]
	v_mfma_f32_16x16x32_bf16 v[94:97], v[164:167], v[216:219], v[94:97]
	v_mfma_f32_16x16x32_bf16 v[90:93], v[172:175], v[216:219], v[90:93]
	v_mfma_f32_16x16x32_bf16 v[78:81], v[164:167], v[224:227], v[78:81]
	v_mfma_f32_16x16x32_bf16 v[74:77], v[172:175], v[224:227], v[74:77]
	v_mfma_f32_16x16x32_bf16 v[118:121], v[176:179], v[196:199], v[118:121]
	v_mfma_f32_16x16x32_bf16 v[114:117], v[184:187], v[196:199], v[114:117]
	v_mfma_f32_16x16x32_bf16 v[102:105], v[176:179], v[204:207], v[102:105]
	v_mfma_f32_16x16x32_bf16 v[98:101], v[184:187], v[204:207], v[98:101]
	v_mfma_f32_16x16x32_bf16 v[86:89], v[176:179], v[212:215], v[86:89]
	v_mfma_f32_16x16x32_bf16 v[82:85], v[184:187], v[212:215], v[82:85]
	v_mfma_f32_16x16x32_bf16 v[70:73], v[176:179], v[220:223], v[70:73]
	v_mfma_f32_16x16x32_bf16 v[66:69], v[184:187], v[220:223], v[66:69]
	v_mfma_f32_16x16x32_bf16 v[118:121], v[180:183], v[200:203], v[118:121]
	v_mfma_f32_16x16x32_bf16 v[114:117], v[188:191], v[200:203], v[114:117]
	v_mfma_f32_16x16x32_bf16 v[102:105], v[180:183], v[208:211], v[102:105]
	v_mfma_f32_16x16x32_bf16 v[98:101], v[188:191], v[208:211], v[98:101]
	v_mfma_f32_16x16x32_bf16 v[86:89], v[180:183], v[216:219], v[86:89]
	v_mfma_f32_16x16x32_bf16 v[82:85], v[188:191], v[216:219], v[82:85]
	v_mfma_f32_16x16x32_bf16 v[70:73], v[180:183], v[224:227], v[70:73]
	v_mfma_f32_16x16x32_bf16 v[66:69], v[188:191], v[224:227], v[66:69]
	s_setprio 0
	s_barrier
	s_add_i32 s81, s71, s62
	v_lshl_add_u64 v[156:157], s[48:49], 0, v[134:135]
	s_mov_b32 m0, s81
	ds_read_b128 v[196:199], v162 offset:16384
	ds_read_b128 v[200:203], v162 offset:17408
	ds_read_b128 v[204:207], v162 offset:18432
	ds_read_b128 v[208:211], v162 offset:19456
	ds_read_b128 v[212:215], v162 offset:20480
	ds_read_b128 v[216:219], v162 offset:21504
	ds_read_b128 v[220:223], v162 offset:22528
	ds_read_b128 v[224:227], v162 offset:23552
	global_load_lds_dwordx4 v[156:157], off
	s_add_i32 m0, s81, 0x2000
	s_add_u32 s82, s48, 0x20000
	v_lshl_add_u64 v[192:193], s[48:49], 0, v[138:139]
	s_addc_u32 s83, s49, 0
	s_add_i32 s81, s72, s62
	global_load_lds_dwordx4 v[192:193], off
	v_lshl_add_u64 v[228:229], s[82:83], 0, v[134:135]
	s_mov_b32 m0, s81
	v_lshl_add_u64 v[230:231], s[60:61], 0, v[136:137]
	global_load_lds_dwordx4 v[228:229], off
	v_lshl_add_u64 v[228:229], s[82:83], 0, v[138:139]
	s_add_i32 m0, s81, 0x2000
	s_nop 0
	global_load_lds_dwordx4 v[228:229], off
	v_lshl_add_u64 v[228:229], s[60:61], 0, v[132:133]
	s_mov_b32 m0, s55
	s_nop 0
	global_load_lds_dwordx4 v[228:229], off
	s_mov_b32 m0, s57
	s_nop 0
	global_load_lds_dwordx4 v[230:231], off
	s_waitcnt vmcnt(8)
	s_waitcnt lgkmcnt(0)
	s_barrier
	s_setprio 1
	v_mfma_f32_16x16x32_bf16 v[62:65], v[152:155], v[196:199], v[62:65]
	v_mfma_f32_16x16x32_bf16 v[58:61], v[168:171], v[196:199], v[58:61]
	v_mfma_f32_16x16x32_bf16 v[46:49], v[152:155], v[204:207], v[46:49]
	v_mfma_f32_16x16x32_bf16 v[42:45], v[168:171], v[204:207], v[42:45]
	v_mfma_f32_16x16x32_bf16 v[30:33], v[152:155], v[212:215], v[30:33]
	v_mfma_f32_16x16x32_bf16 v[26:29], v[168:171], v[212:215], v[26:29]
	v_mfma_f32_16x16x32_bf16 v[14:17], v[152:155], v[220:223], v[14:17]
	v_mfma_f32_16x16x32_bf16 v[10:13], v[168:171], v[220:223], v[10:13]
	v_mfma_f32_16x16x32_bf16 v[62:65], v[164:167], v[200:203], v[62:65]
	v_mfma_f32_16x16x32_bf16 v[58:61], v[172:175], v[200:203], v[58:61]
	v_mfma_f32_16x16x32_bf16 v[46:49], v[164:167], v[208:211], v[46:49]
	v_mfma_f32_16x16x32_bf16 v[42:45], v[172:175], v[208:211], v[42:45]
	v_mfma_f32_16x16x32_bf16 v[30:33], v[164:167], v[216:219], v[30:33]
	v_mfma_f32_16x16x32_bf16 v[26:29], v[172:175], v[216:219], v[26:29]
	v_mfma_f32_16x16x32_bf16 v[14:17], v[164:167], v[224:227], v[14:17]
	v_mfma_f32_16x16x32_bf16 v[10:13], v[172:175], v[224:227], v[10:13]
	v_mfma_f32_16x16x32_bf16 v[54:57], v[176:179], v[196:199], v[54:57]
	v_mfma_f32_16x16x32_bf16 v[50:53], v[184:187], v[196:199], v[50:53]
	v_mfma_f32_16x16x32_bf16 v[38:41], v[176:179], v[204:207], v[38:41]
	v_mfma_f32_16x16x32_bf16 v[34:37], v[184:187], v[204:207], v[34:37]
	v_mfma_f32_16x16x32_bf16 v[22:25], v[176:179], v[212:215], v[22:25]
	v_mfma_f32_16x16x32_bf16 v[18:21], v[184:187], v[212:215], v[18:21]
	v_mfma_f32_16x16x32_bf16 v[6:9], v[176:179], v[220:223], v[6:9]
	v_mfma_f32_16x16x32_bf16 v[2:5], v[184:187], v[220:223], v[2:5]
	v_mfma_f32_16x16x32_bf16 v[54:57], v[180:183], v[200:203], v[54:57]
	v_mfma_f32_16x16x32_bf16 v[50:53], v[188:191], v[200:203], v[50:53]
	v_mfma_f32_16x16x32_bf16 v[38:41], v[180:183], v[208:211], v[38:41]
	v_mfma_f32_16x16x32_bf16 v[34:37], v[188:191], v[208:211], v[34:37]
	v_mfma_f32_16x16x32_bf16 v[22:25], v[180:183], v[216:219], v[22:25]
	v_mfma_f32_16x16x32_bf16 v[18:21], v[188:191], v[216:219], v[18:21]
	v_mfma_f32_16x16x32_bf16 v[6:9], v[180:183], v[224:227], v[6:9]
	v_mfma_f32_16x16x32_bf16 v[2:5], v[188:191], v[224:227], v[2:5]
	s_setprio 0
	s_barrier
	s_add_u32 s60, s60, 0x20000
	s_addc_u32 s61, s61, 0
	s_mov_b32 m0, s63
	v_lshl_add_u64 v[232:233], s[60:61], 0, v[132:133]
	global_load_lds_dwordx4 v[232:233], off
	v_lshl_add_u64 v[232:233], s[60:61], 0, v[136:137]
	s_mov_b32 m0, s64
	s_nop 0
	global_load_lds_dwordx4 v[232:233], off
	s_add_i32 s81, 0, 0x18000
	v_add_u32_e32 v163, s81, v158
	s_add_i32 s82, 0, 0x1c000
	ds_read_b128 v[152:155], v163
	ds_read_b128 v[164:167], v163 offset:1024
	ds_read_b128 v[168:171], v163 offset:2048
	ds_read_b128 v[172:175], v163 offset:3072
	v_add_u32_e32 v163, s82, v158
	ds_read_b128 v[176:179], v163
	ds_read_b128 v[180:183], v163 offset:1024
	ds_read_b128 v[184:187], v163 offset:2048
	ds_read_b128 v[188:191], v163 offset:3072
	ds_read_b128 v[196:199], v162 offset:32768
	ds_read_b128 v[200:203], v162 offset:33792
	ds_read_b128 v[204:207], v162 offset:34816
	ds_read_b128 v[208:211], v162 offset:35840
	ds_read_b128 v[212:215], v162 offset:36864
	ds_read_b128 v[216:219], v162 offset:37888
	ds_read_b128 v[220:223], v162 offset:38912
	ds_read_b128 v[224:227], v162 offset:39936
	s_waitcnt vmcnt(8)
	s_waitcnt lgkmcnt(0)
	s_barrier
	s_setprio 1
	v_mfma_f32_16x16x32_bf16 v[126:129], v[152:155], v[196:199], v[126:129]
	v_mfma_f32_16x16x32_bf16 v[122:125], v[168:171], v[196:199], v[122:125]
	v_mfma_f32_16x16x32_bf16 v[110:113], v[152:155], v[204:207], v[110:113]
	v_mfma_f32_16x16x32_bf16 v[106:109], v[168:171], v[204:207], v[106:109]
	v_mfma_f32_16x16x32_bf16 v[94:97], v[152:155], v[212:215], v[94:97]
	v_mfma_f32_16x16x32_bf16 v[90:93], v[168:171], v[212:215], v[90:93]
	v_mfma_f32_16x16x32_bf16 v[78:81], v[152:155], v[220:223], v[78:81]
	v_mfma_f32_16x16x32_bf16 v[74:77], v[168:171], v[220:223], v[74:77]
	v_mfma_f32_16x16x32_bf16 v[126:129], v[164:167], v[200:203], v[126:129]
	v_mfma_f32_16x16x32_bf16 v[122:125], v[172:175], v[200:203], v[122:125]
	v_mfma_f32_16x16x32_bf16 v[110:113], v[164:167], v[208:211], v[110:113]
	v_mfma_f32_16x16x32_bf16 v[106:109], v[172:175], v[208:211], v[106:109]
	v_mfma_f32_16x16x32_bf16 v[94:97], v[164:167], v[216:219], v[94:97]
	v_mfma_f32_16x16x32_bf16 v[90:93], v[172:175], v[216:219], v[90:93]
	v_mfma_f32_16x16x32_bf16 v[78:81], v[164:167], v[224:227], v[78:81]
	v_mfma_f32_16x16x32_bf16 v[74:77], v[172:175], v[224:227], v[74:77]
	v_mfma_f32_16x16x32_bf16 v[118:121], v[176:179], v[196:199], v[118:121]
	v_mfma_f32_16x16x32_bf16 v[114:117], v[184:187], v[196:199], v[114:117]
	v_mfma_f32_16x16x32_bf16 v[102:105], v[176:179], v[204:207], v[102:105]
	v_mfma_f32_16x16x32_bf16 v[98:101], v[184:187], v[204:207], v[98:101]
	v_mfma_f32_16x16x32_bf16 v[86:89], v[176:179], v[212:215], v[86:89]
	v_mfma_f32_16x16x32_bf16 v[82:85], v[184:187], v[212:215], v[82:85]
	v_mfma_f32_16x16x32_bf16 v[70:73], v[176:179], v[220:223], v[70:73]
	v_mfma_f32_16x16x32_bf16 v[66:69], v[184:187], v[220:223], v[66:69]
	v_mfma_f32_16x16x32_bf16 v[118:121], v[180:183], v[200:203], v[118:121]
	v_mfma_f32_16x16x32_bf16 v[114:117], v[188:191], v[200:203], v[114:117]
	v_mfma_f32_16x16x32_bf16 v[102:105], v[180:183], v[208:211], v[102:105]
	v_mfma_f32_16x16x32_bf16 v[98:101], v[188:191], v[208:211], v[98:101]
	v_mfma_f32_16x16x32_bf16 v[86:89], v[180:183], v[216:219], v[86:89]
	v_mfma_f32_16x16x32_bf16 v[82:85], v[188:191], v[216:219], v[82:85]
	v_mfma_f32_16x16x32_bf16 v[70:73], v[180:183], v[224:227], v[70:73]
	v_mfma_f32_16x16x32_bf16 v[66:69], v[188:191], v[224:227], v[66:69]
	s_setprio 0
	s_barrier
	s_add_i32 s60, s81, s62
	v_lshl_add_u64 v[156:157], v[156:157], 0, s[14:15]
	s_mov_b32 m0, s60
	ds_read_b128 v[196:199], v162 offset:49152
	ds_read_b128 v[200:203], v162 offset:50176
	ds_read_b128 v[204:207], v162 offset:51200
	ds_read_b128 v[208:211], v162 offset:52224
	ds_read_b128 v[212:215], v162 offset:53248
	ds_read_b128 v[216:219], v162 offset:54272
	ds_read_b128 v[220:223], v162 offset:55296
	ds_read_b128 v[224:227], v162 offset:56320
	global_load_lds_dwordx4 v[156:157], off
	s_add_i32 m0, s60, 0x2000
	s_add_u32 s48, s48, 0x20080
	v_lshl_add_u64 v[156:157], v[192:193], 0, s[14:15]
	s_addc_u32 s49, s49, 0
	s_add_i32 s60, s82, s62
	global_load_lds_dwordx4 v[156:157], off
	v_lshl_add_u64 v[156:157], s[48:49], 0, v[134:135]
	s_mov_b32 m0, s60
	s_nop 0
	global_load_lds_dwordx4 v[156:157], off
	v_lshl_add_u64 v[156:157], s[48:49], 0, v[138:139]
	s_add_i32 m0, s60, 0x2000
	s_nop 0
	global_load_lds_dwordx4 v[156:157], off
	v_lshl_add_u64 v[156:157], v[228:229], 0, s[14:15]
	s_mov_b32 m0, s68
	s_nop 0
	global_load_lds_dwordx4 v[156:157], off
	v_lshl_add_u64 v[156:157], v[230:231], 0, s[14:15]
	s_mov_b32 m0, s69
	s_nop 0
	global_load_lds_dwordx4 v[156:157], off
	s_nop 0
	s_waitcnt vmcnt(8)
	s_waitcnt lgkmcnt(0)
	s_barrier
	s_setprio 1
	v_mfma_f32_16x16x32_bf16 v[62:65], v[152:155], v[196:199], v[62:65]
	v_mfma_f32_16x16x32_bf16 v[58:61], v[168:171], v[196:199], v[58:61]
	v_mfma_f32_16x16x32_bf16 v[46:49], v[152:155], v[204:207], v[46:49]
	v_mfma_f32_16x16x32_bf16 v[42:45], v[168:171], v[204:207], v[42:45]
	v_mfma_f32_16x16x32_bf16 v[30:33], v[152:155], v[212:215], v[30:33]
	v_mfma_f32_16x16x32_bf16 v[26:29], v[168:171], v[212:215], v[26:29]
	v_mfma_f32_16x16x32_bf16 v[14:17], v[152:155], v[220:223], v[14:17]
	v_mfma_f32_16x16x32_bf16 v[10:13], v[168:171], v[220:223], v[10:13]
	v_mfma_f32_16x16x32_bf16 v[62:65], v[164:167], v[200:203], v[62:65]
	v_mfma_f32_16x16x32_bf16 v[58:61], v[172:175], v[200:203], v[58:61]
	v_mfma_f32_16x16x32_bf16 v[46:49], v[164:167], v[208:211], v[46:49]
	v_mfma_f32_16x16x32_bf16 v[42:45], v[172:175], v[208:211], v[42:45]
	v_mfma_f32_16x16x32_bf16 v[30:33], v[164:167], v[216:219], v[30:33]
	v_mfma_f32_16x16x32_bf16 v[26:29], v[172:175], v[216:219], v[26:29]
	v_mfma_f32_16x16x32_bf16 v[14:17], v[164:167], v[224:227], v[14:17]
	v_mfma_f32_16x16x32_bf16 v[10:13], v[172:175], v[224:227], v[10:13]
	v_mfma_f32_16x16x32_bf16 v[54:57], v[176:179], v[196:199], v[54:57]
	v_mfma_f32_16x16x32_bf16 v[50:53], v[184:187], v[196:199], v[50:53]
	v_mfma_f32_16x16x32_bf16 v[38:41], v[176:179], v[204:207], v[38:41]
	v_mfma_f32_16x16x32_bf16 v[34:37], v[184:187], v[204:207], v[34:37]
	v_mfma_f32_16x16x32_bf16 v[22:25], v[176:179], v[212:215], v[22:25]
	v_mfma_f32_16x16x32_bf16 v[18:21], v[184:187], v[212:215], v[18:21]
	v_mfma_f32_16x16x32_bf16 v[6:9], v[176:179], v[220:223], v[6:9]
	v_mfma_f32_16x16x32_bf16 v[2:5], v[184:187], v[220:223], v[2:5]
	v_mfma_f32_16x16x32_bf16 v[54:57], v[180:183], v[200:203], v[54:57]
	v_mfma_f32_16x16x32_bf16 v[50:53], v[188:191], v[200:203], v[50:53]
	v_mfma_f32_16x16x32_bf16 v[38:41], v[180:183], v[208:211], v[38:41]
	v_mfma_f32_16x16x32_bf16 v[34:37], v[188:191], v[208:211], v[34:37]
	v_mfma_f32_16x16x32_bf16 v[22:25], v[180:183], v[216:219], v[22:25]
	v_mfma_f32_16x16x32_bf16 v[18:21], v[188:191], v[216:219], v[18:21]
	v_mfma_f32_16x16x32_bf16 v[6:9], v[180:183], v[224:227], v[6:9]
	v_mfma_f32_16x16x32_bf16 v[2:5], v[188:191], v[224:227], v[2:5]
	s_setprio 0
	s_barrier
	s_add_u32 s58, s58, 0x100
	s_addc_u32 s59, s59, 0
	s_add_u32 s47, s47, 0x100
	s_addc_u32 s51, s51, 0
	s_cmp_ge_i32 s80, s79
	s_mov_b32 s48, s80
	s_cbranch_scc0 .LBB0_3983
	s_and_b64 vcc, exec, s[16:17]
	s_cbranch_vccz .LBB0_3986
	s_barrier

.LBB0_4145:
	s_add_i32 s72, s42, 2
	s_add_u32 s43, s40, 0xfff00080
	s_addc_u32 s46, s41, -1
	s_cmp_eq_u32 s69, s42
	s_cselect_b32 s42, s25, s70
	s_cselect_b32 s47, s5, s46
	s_cselect_b32 s46, s23, s43
	s_cselect_b32 s43, s21, s71
	v_lshl_add_u64 v[228:229], s[40:41], 0, v[148:149]
	s_add_i32 m0, s35, 0xc000
	s_nop 0
	global_load_lds_dwordx4 v[228:229], off
	v_lshl_add_u64 v[228:229], s[40:41], 0, v[150:151]
	s_add_i32 m0, s35, 0xe000
	s_nop 0
	global_load_lds_dwordx4 v[228:229], off
	ds_read_b128 v[156:159], v162
	ds_read_b128 v[166:169], v162 offset:1024
	ds_read_b128 v[170:173], v162 offset:2048
	ds_read_b128 v[174:177], v162 offset:3072
	ds_read_b128 v[178:181], v163
	ds_read_b128 v[182:185], v163 offset:1024
	ds_read_b128 v[186:189], v163 offset:2048
	ds_read_b128 v[190:193], v163 offset:3072
	ds_read_b128 v[196:199], v164
	ds_read_b128 v[200:203], v164 offset:1024
	ds_read_b128 v[204:207], v164 offset:2048
	ds_read_b128 v[208:211], v164 offset:3072
	ds_read_b128 v[212:215], v164 offset:4096
	ds_read_b128 v[216:219], v164 offset:5120
	ds_read_b128 v[220:223], v164 offset:6144
	ds_read_b128 v[224:227], v164 offset:7168
	s_waitcnt vmcnt(8)
	s_waitcnt lgkmcnt(0)
	s_barrier
	s_setprio 1
	v_mfma_f32_16x16x32_bf16 v[78:81], v[156:159], v[196:199], v[78:81]
	v_mfma_f32_16x16x32_bf16 v[74:77], v[170:173], v[196:199], v[74:77]
	v_mfma_f32_16x16x32_bf16 v[70:73], v[156:159], v[204:207], v[70:73]
	v_mfma_f32_16x16x32_bf16 v[62:65], v[170:173], v[204:207], v[62:65]
	v_mfma_f32_16x16x32_bf16 v[58:61], v[156:159], v[212:215], v[58:61]
	v_mfma_f32_16x16x32_bf16 v[54:57], v[170:173], v[212:215], v[54:57]
	v_mfma_f32_16x16x32_bf16 v[46:49], v[156:159], v[220:223], v[46:49]
	v_mfma_f32_16x16x32_bf16 v[38:41], v[170:173], v[220:223], v[38:41]
	v_mfma_f32_16x16x32_bf16 v[78:81], v[166:169], v[200:203], v[78:81]
	v_mfma_f32_16x16x32_bf16 v[74:77], v[174:177], v[200:203], v[74:77]
	v_mfma_f32_16x16x32_bf16 v[70:73], v[166:169], v[208:211], v[70:73]
	v_mfma_f32_16x16x32_bf16 v[62:65], v[174:177], v[208:211], v[62:65]
	v_mfma_f32_16x16x32_bf16 v[58:61], v[166:169], v[216:219], v[58:61]
	v_mfma_f32_16x16x32_bf16 v[54:57], v[174:177], v[216:219], v[54:57]
	v_mfma_f32_16x16x32_bf16 v[46:49], v[166:169], v[224:227], v[46:49]
	v_mfma_f32_16x16x32_bf16 v[38:41], v[174:177], v[224:227], v[38:41]
	v_mfma_f32_16x16x32_bf16 v[50:53], v[178:181], v[196:199], v[50:53]
	v_mfma_f32_16x16x32_bf16 v[42:45], v[186:189], v[196:199], v[42:45]
	v_mfma_f32_16x16x32_bf16 v[34:37], v[178:181], v[204:207], v[34:37]
	v_mfma_f32_16x16x32_bf16 v[26:29], v[186:189], v[204:207], v[26:29]
	v_mfma_f32_16x16x32_bf16 v[18:21], v[178:181], v[212:215], v[18:21]
	v_mfma_f32_16x16x32_bf16 v[14:17], v[186:189], v[212:215], v[14:17]
	v_mfma_f32_16x16x32_bf16 v[10:13], v[178:181], v[220:223], v[10:13]
	v_mfma_f32_16x16x32_bf16 v[6:9], v[186:189], v[220:223], v[6:9]
	v_mfma_f32_16x16x32_bf16 v[50:53], v[182:185], v[200:203], v[50:53]
	v_mfma_f32_16x16x32_bf16 v[42:45], v[190:193], v[200:203], v[42:45]
	v_mfma_f32_16x16x32_bf16 v[34:37], v[182:185], v[208:211], v[34:37]
	v_mfma_f32_16x16x32_bf16 v[26:29], v[190:193], v[208:211], v[26:29]
	v_mfma_f32_16x16x32_bf16 v[18:21], v[182:185], v[216:219], v[18:21]
	v_mfma_f32_16x16x32_bf16 v[14:17], v[190:193], v[216:219], v[14:17]
	v_mfma_f32_16x16x32_bf16 v[10:13], v[182:185], v[224:227], v[10:13]
	v_mfma_f32_16x16x32_bf16 v[6:9], v[190:193], v[224:227], v[6:9]
	s_setprio 0
	s_barrier
	s_add_i32 s73, s62, s49
	v_lshl_add_u64 v[228:229], s[42:43], 0, v[134:135]
	s_mov_b32 m0, s73
	ds_read_b128 v[196:199], v164 offset:16384
	ds_read_b128 v[200:203], v164 offset:17408
	ds_read_b128 v[204:207], v164 offset:18432
	ds_read_b128 v[208:211], v164 offset:19456
	ds_read_b128 v[212:215], v164 offset:20480
	ds_read_b128 v[216:219], v164 offset:21504
	ds_read_b128 v[220:223], v164 offset:22528
	ds_read_b128 v[224:227], v164 offset:23552
	global_load_lds_dwordx4 v[228:229], off
	s_add_i32 m0, s73, 0x2000
	s_add_u32 s74, s42, 0x100000
	v_lshl_add_u64 v[230:231], s[42:43], 0, v[138:139]
	s_addc_u32 s75, s43, 0
	s_add_i32 s73, s63, s49
	global_load_lds_dwordx4 v[230:231], off
	v_lshl_add_u64 v[232:233], s[74:75], 0, v[134:135]
	s_mov_b32 m0, s73
	v_lshl_add_u64 v[234:235], s[46:47], 0, v[136:137]
	global_load_lds_dwordx4 v[232:233], off
	v_lshl_add_u64 v[232:233], s[74:75], 0, v[138:139]
	s_add_i32 m0, s73, 0x2000
	s_nop 0
	global_load_lds_dwordx4 v[232:233], off
	v_lshl_add_u64 v[232:233], s[46:47], 0, v[132:133]
	s_mov_b32 m0, s35
	s_nop 0
	global_load_lds_dwordx4 v[232:233], off
	s_mov_b32 m0, s50
	s_nop 0
	global_load_lds_dwordx4 v[234:235], off
	s_waitcnt vmcnt(8)
	s_waitcnt lgkmcnt(0)
	s_barrier
	s_setprio 1
	v_mfma_f32_16x16x32_bf16 v[126:129], v[156:159], v[196:199], v[126:129]
	v_mfma_f32_16x16x32_bf16 v[118:121], v[170:173], v[196:199], v[118:121]
	v_mfma_f32_16x16x32_bf16 v[110:113], v[156:159], v[204:207], v[110:113]
	v_mfma_f32_16x16x32_bf16 v[102:105], v[170:173], v[204:207], v[102:105]
	v_mfma_f32_16x16x32_bf16 v[94:97], v[156:159], v[212:215], v[94:97]
	v_mfma_f32_16x16x32_bf16 v[86:89], v[170:173], v[212:215], v[86:89]
	v_mfma_f32_16x16x32_bf16 v[66:69], v[156:159], v[220:223], v[66:69]
	v_mfma_f32_16x16x32_bf16 v[22:25], v[170:173], v[220:223], v[22:25]
	v_mfma_f32_16x16x32_bf16 v[126:129], v[166:169], v[200:203], v[126:129]
	v_mfma_f32_16x16x32_bf16 v[118:121], v[174:177], v[200:203], v[118:121]
	v_mfma_f32_16x16x32_bf16 v[110:113], v[166:169], v[208:211], v[110:113]
	v_mfma_f32_16x16x32_bf16 v[102:105], v[174:177], v[208:211], v[102:105]
	v_mfma_f32_16x16x32_bf16 v[94:97], v[166:169], v[216:219], v[94:97]
	v_mfma_f32_16x16x32_bf16 v[86:89], v[174:177], v[216:219], v[86:89]
	v_mfma_f32_16x16x32_bf16 v[66:69], v[166:169], v[224:227], v[66:69]
	v_mfma_f32_16x16x32_bf16 v[22:25], v[174:177], v[224:227], v[22:25]
	v_mfma_f32_16x16x32_bf16 v[122:125], v[178:181], v[196:199], v[122:125]
	v_mfma_f32_16x16x32_bf16 v[114:117], v[186:189], v[196:199], v[114:117]
	v_mfma_f32_16x16x32_bf16 v[106:109], v[178:181], v[204:207], v[106:109]
	v_mfma_f32_16x16x32_bf16 v[98:101], v[186:189], v[204:207], v[98:101]
	v_mfma_f32_16x16x32_bf16 v[90:93], v[178:181], v[212:215], v[90:93]
	v_mfma_f32_16x16x32_bf16 v[82:85], v[186:189], v[212:215], v[82:85]
	v_mfma_f32_16x16x32_bf16 v[30:33], v[178:181], v[220:223], v[30:33]
	v_mfma_f32_16x16x32_bf16 v[2:5], v[186:189], v[220:223], v[2:5]
	v_mfma_f32_16x16x32_bf16 v[122:125], v[182:185], v[200:203], v[122:125]
	v_mfma_f32_16x16x32_bf16 v[114:117], v[190:193], v[200:203], v[114:117]
	v_mfma_f32_16x16x32_bf16 v[106:109], v[182:185], v[208:211], v[106:109]
	v_mfma_f32_16x16x32_bf16 v[98:101], v[190:193], v[208:211], v[98:101]
	v_mfma_f32_16x16x32_bf16 v[90:93], v[182:185], v[216:219], v[90:93]
	v_mfma_f32_16x16x32_bf16 v[82:85], v[190:193], v[216:219], v[82:85]
	v_mfma_f32_16x16x32_bf16 v[30:33], v[182:185], v[224:227], v[30:33]
	v_mfma_f32_16x16x32_bf16 v[2:5], v[190:193], v[224:227], v[2:5]
	s_setprio 0
	s_barrier
	s_add_u32 s46, s46, 0x100000
	s_addc_u32 s47, s47, 0
	s_mov_b32 m0, s51
	v_lshl_add_u64 v[236:237], s[46:47], 0, v[132:133]
	global_load_lds_dwordx4 v[236:237], off
	v_lshl_add_u64 v[236:237], s[46:47], 0, v[136:137]
	s_mov_b32 m0, s52
	s_nop 0
	global_load_lds_dwordx4 v[236:237], off
	s_add_i32 s73, 0, 0x18000
	v_add_u32_e32 v165, s73, v160
	s_add_i32 s74, 0, 0x1c000
	ds_read_b128 v[156:159], v165
	ds_read_b128 v[166:169], v165 offset:1024
	ds_read_b128 v[170:173], v165 offset:2048
	ds_read_b128 v[174:177], v165 offset:3072
	v_add_u32_e32 v165, s74, v160
	ds_read_b128 v[178:181], v165
	ds_read_b128 v[182:185], v165 offset:1024
	ds_read_b128 v[186:189], v165 offset:2048
	ds_read_b128 v[190:193], v165 offset:3072
	ds_read_b128 v[196:199], v164 offset:32768
	ds_read_b128 v[200:203], v164 offset:33792
	ds_read_b128 v[204:207], v164 offset:34816
	ds_read_b128 v[208:211], v164 offset:35840
	ds_read_b128 v[212:215], v164 offset:36864
	ds_read_b128 v[216:219], v164 offset:37888
	ds_read_b128 v[220:223], v164 offset:38912
	ds_read_b128 v[224:227], v164 offset:39936
	s_waitcnt vmcnt(8)
	s_waitcnt lgkmcnt(0)
	s_barrier
	s_setprio 1
	v_mfma_f32_16x16x32_bf16 v[78:81], v[156:159], v[196:199], v[78:81]
	v_mfma_f32_16x16x32_bf16 v[74:77], v[170:173], v[196:199], v[74:77]
	v_mfma_f32_16x16x32_bf16 v[70:73], v[156:159], v[204:207], v[70:73]
	v_mfma_f32_16x16x32_bf16 v[62:65], v[170:173], v[204:207], v[62:65]
	v_mfma_f32_16x16x32_bf16 v[58:61], v[156:159], v[212:215], v[58:61]
	v_mfma_f32_16x16x32_bf16 v[54:57], v[170:173], v[212:215], v[54:57]
	v_mfma_f32_16x16x32_bf16 v[46:49], v[156:159], v[220:223], v[46:49]
	v_mfma_f32_16x16x32_bf16 v[38:41], v[170:173], v[220:223], v[38:41]
	v_mfma_f32_16x16x32_bf16 v[78:81], v[166:169], v[200:203], v[78:81]
	v_mfma_f32_16x16x32_bf16 v[74:77], v[174:177], v[200:203], v[74:77]
	v_mfma_f32_16x16x32_bf16 v[70:73], v[166:169], v[208:211], v[70:73]
	v_mfma_f32_16x16x32_bf16 v[62:65], v[174:177], v[208:211], v[62:65]
	v_mfma_f32_16x16x32_bf16 v[58:61], v[166:169], v[216:219], v[58:61]
	v_mfma_f32_16x16x32_bf16 v[54:57], v[174:177], v[216:219], v[54:57]
	v_mfma_f32_16x16x32_bf16 v[46:49], v[166:169], v[224:227], v[46:49]
	v_mfma_f32_16x16x32_bf16 v[38:41], v[174:177], v[224:227], v[38:41]
	v_mfma_f32_16x16x32_bf16 v[50:53], v[178:181], v[196:199], v[50:53]
	v_mfma_f32_16x16x32_bf16 v[42:45], v[186:189], v[196:199], v[42:45]
	v_mfma_f32_16x16x32_bf16 v[34:37], v[178:181], v[204:207], v[34:37]
	v_mfma_f32_16x16x32_bf16 v[26:29], v[186:189], v[204:207], v[26:29]
	v_mfma_f32_16x16x32_bf16 v[18:21], v[178:181], v[212:215], v[18:21]
	v_mfma_f32_16x16x32_bf16 v[14:17], v[186:189], v[212:215], v[14:17]
	v_mfma_f32_16x16x32_bf16 v[10:13], v[178:181], v[220:223], v[10:13]
	v_mfma_f32_16x16x32_bf16 v[6:9], v[186:189], v[220:223], v[6:9]
	v_mfma_f32_16x16x32_bf16 v[50:53], v[182:185], v[200:203], v[50:53]
	v_mfma_f32_16x16x32_bf16 v[42:45], v[190:193], v[200:203], v[42:45]
	v_mfma_f32_16x16x32_bf16 v[34:37], v[182:185], v[208:211], v[34:37]
	v_mfma_f32_16x16x32_bf16 v[26:29], v[190:193], v[208:211], v[26:29]
	v_mfma_f32_16x16x32_bf16 v[18:21], v[182:185], v[216:219], v[18:21]
	v_mfma_f32_16x16x32_bf16 v[14:17], v[190:193], v[216:219], v[14:17]
	v_mfma_f32_16x16x32_bf16 v[10:13], v[182:185], v[224:227], v[10:13]
	v_mfma_f32_16x16x32_bf16 v[6:9], v[190:193], v[224:227], v[6:9]
	s_setprio 0
	s_barrier
	s_add_i32 s46, s73, s49
	v_lshl_add_u64 v[228:229], v[228:229], 0, s[10:11]
	s_mov_b32 m0, s46
	ds_read_b128 v[196:199], v164 offset:49152
	ds_read_b128 v[200:203], v164 offset:50176
	ds_read_b128 v[204:207], v164 offset:51200
	ds_read_b128 v[208:211], v164 offset:52224
	ds_read_b128 v[212:215], v164 offset:53248
	ds_read_b128 v[216:219], v164 offset:54272
	ds_read_b128 v[220:223], v164 offset:55296
	ds_read_b128 v[224:227], v164 offset:56320
	global_load_lds_dwordx4 v[228:229], off
	s_add_i32 m0, s46, 0x2000
	s_add_u32 s42, s42, 0x100080
	v_lshl_add_u64 v[228:229], v[230:231], 0, s[10:11]
	s_addc_u32 s43, s43, 0
	s_add_i32 s46, s74, s49
	global_load_lds_dwordx4 v[228:229], off
	v_lshl_add_u64 v[228:229], s[42:43], 0, v[134:135]
	s_mov_b32 m0, s46
	s_nop 0
	global_load_lds_dwordx4 v[228:229], off
	v_lshl_add_u64 v[228:229], s[42:43], 0, v[138:139]
	s_add_i32 m0, s46, 0x2000
	s_nop 0
	global_load_lds_dwordx4 v[228:229], off
	v_lshl_add_u64 v[228:229], v[232:233], 0, s[10:11]
	s_mov_b32 m0, s55
	s_nop 0
	global_load_lds_dwordx4 v[228:229], off
	v_lshl_add_u64 v[228:229], v[234:235], 0, s[10:11]
	s_mov_b32 m0, s56
	s_nop 0
	global_load_lds_dwordx4 v[228:229], off
	s_nop 0
	s_waitcnt vmcnt(8)
	s_waitcnt lgkmcnt(0)
	s_barrier
	s_setprio 1
	v_mfma_f32_16x16x32_bf16 v[126:129], v[156:159], v[196:199], v[126:129]
	v_mfma_f32_16x16x32_bf16 v[118:121], v[170:173], v[196:199], v[118:121]
	v_mfma_f32_16x16x32_bf16 v[110:113], v[156:159], v[204:207], v[110:113]
	v_mfma_f32_16x16x32_bf16 v[102:105], v[170:173], v[204:207], v[102:105]
	v_mfma_f32_16x16x32_bf16 v[94:97], v[156:159], v[212:215], v[94:97]
	v_mfma_f32_16x16x32_bf16 v[86:89], v[170:173], v[212:215], v[86:89]
	v_mfma_f32_16x16x32_bf16 v[66:69], v[156:159], v[220:223], v[66:69]
	v_mfma_f32_16x16x32_bf16 v[22:25], v[170:173], v[220:223], v[22:25]
	v_mfma_f32_16x16x32_bf16 v[126:129], v[166:169], v[200:203], v[126:129]
	v_mfma_f32_16x16x32_bf16 v[118:121], v[174:177], v[200:203], v[118:121]
	v_mfma_f32_16x16x32_bf16 v[110:113], v[166:169], v[208:211], v[110:113]
	v_mfma_f32_16x16x32_bf16 v[102:105], v[174:177], v[208:211], v[102:105]
	v_mfma_f32_16x16x32_bf16 v[94:97], v[166:169], v[216:219], v[94:97]
	v_mfma_f32_16x16x32_bf16 v[86:89], v[174:177], v[216:219], v[86:89]
	v_mfma_f32_16x16x32_bf16 v[66:69], v[166:169], v[224:227], v[66:69]
	v_mfma_f32_16x16x32_bf16 v[22:25], v[174:177], v[224:227], v[22:25]
	v_mfma_f32_16x16x32_bf16 v[122:125], v[178:181], v[196:199], v[122:125]
	v_mfma_f32_16x16x32_bf16 v[114:117], v[186:189], v[196:199], v[114:117]
	v_mfma_f32_16x16x32_bf16 v[106:109], v[178:181], v[204:207], v[106:109]
	v_mfma_f32_16x16x32_bf16 v[98:101], v[186:189], v[204:207], v[98:101]
	v_mfma_f32_16x16x32_bf16 v[90:93], v[178:181], v[212:215], v[90:93]
	v_mfma_f32_16x16x32_bf16 v[82:85], v[186:189], v[212:215], v[82:85]
	v_mfma_f32_16x16x32_bf16 v[30:33], v[178:181], v[220:223], v[30:33]
	v_mfma_f32_16x16x32_bf16 v[2:5], v[186:189], v[220:223], v[2:5]
	v_mfma_f32_16x16x32_bf16 v[122:125], v[182:185], v[200:203], v[122:125]
	v_mfma_f32_16x16x32_bf16 v[114:117], v[190:193], v[200:203], v[114:117]
	v_mfma_f32_16x16x32_bf16 v[106:109], v[182:185], v[208:211], v[106:109]
	v_mfma_f32_16x16x32_bf16 v[98:101], v[190:193], v[208:211], v[98:101]
	v_mfma_f32_16x16x32_bf16 v[90:93], v[182:185], v[216:219], v[90:93]
	v_mfma_f32_16x16x32_bf16 v[82:85], v[190:193], v[216:219], v[82:85]
	v_mfma_f32_16x16x32_bf16 v[30:33], v[182:185], v[224:227], v[30:33]
	v_mfma_f32_16x16x32_bf16 v[2:5], v[190:193], v[224:227], v[2:5]
	s_setprio 0
	s_barrier
	s_add_u32 s40, s40, 0x100
	s_addc_u32 s41, s41, 0
	s_add_u32 s70, s70, 0x100
	s_addc_u32 s71, s71, 0
	s_cmp_ge_i32 s72, s68
	s_mov_b32 s42, s72
	s_cbranch_scc0 .LBB0_4145
	s_and_b64 vcc, exec, s[12:13]
	s_cbranch_vccz .LBB0_4150
	s_barrier
	s_cmp_lt_i32 s48, 0
	s_mov_b64 s[40:41], -1
	s_cbranch_scc1 .LBB0_4151

.LBB0_4304:
	s_add_i32 s80, s48, 2
	s_add_u32 s49, s50, 0xffd50080
	s_addc_u32 s52, s51, -1
	s_cmp_eq_u32 s43, s48
	s_cselect_b32 s48, s46, s78
	s_cselect_b32 s53, s5, s52
	s_cselect_b32 s52, s4, s49
	s_cselect_b32 s49, s47, s79
	v_lshl_add_u64 v[154:155], s[50:51], 0, v[138:139]
	s_add_i32 m0, s55, 0xc000
	s_nop 0
	global_load_lds_dwordx4 v[154:155], off
	v_lshl_add_u64 v[154:155], s[50:51], 0, v[140:141]
	s_add_i32 m0, s55, 0xe000
	s_nop 0
	global_load_lds_dwordx4 v[154:155], off
	ds_read_b128 v[150:153], v158
	ds_read_b128 v[162:165], v158 offset:1024
	ds_read_b128 v[166:169], v158 offset:2048
	ds_read_b128 v[170:173], v158 offset:3072
	ds_read_b128 v[174:177], v159
	ds_read_b128 v[178:181], v159 offset:1024
	ds_read_b128 v[182:185], v159 offset:2048
	ds_read_b128 v[186:189], v159 offset:3072
	ds_read_b128 v[190:193], v160
	ds_read_b128 v[196:199], v160 offset:1024
	ds_read_b128 v[200:203], v160 offset:2048
	ds_read_b128 v[204:207], v160 offset:3072
	ds_read_b128 v[208:211], v160 offset:4096
	ds_read_b128 v[212:215], v160 offset:5120
	ds_read_b128 v[216:219], v160 offset:6144
	ds_read_b128 v[220:223], v160 offset:7168
	s_waitcnt vmcnt(8)
	s_waitcnt lgkmcnt(0)
	s_barrier
	s_setprio 1
	v_mfma_f32_16x16x32_bf16 v[124:127], v[150:153], v[190:193], v[124:127]
	v_mfma_f32_16x16x32_bf16 v[120:123], v[166:169], v[190:193], v[120:123]
	v_mfma_f32_16x16x32_bf16 v[108:111], v[150:153], v[200:203], v[108:111]
	v_mfma_f32_16x16x32_bf16 v[104:107], v[166:169], v[200:203], v[104:107]
	v_mfma_f32_16x16x32_bf16 v[92:95], v[150:153], v[208:211], v[92:95]
	v_mfma_f32_16x16x32_bf16 v[88:91], v[166:169], v[208:211], v[88:91]
	v_mfma_f32_16x16x32_bf16 v[76:79], v[150:153], v[216:219], v[76:79]
	v_mfma_f32_16x16x32_bf16 v[72:75], v[166:169], v[216:219], v[72:75]
	v_mfma_f32_16x16x32_bf16 v[124:127], v[162:165], v[196:199], v[124:127]
	v_mfma_f32_16x16x32_bf16 v[120:123], v[170:173], v[196:199], v[120:123]
	v_mfma_f32_16x16x32_bf16 v[108:111], v[162:165], v[204:207], v[108:111]
	v_mfma_f32_16x16x32_bf16 v[104:107], v[170:173], v[204:207], v[104:107]
	v_mfma_f32_16x16x32_bf16 v[92:95], v[162:165], v[212:215], v[92:95]
	v_mfma_f32_16x16x32_bf16 v[88:91], v[170:173], v[212:215], v[88:91]
	v_mfma_f32_16x16x32_bf16 v[76:79], v[162:165], v[220:223], v[76:79]
	v_mfma_f32_16x16x32_bf16 v[72:75], v[170:173], v[220:223], v[72:75]
	v_mfma_f32_16x16x32_bf16 v[116:119], v[174:177], v[190:193], v[116:119]
	v_mfma_f32_16x16x32_bf16 v[112:115], v[182:185], v[190:193], v[112:115]
	v_mfma_f32_16x16x32_bf16 v[100:103], v[174:177], v[200:203], v[100:103]
	v_mfma_f32_16x16x32_bf16 v[96:99], v[182:185], v[200:203], v[96:99]
	v_mfma_f32_16x16x32_bf16 v[84:87], v[174:177], v[208:211], v[84:87]
	v_mfma_f32_16x16x32_bf16 v[80:83], v[182:185], v[208:211], v[80:83]
	v_mfma_f32_16x16x32_bf16 v[68:71], v[174:177], v[216:219], v[68:71]
	v_mfma_f32_16x16x32_bf16 v[64:67], v[182:185], v[216:219], v[64:67]
	v_mfma_f32_16x16x32_bf16 v[116:119], v[178:181], v[196:199], v[116:119]
	v_mfma_f32_16x16x32_bf16 v[112:115], v[186:189], v[196:199], v[112:115]
	v_mfma_f32_16x16x32_bf16 v[100:103], v[178:181], v[204:207], v[100:103]
	v_mfma_f32_16x16x32_bf16 v[96:99], v[186:189], v[204:207], v[96:99]
	v_mfma_f32_16x16x32_bf16 v[84:87], v[178:181], v[212:215], v[84:87]
	v_mfma_f32_16x16x32_bf16 v[80:83], v[186:189], v[212:215], v[80:83]
	v_mfma_f32_16x16x32_bf16 v[68:71], v[178:181], v[220:223], v[68:71]
	v_mfma_f32_16x16x32_bf16 v[64:67], v[186:189], v[220:223], v[64:67]
	s_setprio 0
	s_barrier
	s_add_i32 s81, s65, s54
	v_lshl_add_u64 v[154:155], s[48:49], 0, v[132:133]
	s_mov_b32 m0, s81
	ds_read_b128 v[190:193], v160 offset:16384
	ds_read_b128 v[196:199], v160 offset:17408
	ds_read_b128 v[200:203], v160 offset:18432
	ds_read_b128 v[204:207], v160 offset:19456
	ds_read_b128 v[208:211], v160 offset:20480
	ds_read_b128 v[212:215], v160 offset:21504
	ds_read_b128 v[216:219], v160 offset:22528
	ds_read_b128 v[220:223], v160 offset:23552
	global_load_lds_dwordx4 v[154:155], off
	s_add_i32 m0, s81, 0x2000
	s_add_u32 s82, s48, 0x2b0000
	v_lshl_add_u64 v[224:225], s[48:49], 0, v[136:137]
	s_addc_u32 s83, s49, 0
	s_add_i32 s81, s66, s54
	global_load_lds_dwordx4 v[224:225], off
	v_lshl_add_u64 v[226:227], s[82:83], 0, v[132:133]
	s_mov_b32 m0, s81
	v_lshl_add_u64 v[228:229], s[52:53], 0, v[134:135]
	global_load_lds_dwordx4 v[226:227], off
	v_lshl_add_u64 v[226:227], s[82:83], 0, v[136:137]
	s_add_i32 m0, s81, 0x2000
	s_nop 0
	global_load_lds_dwordx4 v[226:227], off
	v_lshl_add_u64 v[226:227], s[52:53], 0, v[128:129]
	s_mov_b32 m0, s55
	s_nop 0
	global_load_lds_dwordx4 v[226:227], off
	s_mov_b32 m0, s56
	s_nop 0
	global_load_lds_dwordx4 v[228:229], off
	s_waitcnt vmcnt(8)
	s_waitcnt lgkmcnt(0)
	s_barrier
	s_setprio 1
	v_mfma_f32_16x16x32_bf16 v[60:63], v[150:153], v[190:193], v[60:63]
	v_mfma_f32_16x16x32_bf16 v[56:59], v[166:169], v[190:193], v[56:59]
	v_mfma_f32_16x16x32_bf16 v[44:47], v[150:153], v[200:203], v[44:47]
	v_mfma_f32_16x16x32_bf16 v[40:43], v[166:169], v[200:203], v[40:43]
	v_mfma_f32_16x16x32_bf16 v[28:31], v[150:153], v[208:211], v[28:31]
	v_mfma_f32_16x16x32_bf16 v[24:27], v[166:169], v[208:211], v[24:27]
	v_mfma_f32_16x16x32_bf16 v[12:15], v[150:153], v[216:219], v[12:15]
	v_mfma_f32_16x16x32_bf16 v[8:11], v[166:169], v[216:219], v[8:11]
	v_mfma_f32_16x16x32_bf16 v[60:63], v[162:165], v[196:199], v[60:63]
	v_mfma_f32_16x16x32_bf16 v[56:59], v[170:173], v[196:199], v[56:59]
	v_mfma_f32_16x16x32_bf16 v[44:47], v[162:165], v[204:207], v[44:47]
	v_mfma_f32_16x16x32_bf16 v[40:43], v[170:173], v[204:207], v[40:43]
	v_mfma_f32_16x16x32_bf16 v[28:31], v[162:165], v[212:215], v[28:31]
	v_mfma_f32_16x16x32_bf16 v[24:27], v[170:173], v[212:215], v[24:27]
	v_mfma_f32_16x16x32_bf16 v[12:15], v[162:165], v[220:223], v[12:15]
	v_mfma_f32_16x16x32_bf16 v[8:11], v[170:173], v[220:223], v[8:11]
	v_mfma_f32_16x16x32_bf16 v[52:55], v[174:177], v[190:193], v[52:55]
	v_mfma_f32_16x16x32_bf16 v[48:51], v[182:185], v[190:193], v[48:51]
	v_mfma_f32_16x16x32_bf16 v[36:39], v[174:177], v[200:203], v[36:39]
	v_mfma_f32_16x16x32_bf16 v[32:35], v[182:185], v[200:203], v[32:35]
	v_mfma_f32_16x16x32_bf16 v[20:23], v[174:177], v[208:211], v[20:23]
	v_mfma_f32_16x16x32_bf16 v[16:19], v[182:185], v[208:211], v[16:19]
	v_mfma_f32_16x16x32_bf16 v[4:7], v[174:177], v[216:219], v[4:7]
	v_mfma_f32_16x16x32_bf16 v[0:3], v[182:185], v[216:219], v[0:3]
	v_mfma_f32_16x16x32_bf16 v[52:55], v[178:181], v[196:199], v[52:55]
	v_mfma_f32_16x16x32_bf16 v[48:51], v[186:189], v[196:199], v[48:51]
	v_mfma_f32_16x16x32_bf16 v[36:39], v[178:181], v[204:207], v[36:39]
	v_mfma_f32_16x16x32_bf16 v[32:35], v[186:189], v[204:207], v[32:35]
	v_mfma_f32_16x16x32_bf16 v[20:23], v[178:181], v[212:215], v[20:23]
	v_mfma_f32_16x16x32_bf16 v[16:19], v[186:189], v[212:215], v[16:19]
	v_mfma_f32_16x16x32_bf16 v[4:7], v[178:181], v[220:223], v[4:7]
	v_mfma_f32_16x16x32_bf16 v[0:3], v[186:189], v[220:223], v[0:3]
	s_setprio 0
	s_barrier
	s_add_u32 s52, s52, 0x2b0000
	s_addc_u32 s53, s53, 0
	s_mov_b32 m0, s57
	v_lshl_add_u64 v[230:231], s[52:53], 0, v[128:129]
	global_load_lds_dwordx4 v[230:231], off
	v_lshl_add_u64 v[230:231], s[52:53], 0, v[134:135]
	s_mov_b32 m0, s58
	s_nop 0
	global_load_lds_dwordx4 v[230:231], off
	s_add_i32 s81, 0, 0x18000
	v_add_u32_e32 v161, s81, v156
	s_add_i32 s82, 0, 0x1c000
	ds_read_b128 v[150:153], v161
	ds_read_b128 v[162:165], v161 offset:1024
	ds_read_b128 v[166:169], v161 offset:2048
	ds_read_b128 v[170:173], v161 offset:3072
	v_add_u32_e32 v161, s82, v156
	ds_read_b128 v[174:177], v161
	ds_read_b128 v[178:181], v161 offset:1024
	ds_read_b128 v[182:185], v161 offset:2048
	ds_read_b128 v[186:189], v161 offset:3072
	ds_read_b128 v[190:193], v160 offset:32768
	ds_read_b128 v[196:199], v160 offset:33792
	ds_read_b128 v[200:203], v160 offset:34816
	ds_read_b128 v[204:207], v160 offset:35840
	ds_read_b128 v[208:211], v160 offset:36864
	ds_read_b128 v[212:215], v160 offset:37888
	ds_read_b128 v[216:219], v160 offset:38912
	ds_read_b128 v[220:223], v160 offset:39936
	s_waitcnt vmcnt(8)
	s_waitcnt lgkmcnt(0)
	s_barrier
	s_setprio 1
	v_mfma_f32_16x16x32_bf16 v[124:127], v[150:153], v[190:193], v[124:127]
	v_mfma_f32_16x16x32_bf16 v[120:123], v[166:169], v[190:193], v[120:123]
	v_mfma_f32_16x16x32_bf16 v[108:111], v[150:153], v[200:203], v[108:111]
	v_mfma_f32_16x16x32_bf16 v[104:107], v[166:169], v[200:203], v[104:107]
	v_mfma_f32_16x16x32_bf16 v[92:95], v[150:153], v[208:211], v[92:95]
	v_mfma_f32_16x16x32_bf16 v[88:91], v[166:169], v[208:211], v[88:91]
	v_mfma_f32_16x16x32_bf16 v[76:79], v[150:153], v[216:219], v[76:79]
	v_mfma_f32_16x16x32_bf16 v[72:75], v[166:169], v[216:219], v[72:75]
	v_mfma_f32_16x16x32_bf16 v[124:127], v[162:165], v[196:199], v[124:127]
	v_mfma_f32_16x16x32_bf16 v[120:123], v[170:173], v[196:199], v[120:123]
	v_mfma_f32_16x16x32_bf16 v[108:111], v[162:165], v[204:207], v[108:111]
	v_mfma_f32_16x16x32_bf16 v[104:107], v[170:173], v[204:207], v[104:107]
	v_mfma_f32_16x16x32_bf16 v[92:95], v[162:165], v[212:215], v[92:95]
	v_mfma_f32_16x16x32_bf16 v[88:91], v[170:173], v[212:215], v[88:91]
	v_mfma_f32_16x16x32_bf16 v[76:79], v[162:165], v[220:223], v[76:79]
	v_mfma_f32_16x16x32_bf16 v[72:75], v[170:173], v[220:223], v[72:75]
	v_mfma_f32_16x16x32_bf16 v[116:119], v[174:177], v[190:193], v[116:119]
	v_mfma_f32_16x16x32_bf16 v[112:115], v[182:185], v[190:193], v[112:115]
	v_mfma_f32_16x16x32_bf16 v[100:103], v[174:177], v[200:203], v[100:103]
	v_mfma_f32_16x16x32_bf16 v[96:99], v[182:185], v[200:203], v[96:99]
	v_mfma_f32_16x16x32_bf16 v[84:87], v[174:177], v[208:211], v[84:87]
	v_mfma_f32_16x16x32_bf16 v[80:83], v[182:185], v[208:211], v[80:83]
	v_mfma_f32_16x16x32_bf16 v[68:71], v[174:177], v[216:219], v[68:71]
	v_mfma_f32_16x16x32_bf16 v[64:67], v[182:185], v[216:219], v[64:67]
	v_mfma_f32_16x16x32_bf16 v[116:119], v[178:181], v[196:199], v[116:119]
	v_mfma_f32_16x16x32_bf16 v[112:115], v[186:189], v[196:199], v[112:115]
	v_mfma_f32_16x16x32_bf16 v[100:103], v[178:181], v[204:207], v[100:103]
	v_mfma_f32_16x16x32_bf16 v[96:99], v[186:189], v[204:207], v[96:99]
	v_mfma_f32_16x16x32_bf16 v[84:87], v[178:181], v[212:215], v[84:87]
	v_mfma_f32_16x16x32_bf16 v[80:83], v[186:189], v[212:215], v[80:83]
	v_mfma_f32_16x16x32_bf16 v[68:71], v[178:181], v[220:223], v[68:71]
	v_mfma_f32_16x16x32_bf16 v[64:67], v[186:189], v[220:223], v[64:67]
	s_setprio 0
	s_barrier
	s_add_i32 s52, s81, s54
	v_lshl_add_u64 v[154:155], v[154:155], 0, s[14:15]
	s_mov_b32 m0, s52
	ds_read_b128 v[190:193], v160 offset:49152
	ds_read_b128 v[196:199], v160 offset:50176
	ds_read_b128 v[200:203], v160 offset:51200
	ds_read_b128 v[204:207], v160 offset:52224
	ds_read_b128 v[208:211], v160 offset:53248
	ds_read_b128 v[212:215], v160 offset:54272
	ds_read_b128 v[216:219], v160 offset:55296
	ds_read_b128 v[220:223], v160 offset:56320
	global_load_lds_dwordx4 v[154:155], off
	s_add_i32 m0, s52, 0x2000
	s_add_u32 s48, s48, 0x2b0080
	v_lshl_add_u64 v[154:155], v[224:225], 0, s[14:15]
	s_addc_u32 s49, s49, 0
	s_add_i32 s52, s82, s54
	global_load_lds_dwordx4 v[154:155], off
	v_lshl_add_u64 v[154:155], s[48:49], 0, v[132:133]
	s_mov_b32 m0, s52
	s_nop 0
	global_load_lds_dwordx4 v[154:155], off
	v_lshl_add_u64 v[154:155], s[48:49], 0, v[136:137]
	s_add_i32 m0, s52, 0x2000
	s_nop 0
	global_load_lds_dwordx4 v[154:155], off
	v_lshl_add_u64 v[154:155], v[226:227], 0, s[14:15]
	s_mov_b32 m0, s62
	s_nop 0
	global_load_lds_dwordx4 v[154:155], off
	v_lshl_add_u64 v[154:155], v[228:229], 0, s[14:15]
	s_mov_b32 m0, s63
	s_nop 0
	global_load_lds_dwordx4 v[154:155], off
	s_nop 0
	s_waitcnt vmcnt(8)
	s_waitcnt lgkmcnt(0)
	s_barrier
	s_setprio 1
	v_mfma_f32_16x16x32_bf16 v[60:63], v[150:153], v[190:193], v[60:63]
	v_mfma_f32_16x16x32_bf16 v[56:59], v[166:169], v[190:193], v[56:59]
	v_mfma_f32_16x16x32_bf16 v[44:47], v[150:153], v[200:203], v[44:47]
	v_mfma_f32_16x16x32_bf16 v[40:43], v[166:169], v[200:203], v[40:43]
	v_mfma_f32_16x16x32_bf16 v[28:31], v[150:153], v[208:211], v[28:31]
	v_mfma_f32_16x16x32_bf16 v[24:27], v[166:169], v[208:211], v[24:27]
	v_mfma_f32_16x16x32_bf16 v[12:15], v[150:153], v[216:219], v[12:15]
	v_mfma_f32_16x16x32_bf16 v[8:11], v[166:169], v[216:219], v[8:11]
	v_mfma_f32_16x16x32_bf16 v[60:63], v[162:165], v[196:199], v[60:63]
	v_mfma_f32_16x16x32_bf16 v[56:59], v[170:173], v[196:199], v[56:59]
	v_mfma_f32_16x16x32_bf16 v[44:47], v[162:165], v[204:207], v[44:47]
	v_mfma_f32_16x16x32_bf16 v[40:43], v[170:173], v[204:207], v[40:43]
	v_mfma_f32_16x16x32_bf16 v[28:31], v[162:165], v[212:215], v[28:31]
	v_mfma_f32_16x16x32_bf16 v[24:27], v[170:173], v[212:215], v[24:27]
	v_mfma_f32_16x16x32_bf16 v[12:15], v[162:165], v[220:223], v[12:15]
	v_mfma_f32_16x16x32_bf16 v[8:11], v[170:173], v[220:223], v[8:11]
	v_mfma_f32_16x16x32_bf16 v[52:55], v[174:177], v[190:193], v[52:55]
	v_mfma_f32_16x16x32_bf16 v[48:51], v[182:185], v[190:193], v[48:51]
	v_mfma_f32_16x16x32_bf16 v[36:39], v[174:177], v[200:203], v[36:39]
	v_mfma_f32_16x16x32_bf16 v[32:35], v[182:185], v[200:203], v[32:35]
	v_mfma_f32_16x16x32_bf16 v[20:23], v[174:177], v[208:211], v[20:23]
	v_mfma_f32_16x16x32_bf16 v[16:19], v[182:185], v[208:211], v[16:19]
	v_mfma_f32_16x16x32_bf16 v[4:7], v[174:177], v[216:219], v[4:7]
	v_mfma_f32_16x16x32_bf16 v[0:3], v[182:185], v[216:219], v[0:3]
	v_mfma_f32_16x16x32_bf16 v[52:55], v[178:181], v[196:199], v[52:55]
	v_mfma_f32_16x16x32_bf16 v[48:51], v[186:189], v[196:199], v[48:51]
	v_mfma_f32_16x16x32_bf16 v[36:39], v[178:181], v[204:207], v[36:39]
	v_mfma_f32_16x16x32_bf16 v[32:35], v[186:189], v[204:207], v[32:35]
	v_mfma_f32_16x16x32_bf16 v[20:23], v[178:181], v[212:215], v[20:23]
	v_mfma_f32_16x16x32_bf16 v[16:19], v[186:189], v[212:215], v[16:19]
	v_mfma_f32_16x16x32_bf16 v[4:7], v[178:181], v[220:223], v[4:7]
	v_mfma_f32_16x16x32_bf16 v[0:3], v[186:189], v[220:223], v[0:3]
	s_setprio 0
	s_barrier
	s_add_u32 s50, s50, 0x100
	s_addc_u32 s51, s51, 0
	s_add_u32 s78, s78, 0x100
	s_addc_u32 s79, s79, 0
	s_cmp_ge_i32 s80, s76
	s_mov_b32 s48, s80
	s_cbranch_scc0 .LBB0_4304
	s_and_b64 vcc, exec, s[16:17]
	s_cbranch_vccz .LBB0_4307
	s_barrier
